# rowstat partials in a permuted row layout: 2 dwordx4 stores per lane per unit instead of 8 dword stores; loops 64B-aligned
# speedup vs baseline: 1.0024x; 1.0024x over previous
; #define PG8_STAGE(bufoff, gbase, voff) do { _Pragma("unroll") for (int _i = 0; _i < 2; ++_i) \
;         __builtin_amdgcn_global_load_lds((const unsigned*)((const char*)(gbase) + (voff)[_i]), (LAS unsigned*)(lds + (bufoff) + ldsw + _i * 8192), 16, 0, 0); } while (0)
; #define PG8_LDA(dst, b, h) do { _Pragma("unroll") for (int m = 0; m < 4; ++m) _Pragma("unroll") for (int k = 0; k < 2; ++k) dst[m][k] = *(const LAS bf16x8*)(lds + PG8_SA(b, h) + aoff + m * 2048 + k * 1024); } while (0)
; #define PG8_LDB(dst, b, h) do { _Pragma("unroll") for (int n = 0; n < 2; ++n) _Pragma("unroll") for (int k = 0; k < 2; ++k) dst[n][k] = *(const LAS bf16x8*)(lds + PG8_SB(b, h) + boff + n * 2048 + k * 1024); } while (0)
; #define PG8_MMA(ai, bj, At, Bt) do { __builtin_amdgcn_s_setprio(1); _Pragma("unroll") for (int m = 0; m < 4; ++m) _Pragma("unroll") for (int n = 0; n < 2; ++n) _Pragma("unroll") for (int k = 0; k < 2; ++k) \
;         acc[ai][bj][m][n] = __builtin_amdgcn_mfma_f32_16x16x32_bf16(Bt[n][k], At[m][k], acc[ai][bj][m][n], 0, 0, 0); __builtin_amdgcn_s_setprio(0); } while (0)
; #define PG8_WAIT_V(n) asm volatile("s_waitcnt vmcnt(" #n ")" ::: "memory")
; #define PG8_WAIT_L(n) asm volatile("s_waitcnt lgkmcnt(" #n ")" ::: "memory")
; #define PG8_BAR __builtin_amdgcn_s_barrier()
; #define PG8_SCHED __builtin_amdgcn_sched_barrier(0)
; template <class Epi, class Sched>
; __device__ __forceinline__ void gemm_phase(LAS unsigned char* lds, const Gemm g, const Sched& S, const Epi& E) {
;     ...
;             PG8_LDB(B0, 0, 0); PG8_SCHED; PG8_LDA(At, 0, 0); PG8_STAGE(PG8_SA(1, 1), a1 + hstepA, voffA);
;             PG8_WAIT_L(8); PG8_BAR; PG8_WAIT_L(0); PG8_MMA(0, 0, At, B0); PG8_BAR; PG8_SCHED;
;             PG8_LDB(B1, 0, 1); PG8_STAGE(PG8_SB(0, 0), b2, voffB);
;             PG8_BAR; PG8_WAIT_L(0); PG8_MMA(0, 1, At, B1); PG8_BAR;
;             PG8_LDA(At, 0, 1); PG8_STAGE(PG8_SA(0, 0), a2, voffA);
;             PG8_BAR; PG8_WAIT_L(0); PG8_MMA(1, 0, At, B0); PG8_BAR; PG8_SCHED;
;             PG8_STAGE(PG8_SB(0, 1), b2 + hstepB, voffB);
;             PG8_WAIT_V(6); PG8_BAR; PG8_MMA(1, 1, At, B1); PG8_BAR;
.LBB0_966:
	s_setprio 0
	s_add_u32 s20, s6, 0xfff80080
	s_addc_u32 s21, s7, -1
	s_add_i32 s52, 0, 0x10000
	v_add_u32_e32 v144, s52, v1
	ds_read_b128 v[132:135], v144
	ds_read_b128 v[136:139], v144 offset:1024
	ds_read_b128 v[140:143], v144 offset:2048
	ds_read_b128 v[144:147], v144 offset:3072
	s_cmp_eq_u32 s51, 28
	s_cselect_b32 s25, s15, s21
	s_cselect_b32 s24, s47, s20
	s_cselect_b32 s21, s1, s50
	s_cselect_b32 s20, s48, s49
	ds_read_b128 v[148:151], v224
	ds_read_b128 v[152:155], v224 offset:1024
	ds_read_b128 v[156:159], v224 offset:2048
	ds_read_b128 v[160:163], v224 offset:3072
	ds_read_b128 v[164:167], v224 offset:4096
	ds_read_b128 v[168:171], v224 offset:5120
	ds_read_b128 v[172:175], v224 offset:6144
	ds_read_b128 v[176:179], v224 offset:7168
	s_add_i32 s54, 0, 0x14000
	v_add_u32_e32 v202, s54, v1
	ds_read_b128 v[180:183], v202
	ds_read_b128 v[184:187], v202 offset:1024
	ds_read_b128 v[188:191], v202 offset:2048
	ds_read_b128 v[202:205], v202 offset:3072
	s_add_i32 m0, s31, 0xc000
	s_nop 0
	global_load_lds_dwordx4 v198, s[6:7]
	s_add_i32 m0, s31, 0xe000
	s_nop 0
	global_load_lds_dwordx4 v200, s[6:7]
	s_waitcnt lgkmcnt(0)
	s_setprio 1
	s_barrier
	v_mfma_f32_16x16x32_bf16 v[128:131], v[132:135], v[148:151], v[128:131]
	v_mfma_f32_16x16x32_bf16 v[124:127], v[140:143], v[148:151], v[124:127]
	v_mfma_f32_16x16x32_bf16 v[112:115], v[132:135], v[156:159], v[112:115]
	v_mfma_f32_16x16x32_bf16 v[108:111], v[140:143], v[156:159], v[108:111]
	v_mfma_f32_16x16x32_bf16 v[100:103], v[132:135], v[164:167], v[100:103]
	v_mfma_f32_16x16x32_bf16 v[92:95], v[140:143], v[164:167], v[92:95]
	v_mfma_f32_16x16x32_bf16 v[84:87], v[132:135], v[172:175], v[84:87]
	v_mfma_f32_16x16x32_bf16 v[76:79], v[140:143], v[172:175], v[76:79]
	v_mfma_f32_16x16x32_bf16 v[128:131], v[136:139], v[152:155], v[128:131]
	v_mfma_f32_16x16x32_bf16 v[124:127], v[144:147], v[152:155], v[124:127]
	v_mfma_f32_16x16x32_bf16 v[112:115], v[136:139], v[160:163], v[112:115]
	v_mfma_f32_16x16x32_bf16 v[108:111], v[144:147], v[160:163], v[108:111]
	v_mfma_f32_16x16x32_bf16 v[100:103], v[136:139], v[168:171], v[100:103]
	v_mfma_f32_16x16x32_bf16 v[92:95], v[144:147], v[168:171], v[92:95]
	v_mfma_f32_16x16x32_bf16 v[84:87], v[136:139], v[176:179], v[84:87]
	v_mfma_f32_16x16x32_bf16 v[76:79], v[144:147], v[176:179], v[76:79]
	v_mfma_f32_16x16x32_bf16 v[120:123], v[180:183], v[148:151], v[120:123]
	v_mfma_f32_16x16x32_bf16 v[116:119], v[188:191], v[148:151], v[116:119]
	v_mfma_f32_16x16x32_bf16 v[104:107], v[180:183], v[156:159], v[104:107]
	v_mfma_f32_16x16x32_bf16 v[96:99], v[188:191], v[156:159], v[96:99]
	v_mfma_f32_16x16x32_bf16 v[88:91], v[180:183], v[164:167], v[88:91]
	v_mfma_f32_16x16x32_bf16 v[80:83], v[188:191], v[164:167], v[80:83]
	v_mfma_f32_16x16x32_bf16 v[72:75], v[180:183], v[172:175], v[72:75]
	v_mfma_f32_16x16x32_bf16 v[68:71], v[188:191], v[172:175], v[68:71]
	v_mfma_f32_16x16x32_bf16 v[120:123], v[184:187], v[152:155], v[120:123]
	v_mfma_f32_16x16x32_bf16 v[116:119], v[202:205], v[152:155], v[116:119]
	v_mfma_f32_16x16x32_bf16 v[104:107], v[184:187], v[160:163], v[104:107]
	v_mfma_f32_16x16x32_bf16 v[96:99], v[202:205], v[160:163], v[96:99]
	v_mfma_f32_16x16x32_bf16 v[88:91], v[184:187], v[168:171], v[88:91]
	v_mfma_f32_16x16x32_bf16 v[80:83], v[202:205], v[168:171], v[80:83]
	v_mfma_f32_16x16x32_bf16 v[72:75], v[184:187], v[176:179], v[72:75]
	v_mfma_f32_16x16x32_bf16 v[68:71], v[202:205], v[176:179], v[68:71]
	s_barrier
	s_setprio 0
	ds_read_b128 v[148:151], v224 offset:16384
	ds_read_b128 v[152:155], v224 offset:17408
	ds_read_b128 v[156:159], v224 offset:18432
	ds_read_b128 v[160:163], v224 offset:19456
	ds_read_b128 v[164:167], v224 offset:20480
	ds_read_b128 v[168:171], v224 offset:21504
	ds_read_b128 v[172:175], v224 offset:22528
	ds_read_b128 v[176:179], v224 offset:23552
	s_add_i32 s52, s52, s30
	v_lshl_add_u64 v[206:207], s[20:21], 0, v[2:3]
	s_mov_b32 m0, s52
	s_nop 0
	global_load_lds_dwordx4 v[206:207], off
	v_lshl_add_u64 v[208:209], s[20:21], 0, v[192:193]
	s_add_i32 m0, s52, 0x2000
	s_nop 0
	global_load_lds_dwordx4 v[208:209], off
	s_mov_b32 m0, s31
	v_lshl_add_u64 v[210:211], s[24:25], 0, v[196:197]
	global_load_lds_dwordx4 v[210:211], off
	v_lshl_add_u64 v[212:213], s[24:25], 0, v[194:195]
	s_mov_b32 m0, s35
	s_nop 0
	global_load_lds_dwordx4 v[212:213], off
	s_add_u32 s52, s20, 0x80000
	s_addc_u32 s53, s21, 0
	s_add_i32 s54, s54, s30
	s_mov_b32 m0, s54
	s_nop 0
	global_load_lds_dwordx4 v2, s[52:53]
	s_add_i32 m0, s54, 0x2000
	s_nop 0
	global_load_lds_dwordx4 v192, s[52:53]
	s_waitcnt lgkmcnt(0)
	s_waitcnt vmcnt(6)
	s_setprio 1
	s_barrier
; #define PG8_STAGE(bufoff, gbase, voff) do { _Pragma("unroll") for (int _i = 0; _i < 2; ++_i) \
;         __builtin_amdgcn_global_load_lds((const unsigned*)((const char*)(gbase) + (voff)[_i]), (LAS unsigned*)(lds + (bufoff) + ldsw + _i * 8192), 16, 0, 0); } while (0)
; #define PG8_LDA(dst, b, h) do { _Pragma("unroll") for (int m = 0; m < 4; ++m) _Pragma("unroll") for (int k = 0; k < 2; ++k) dst[m][k] = *(const LAS bf16x8*)(lds + PG8_SA(b, h) + aoff + m * 2048 + k * 1024); } while (0)
; #define PG8_LDB(dst, b, h) do { _Pragma("unroll") for (int n = 0; n < 2; ++n) _Pragma("unroll") for (int k = 0; k < 2; ++k) dst[n][k] = *(const LAS bf16x8*)(lds + PG8_SB(b, h) + boff + n * 2048 + k * 1024); } while (0)
; #define PG8_MMA(ai, bj, At, Bt) do { __builtin_amdgcn_s_setprio(1); _Pragma("unroll") for (int m = 0; m < 4; ++m) _Pragma("unroll") for (int n = 0; n < 2; ++n) _Pragma("unroll") for (int k = 0; k < 2; ++k) \
;         acc[ai][bj][m][n] = __builtin_amdgcn_mfma_f32_16x16x32_bf16(Bt[n][k], At[m][k], acc[ai][bj][m][n], 0, 0, 0); __builtin_amdgcn_s_setprio(0); } while (0)
; #define PG8_WAIT_V(n) asm volatile("s_waitcnt vmcnt(" #n ")" ::: "memory")
; #define PG8_WAIT_L(n) asm volatile("s_waitcnt lgkmcnt(" #n ")" ::: "memory")
; #define PG8_BAR __builtin_amdgcn_s_barrier()
; #define PG8_SCHED __builtin_amdgcn_sched_barrier(0)
; template <class Epi, class Sched>
; __device__ __forceinline__ void gemm_phase(LAS unsigned char* lds, const Gemm g, const Sched& S, const Epi& E) {
;     ...
;             PG8_WAIT_V(6); PG8_BAR; PG8_MMA(1, 1, At, B1); PG8_BAR;
;             PG8_LDB(B0, 1, 0); PG8_SCHED; PG8_LDA(At, 1, 0); PG8_STAGE(PG8_SA(0, 1), a2 + hstepA, voffA);
;             PG8_WAIT_L(8); PG8_BAR; PG8_WAIT_L(0); PG8_MMA(0, 0, At, B0); PG8_BAR; PG8_SCHED;
;             PG8_LDB(B1, 1, 1); PG8_STAGE(PG8_SB(1, 0), b3, voffB);
;             PG8_BAR; PG8_WAIT_L(0); PG8_MMA(0, 1, At, B1); PG8_BAR;
	v_mfma_f32_16x16x32_bf16 v[64:67], v[132:135], v[148:151], v[64:67]
	v_mfma_f32_16x16x32_bf16 v[60:63], v[140:143], v[148:151], v[60:63]
	v_mfma_f32_16x16x32_bf16 v[52:55], v[132:135], v[156:159], v[52:55]
	v_mfma_f32_16x16x32_bf16 v[44:47], v[140:143], v[156:159], v[44:47]
	v_mfma_f32_16x16x32_bf16 v[36:39], v[132:135], v[164:167], v[36:39]
	v_mfma_f32_16x16x32_bf16 v[28:31], v[140:143], v[164:167], v[28:31]
	v_mfma_f32_16x16x32_bf16 v[20:23], v[132:135], v[172:175], v[20:23]
	v_mfma_f32_16x16x32_bf16 v[12:15], v[140:143], v[172:175], v[12:15]
	v_mfma_f32_16x16x32_bf16 v[64:67], v[136:139], v[152:155], v[64:67]
	v_mfma_f32_16x16x32_bf16 v[60:63], v[144:147], v[152:155], v[60:63]
	v_mfma_f32_16x16x32_bf16 v[52:55], v[136:139], v[160:163], v[52:55]
	v_mfma_f32_16x16x32_bf16 v[44:47], v[144:147], v[160:163], v[44:47]
	v_mfma_f32_16x16x32_bf16 v[36:39], v[136:139], v[168:171], v[36:39]
	v_mfma_f32_16x16x32_bf16 v[28:31], v[144:147], v[168:171], v[28:31]
	v_mfma_f32_16x16x32_bf16 v[20:23], v[136:139], v[176:179], v[20:23]
	v_mfma_f32_16x16x32_bf16 v[12:15], v[144:147], v[176:179], v[12:15]
	v_mfma_f32_16x16x32_bf16 v[56:59], v[180:183], v[148:151], v[56:59]
	v_mfma_f32_16x16x32_bf16 v[48:51], v[188:191], v[148:151], v[48:51]
	v_mfma_f32_16x16x32_bf16 v[40:43], v[180:183], v[156:159], v[40:43]
	v_mfma_f32_16x16x32_bf16 v[32:35], v[188:191], v[156:159], v[32:35]
	v_mfma_f32_16x16x32_bf16 v[24:27], v[180:183], v[164:167], v[24:27]
	v_mfma_f32_16x16x32_bf16 v[16:19], v[188:191], v[164:167], v[16:19]
	v_mfma_f32_16x16x32_bf16 v[8:11], v[180:183], v[172:175], v[8:11]
	v_mfma_f32_16x16x32_bf16 v[4:7], v[188:191], v[172:175], v[4:7]
	v_mfma_f32_16x16x32_bf16 v[56:59], v[184:187], v[152:155], v[56:59]
	v_mfma_f32_16x16x32_bf16 v[48:51], v[202:205], v[152:155], v[48:51]
	v_mfma_f32_16x16x32_bf16 v[40:43], v[184:187], v[160:163], v[40:43]
	v_mfma_f32_16x16x32_bf16 v[32:35], v[202:205], v[160:163], v[32:35]
	v_mfma_f32_16x16x32_bf16 v[24:27], v[184:187], v[168:171], v[24:27]
	v_mfma_f32_16x16x32_bf16 v[16:19], v[202:205], v[168:171], v[16:19]
	v_mfma_f32_16x16x32_bf16 v[8:11], v[184:187], v[176:179], v[8:11]
	v_mfma_f32_16x16x32_bf16 v[4:7], v[202:205], v[176:179], v[4:7]
	s_barrier
	s_setprio 0
	s_add_i32 s52, 0, 0x18000
	v_add_u32_e32 v144, s52, v1
	ds_read_b128 v[132:135], v144
	ds_read_b128 v[136:139], v144 offset:1024
	ds_read_b128 v[140:143], v144 offset:2048
	ds_read_b128 v[144:147], v144 offset:3072
	s_add_u32 s24, s24, 0x80000
	s_addc_u32 s25, s25, 0
	ds_read_b128 v[148:151], v224 offset:32768
	ds_read_b128 v[152:155], v224 offset:33792
	ds_read_b128 v[156:159], v224 offset:34816
	ds_read_b128 v[160:163], v224 offset:35840
	ds_read_b128 v[164:167], v224 offset:36864
	ds_read_b128 v[168:171], v224 offset:37888
	ds_read_b128 v[172:175], v224 offset:38912
	ds_read_b128 v[176:179], v224 offset:39936
	s_mov_b32 m0, s36
	s_nop 0
	global_load_lds_dwordx4 v196, s[24:25]
	s_mov_b32 m0, s37
	s_nop 0
	global_load_lds_dwordx4 v194, s[24:25]
	s_add_i32 s24, 0, 0x1c000
	v_add_u32_e32 v202, s24, v1
	ds_read_b128 v[180:183], v202
	ds_read_b128 v[184:187], v202 offset:1024
	ds_read_b128 v[188:191], v202 offset:2048
	ds_read_b128 v[202:205], v202 offset:3072
	s_waitcnt lgkmcnt(0)
	s_setprio 1
	s_barrier
	v_mfma_f32_16x16x32_bf16 v[128:131], v[132:135], v[148:151], v[128:131]
	v_mfma_f32_16x16x32_bf16 v[124:127], v[140:143], v[148:151], v[124:127]
	v_mfma_f32_16x16x32_bf16 v[112:115], v[132:135], v[156:159], v[112:115]
	v_mfma_f32_16x16x32_bf16 v[108:111], v[140:143], v[156:159], v[108:111]
	v_mfma_f32_16x16x32_bf16 v[100:103], v[132:135], v[164:167], v[100:103]
	v_mfma_f32_16x16x32_bf16 v[92:95], v[140:143], v[164:167], v[92:95]
	v_mfma_f32_16x16x32_bf16 v[84:87], v[132:135], v[172:175], v[84:87]
	v_mfma_f32_16x16x32_bf16 v[76:79], v[140:143], v[172:175], v[76:79]
	v_mfma_f32_16x16x32_bf16 v[128:131], v[136:139], v[152:155], v[128:131]
	v_mfma_f32_16x16x32_bf16 v[124:127], v[144:147], v[152:155], v[124:127]
	v_mfma_f32_16x16x32_bf16 v[112:115], v[136:139], v[160:163], v[112:115]
	v_mfma_f32_16x16x32_bf16 v[108:111], v[144:147], v[160:163], v[108:111]
	v_mfma_f32_16x16x32_bf16 v[100:103], v[136:139], v[168:171], v[100:103]
	v_mfma_f32_16x16x32_bf16 v[92:95], v[144:147], v[168:171], v[92:95]
	v_mfma_f32_16x16x32_bf16 v[84:87], v[136:139], v[176:179], v[84:87]
	v_mfma_f32_16x16x32_bf16 v[76:79], v[144:147], v[176:179], v[76:79]
	v_mfma_f32_16x16x32_bf16 v[120:123], v[180:183], v[148:151], v[120:123]
	v_mfma_f32_16x16x32_bf16 v[116:119], v[188:191], v[148:151], v[116:119]
	v_mfma_f32_16x16x32_bf16 v[104:107], v[180:183], v[156:159], v[104:107]
	v_mfma_f32_16x16x32_bf16 v[96:99], v[188:191], v[156:159], v[96:99]
	v_mfma_f32_16x16x32_bf16 v[88:91], v[180:183], v[164:167], v[88:91]
	v_mfma_f32_16x16x32_bf16 v[80:83], v[188:191], v[164:167], v[80:83]
	v_mfma_f32_16x16x32_bf16 v[72:75], v[180:183], v[172:175], v[72:75]
	v_mfma_f32_16x16x32_bf16 v[68:71], v[188:191], v[172:175], v[68:71]
	v_mfma_f32_16x16x32_bf16 v[120:123], v[184:187], v[152:155], v[120:123]
	v_mfma_f32_16x16x32_bf16 v[116:119], v[202:205], v[152:155], v[116:119]
	v_mfma_f32_16x16x32_bf16 v[104:107], v[184:187], v[160:163], v[104:107]
	v_mfma_f32_16x16x32_bf16 v[96:99], v[202:205], v[160:163], v[96:99]
	v_mfma_f32_16x16x32_bf16 v[88:91], v[184:187], v[168:171], v[88:91]
	v_mfma_f32_16x16x32_bf16 v[80:83], v[202:205], v[168:171], v[80:83]
	v_mfma_f32_16x16x32_bf16 v[72:75], v[184:187], v[176:179], v[72:75]
	v_mfma_f32_16x16x32_bf16 v[68:71], v[202:205], v[176:179], v[68:71]
	s_barrier
; __device__ __forceinline__ int opaque_tid() { int t = threadIdx.x; asm volatile("" : "+v"(t)); return t; }
; #define PG8_STAGE(bufoff, gbase, voff) do { _Pragma("unroll") for (int _i = 0; _i < 2; ++_i) \
;         __builtin_amdgcn_global_load_lds((const unsigned*)((const char*)(gbase) + (voff)[_i]), (LAS unsigned*)(lds + (bufoff) + ldsw + _i * 8192), 16, 0, 0); } while (0)
; #define PG8_LDA(dst, b, h) do { _Pragma("unroll") for (int m = 0; m < 4; ++m) _Pragma("unroll") for (int k = 0; k < 2; ++k) dst[m][k] = *(const LAS bf16x8*)(lds + PG8_SA(b, h) + aoff + m * 2048 + k * 1024); } while (0)
; #define PG8_MMA(ai, bj, At, Bt) do { __builtin_amdgcn_s_setprio(1); _Pragma("unroll") for (int m = 0; m < 4; ++m) _Pragma("unroll") for (int n = 0; n < 2; ++n) _Pragma("unroll") for (int k = 0; k < 2; ++k) \
;         acc[ai][bj][m][n] = __builtin_amdgcn_mfma_f32_16x16x32_bf16(Bt[n][k], At[m][k], acc[ai][bj][m][n], 0, 0, 0); __builtin_amdgcn_s_setprio(0); } while (0)
; #define PG8_WAIT_V(n) asm volatile("s_waitcnt vmcnt(" #n ")" ::: "memory")
; #define PG8_WAIT_L(n) asm volatile("s_waitcnt lgkmcnt(" #n ")" ::: "memory")
; #define PG8_BAR __builtin_amdgcn_s_barrier()
; #define PG8_SCHED __builtin_amdgcn_sched_barrier(0)
;     __device__ __forceinline__ void operator()(const f32x4 (&acc)[2][2][4][2], const Unit& u, int wr, int wc, int, int) const {
;         const int ol_ = opaque_tid() & 63, fr = ol_ & 15, fq = ol_ >> 4;
;         const int row0 = u.pm * BM + wr * 64 + fr, col0 = u.pn * BM + wc * 32 + 8 * fq;
;         u32x4 cin[2][4][2];
; #pragma unroll
;         for (int ai = 0; ai < 2; ++ai)
; #pragma unroll
;             for (int m = 0; m < 4; ++m)
; #pragma unroll
;                 for (int bj = 0; bj < 2; ++bj) cin[ai][m][bj] = *(const u32x4*)(C + (size_t)(row0 + ai * HALF + m * 16) * ldc + col0 + bj * HALF);
; template <class Epi, class Sched>
; __device__ __forceinline__ void gemm_phase(LAS unsigned char* lds, const Gemm g, const Sched& S, const Epi& E) {
;     ...
;             PG8_BAR; PG8_WAIT_L(0); PG8_MMA(0, 1, At, B1); PG8_BAR;
;             PG8_LDA(At, 1, 1); PG8_STAGE(PG8_SA(1, 0), a3, voffA);
;             PG8_BAR; PG8_WAIT_L(0); PG8_MMA(1, 0, At, B0); PG8_BAR; PG8_SCHED;
;             PG8_STAGE(PG8_SB(1, 1), b3 + hstepB, voffB);
;             PG8_WAIT_V(6); PG8_BAR; PG8_MMA(1, 1, At, B1); PG8_BAR;
;         }
;         E(acc, cur, wr, wc, ui, fq);
	s_setprio 0
	ds_read_b128 v[148:151], v224 offset:49152
	ds_read_b128 v[152:155], v224 offset:50176
	ds_read_b128 v[156:159], v224 offset:51200
	ds_read_b128 v[160:163], v224 offset:52224
	ds_read_b128 v[164:167], v224 offset:53248
	ds_read_b128 v[168:171], v224 offset:54272
	ds_read_b128 v[172:175], v224 offset:55296
	ds_read_b128 v[176:179], v224 offset:56320
	s_add_i32 s25, s52, s30
	v_lshl_add_u64 v[206:207], v[206:207], 0, s[8:9]
	s_mov_b32 m0, s25
	s_nop 0
	global_load_lds_dwordx4 v[206:207], off
	v_lshl_add_u64 v[206:207], v[208:209], 0, s[8:9]
	s_add_i32 m0, s25, 0x2000
	s_nop 0
	global_load_lds_dwordx4 v[206:207], off
	s_mov_b32 m0, s40
	v_lshl_add_u64 v[206:207], v[210:211], 0, s[8:9]
	global_load_lds_dwordx4 v[206:207], off
	v_lshl_add_u64 v[206:207], v[212:213], 0, s[8:9]
	s_mov_b32 m0, s41
	s_nop 0
	global_load_lds_dwordx4 v[206:207], off
	s_add_u32 s20, s20, 0x80080
	s_addc_u32 s21, s21, 0
	s_add_i32 s24, s24, s30
	s_mov_b32 m0, s24
	s_nop 0
	global_load_lds_dwordx4 v2, s[20:21]
	s_add_i32 m0, s24, 0x2000
	s_nop 0
	global_load_lds_dwordx4 v192, s[20:21]
	s_add_i32 s51, s51, 2
	s_add_u32 s6, s6, 0x100
	s_addc_u32 s7, s7, 0
	s_add_u32 s49, s49, 0x100
	s_addc_u32 s50, s50, 0
	s_cmp_gt_u32 s51, 29
	s_waitcnt lgkmcnt(0)
	s_waitcnt vmcnt(6)
	s_setprio 1
	s_barrier
	v_mfma_f32_16x16x32_bf16 v[64:67], v[132:135], v[148:151], v[64:67]
	v_mfma_f32_16x16x32_bf16 v[60:63], v[140:143], v[148:151], v[60:63]
	v_mfma_f32_16x16x32_bf16 v[52:55], v[132:135], v[156:159], v[52:55]
	v_mfma_f32_16x16x32_bf16 v[44:47], v[140:143], v[156:159], v[44:47]
	v_mfma_f32_16x16x32_bf16 v[36:39], v[132:135], v[164:167], v[36:39]
	v_mfma_f32_16x16x32_bf16 v[28:31], v[140:143], v[164:167], v[28:31]
	v_mfma_f32_16x16x32_bf16 v[20:23], v[132:135], v[172:175], v[20:23]
	v_mfma_f32_16x16x32_bf16 v[12:15], v[140:143], v[172:175], v[12:15]
	v_mfma_f32_16x16x32_bf16 v[64:67], v[136:139], v[152:155], v[64:67]
	v_mfma_f32_16x16x32_bf16 v[60:63], v[144:147], v[152:155], v[60:63]
	v_mfma_f32_16x16x32_bf16 v[52:55], v[136:139], v[160:163], v[52:55]
	v_mfma_f32_16x16x32_bf16 v[44:47], v[144:147], v[160:163], v[44:47]
	v_mfma_f32_16x16x32_bf16 v[36:39], v[136:139], v[168:171], v[36:39]
	v_mfma_f32_16x16x32_bf16 v[28:31], v[144:147], v[168:171], v[28:31]
	v_mfma_f32_16x16x32_bf16 v[20:23], v[136:139], v[176:179], v[20:23]
	v_mfma_f32_16x16x32_bf16 v[12:15], v[144:147], v[176:179], v[12:15]
	v_mfma_f32_16x16x32_bf16 v[56:59], v[180:183], v[148:151], v[56:59]
	v_mfma_f32_16x16x32_bf16 v[48:51], v[188:191], v[148:151], v[48:51]
	v_mfma_f32_16x16x32_bf16 v[40:43], v[180:183], v[156:159], v[40:43]
	v_mfma_f32_16x16x32_bf16 v[32:35], v[188:191], v[156:159], v[32:35]
	v_mfma_f32_16x16x32_bf16 v[24:27], v[180:183], v[164:167], v[24:27]
	v_mfma_f32_16x16x32_bf16 v[16:19], v[188:191], v[164:167], v[16:19]
	v_mfma_f32_16x16x32_bf16 v[8:11], v[180:183], v[172:175], v[8:11]
	v_mfma_f32_16x16x32_bf16 v[4:7], v[188:191], v[172:175], v[4:7]
	v_mfma_f32_16x16x32_bf16 v[56:59], v[184:187], v[152:155], v[56:59]
	v_mfma_f32_16x16x32_bf16 v[48:51], v[202:205], v[152:155], v[48:51]
	v_mfma_f32_16x16x32_bf16 v[40:43], v[184:187], v[160:163], v[40:43]
	v_mfma_f32_16x16x32_bf16 v[32:35], v[202:205], v[160:163], v[32:35]
	v_mfma_f32_16x16x32_bf16 v[24:27], v[184:187], v[168:171], v[24:27]
	v_mfma_f32_16x16x32_bf16 v[16:19], v[202:205], v[168:171], v[16:19]
	v_mfma_f32_16x16x32_bf16 v[8:11], v[184:187], v[176:179], v[8:11]
	v_mfma_f32_16x16x32_bf16 v[4:7], v[202:205], v[176:179], v[4:7]
	s_barrier
	s_cbranch_scc0 .LBB0_966
	s_setprio 0
	v_mov_b32_e32 v133, v0
	s_lshl_b32 s1, s46, 8
	s_add_i32 s1, s1, s38
	v_and_or_b32 v132, v133, 15, s1
	s_lshl_b32 s1, s45, 8
	v_lshrrev_b32_e32 v133, 1, v133
	v_and_or_b32 v133, v133, 24, s1
	v_or_b32_e32 v134, s39, v133
	v_ashrrev_i32_e32 v135, 31, v134
	v_lshlrev_b64 v[202:203], 1, v[134:135]
	v_ashrrev_i32_e32 v133, 31, v132
	v_lshl_add_u64 v[134:135], s[88:89], 0, v[202:203]
	v_lshlrev_b64 v[226:227], 12, v[132:133]
	v_lshl_add_u64 v[136:137], v[134:135], 0, v[226:227]
	global_load_dwordx4 v[216:219], v[136:137], off
	global_load_dwordx4 v[188:191], v[136:137], off offset:256
	v_or_b32_e32 v136, 16, v132
	v_ashrrev_i32_e32 v137, 31, v136
	v_lshlrev_b64 v[222:223], 12, v[136:137]
	v_lshl_add_u64 v[136:137], v[134:135], 0, v[222:223]
	global_load_dwordx4 v[184:187], v[136:137], off
	global_load_dwordx4 v[180:183], v[136:137], off offset:256
	v_or_b32_e32 v136, 32, v132
	v_ashrrev_i32_e32 v137, 31, v136
	v_lshlrev_b64 v[220:221], 12, v[136:137]
	v_lshl_add_u64 v[136:137], v[134:135], 0, v[220:221]
	global_load_dwordx4 v[176:179], v[136:137], off
	global_load_dwordx4 v[168:171], v[136:137], off offset:256
	v_or_b32_e32 v132, 48, v132
	v_ashrrev_i32_e32 v133, 31, v132
	v_lshlrev_b64 v[212:213], 12, v[132:133]
	v_lshl_add_u64 v[132:133], v[134:135], 0, v[212:213]
	global_load_dwordx4 v[172:175], v[132:133], off
	global_load_dwordx4 v[164:167], v[132:133], off offset:256
	s_mov_b64 s[6:7], 0x80000
	v_lshl_add_u64 v[210:211], v[226:227], 0, s[6:7]
	v_lshl_add_u64 v[132:133], v[134:135], 0, v[210:211]
	global_load_dwordx4 v[160:163], v[132:133], off
	global_load_dwordx4 v[156:159], v[132:133], off offset:256
	s_mov_b64 s[6:7], 0x90000
	v_lshl_add_u64 v[208:209], v[226:227], 0, s[6:7]
	v_lshl_add_u64 v[132:133], v[134:135], 0, v[208:209]
	global_load_dwordx4 v[152:155], v[132:133], off
	global_load_dwordx4 v[148:151], v[132:133], off offset:256
	s_mov_b64 s[6:7], 0xa0000
	v_lshl_add_u64 v[206:207], v[226:227], 0, s[6:7]
	v_lshl_add_u64 v[132:133], v[134:135], 0, v[206:207]
	global_load_dwordx4 v[144:147], v[132:133], off
	global_load_dwordx4 v[140:143], v[132:133], off offset:256
	s_mov_b64 s[6:7], 0xb0000
	v_lshl_add_u64 v[204:205], v[226:227], 0, s[6:7]
	v_lshl_add_u64 v[132:133], v[134:135], 0, v[204:205]
	global_load_dwordx4 v[136:139], v[132:133], off
	s_nop 0
	global_load_dwordx4 v[132:135], v[132:133], off offset:256
	s_and_b64 vcc, exec, s[42:43]
	s_mov_b32 s45, s0
	s_mov_b32 s46, s14
	s_mov_b64 s[20:21], s[18:19]
	s_mov_b64 s[6:7], s[4:5]
	s_waitcnt vmcnt(15)
; __device__ __forceinline__ unsigned cvt_pk_bf16(float lo, float hi) { const f32x2 v = {lo, hi}; const bf16v2_ r = __builtin_convertvector(v, bf16v2_); return __builtin_bit_cast(unsigned, r); }
; __device__ __forceinline__ float bflo(unsigned w) { return __uint_as_float(w << 16); }
; __device__ __forceinline__ float bfhi(unsigned w) { return __uint_as_float(w & 0xffff0000u); }
;     __device__ __forceinline__ void operator()(const f32x4 (&acc)[2][2][4][2], const Unit& u, int wr, int wc, int, int) const {
;     ...
; #pragma unroll
;         for (int ai = 0; ai < 2; ++ai)
; #pragma unroll
;             for (int m = 0; m < 4; ++m)
; #pragma unroll
;                 for (int bj = 0; bj < 2; ++bj) { const u32x4 c = cin[ai][m][bj]; const f32x4 v0 = acc[ai][bj][m][0], v1 = acc[ai][bj][m][1];
;                     u32x4 w; w.x = cvt_pk_bf16(bflo(c.x) + v0[0], bfhi(c.x) + v0[1]); w.y = cvt_pk_bf16(bflo(c.y) + v0[2], bfhi(c.y) + v0[3]);
;                     w.z = cvt_pk_bf16(bflo(c.z) + v1[0], bfhi(c.z) + v1[1]); w.w = cvt_pk_bf16(bflo(c.w) + v1[2], bfhi(c.w) + v1[3]);
;                     *(u32x4*)(C + (size_t)(row0 + ai * HALF + m * 16) * ldc + col0 + bj * HALF) = w; }
	v_lshlrev_b32_e32 v228, 16, v216
	v_and_b32_e32 v229, 0xffff0000, v216
	v_lshlrev_b32_e32 v216, 16, v217
	v_and_b32_e32 v217, 0xffff0000, v217
	v_pk_add_f32 v[128:129], v[128:129], v[228:229]
	v_pk_add_f32 v[130:131], v[130:131], v[216:217]
	v_cvt_pk_bf16_f32 v128, v128, v129
	v_cvt_pk_bf16_f32 v129, v130, v131
	v_lshlrev_b32_e32 v130, 16, v218
	v_and_b32_e32 v131, 0xffff0000, v218
	v_pk_add_f32 v[124:125], v[124:125], v[130:131]
	s_nop 0
	v_cvt_pk_bf16_f32 v130, v124, v125
	v_lshlrev_b32_e32 v124, 16, v219
	v_and_b32_e32 v125, 0xffff0000, v219
	v_pk_add_f32 v[124:125], v[126:127], v[124:125]
	s_waitcnt vmcnt(14)
	v_lshlrev_b32_e32 v126, 16, v188
	v_and_b32_e32 v127, 0xffff0000, v188
	v_pk_add_f32 v[120:121], v[120:121], v[126:127]
	v_lshlrev_b32_e32 v126, 16, v189
	v_and_b32_e32 v127, 0xffff0000, v189
	v_pk_add_f32 v[122:123], v[122:123], v[126:127]
	v_cvt_pk_bf16_f32 v120, v120, v121
	v_cvt_pk_bf16_f32 v121, v122, v123
	v_lshlrev_b32_e32 v122, 16, v190
	v_and_b32_e32 v123, 0xffff0000, v190
	v_pk_add_f32 v[116:117], v[116:117], v[122:123]
	v_cvt_pk_bf16_f32 v131, v124, v125
	v_cvt_pk_bf16_f32 v122, v116, v117
	v_lshlrev_b32_e32 v116, 16, v191
	v_and_b32_e32 v117, 0xffff0000, v191
	v_pk_add_f32 v[116:117], v[118:119], v[116:117]
	v_lshl_add_u64 v[124:125], s[88:89], 0, v[226:227]
	v_cvt_pk_bf16_f32 v123, v116, v117
	s_waitcnt vmcnt(13)
	v_lshlrev_b32_e32 v116, 16, v184
	v_and_b32_e32 v117, 0xffff0000, v184
	v_pk_add_f32 v[112:113], v[112:113], v[116:117]
	v_lshlrev_b32_e32 v116, 16, v185
	v_and_b32_e32 v117, 0xffff0000, v185
	v_pk_add_f32 v[114:115], v[114:115], v[116:117]
	v_cvt_pk_bf16_f32 v112, v112, v113
	v_cvt_pk_bf16_f32 v113, v114, v115
	v_lshlrev_b32_e32 v114, 16, v186
	v_and_b32_e32 v115, 0xffff0000, v186
	v_pk_add_f32 v[108:109], v[108:109], v[114:115]
	v_lshl_add_u64 v[124:125], v[124:125], 0, v[202:203]
	v_cvt_pk_bf16_f32 v114, v108, v109
	v_lshlrev_b32_e32 v108, 16, v187
	v_and_b32_e32 v109, 0xffff0000, v187
	v_pk_add_f32 v[108:109], v[110:111], v[108:109]
	s_waitcnt vmcnt(12)
	v_lshlrev_b32_e32 v110, 16, v180
	v_and_b32_e32 v111, 0xffff0000, v180
	v_pk_add_f32 v[104:105], v[104:105], v[110:111]
	v_lshlrev_b32_e32 v110, 16, v181
	v_and_b32_e32 v111, 0xffff0000, v181
	v_pk_add_f32 v[106:107], v[106:107], v[110:111]
	v_cvt_pk_bf16_f32 v104, v104, v105
	v_cvt_pk_bf16_f32 v105, v106, v107
	v_lshlrev_b32_e32 v106, 16, v182
	v_and_b32_e32 v107, 0xffff0000, v182
	v_pk_add_f32 v[96:97], v[96:97], v[106:107]
	v_cvt_pk_bf16_f32 v115, v108, v109
	v_cvt_pk_bf16_f32 v106, v96, v97
	v_lshlrev_b32_e32 v96, 16, v183
	v_and_b32_e32 v97, 0xffff0000, v183
	v_pk_add_f32 v[96:97], v[98:99], v[96:97]
	s_waitcnt vmcnt(11)
	v_lshlrev_b32_e32 v98, 16, v177
	v_cvt_pk_bf16_f32 v107, v96, v97
	v_lshlrev_b32_e32 v96, 16, v176
	v_and_b32_e32 v97, 0xffff0000, v176
	v_and_b32_e32 v99, 0xffff0000, v177
	v_pk_add_f32 v[96:97], v[100:101], v[96:97]
	v_pk_add_f32 v[98:99], v[102:103], v[98:99]
	v_cvt_pk_bf16_f32 v96, v96, v97
	v_cvt_pk_bf16_f32 v97, v98, v99
	v_lshlrev_b32_e32 v98, 16, v178
	v_and_b32_e32 v99, 0xffff0000, v178
	v_pk_add_f32 v[92:93], v[92:93], v[98:99]
	v_lshl_add_u64 v[108:109], s[88:89], 0, v[222:223]
	v_cvt_pk_bf16_f32 v98, v92, v93
	v_lshlrev_b32_e32 v92, 16, v179
	v_and_b32_e32 v93, 0xffff0000, v179
	v_pk_add_f32 v[92:93], v[94:95], v[92:93]
	s_waitcnt vmcnt(10)
	v_lshlrev_b32_e32 v94, 16, v168
	v_and_b32_e32 v95, 0xffff0000, v168
	v_pk_add_f32 v[88:89], v[88:89], v[94:95]
	v_lshlrev_b32_e32 v94, 16, v169
	v_and_b32_e32 v95, 0xffff0000, v169
	v_pk_add_f32 v[90:91], v[90:91], v[94:95]
	v_cvt_pk_bf16_f32 v88, v88, v89
	v_cvt_pk_bf16_f32 v89, v90, v91
	v_lshlrev_b32_e32 v90, 16, v170
	v_and_b32_e32 v91, 0xffff0000, v170
	v_pk_add_f32 v[80:81], v[80:81], v[90:91]
	v_cvt_pk_bf16_f32 v99, v92, v93
	v_cvt_pk_bf16_f32 v90, v80, v81
	v_lshlrev_b32_e32 v80, 16, v171
	v_and_b32_e32 v81, 0xffff0000, v171
	v_pk_add_f32 v[80:81], v[82:83], v[80:81]
	s_waitcnt vmcnt(9)
	v_lshlrev_b32_e32 v82, 16, v173
	v_cvt_pk_bf16_f32 v91, v80, v81
	v_lshlrev_b32_e32 v80, 16, v172
	v_and_b32_e32 v81, 0xffff0000, v172
	v_and_b32_e32 v83, 0xffff0000, v173
	v_pk_add_f32 v[80:81], v[84:85], v[80:81]
	v_pk_add_f32 v[82:83], v[86:87], v[82:83]
	v_cvt_pk_bf16_f32 v80, v80, v81
	v_cvt_pk_bf16_f32 v81, v82, v83
	v_lshlrev_b32_e32 v82, 16, v174
	v_and_b32_e32 v83, 0xffff0000, v174
	v_pk_add_f32 v[76:77], v[76:77], v[82:83]
	v_lshl_add_u64 v[92:93], s[88:89], 0, v[220:221]
	v_cvt_pk_bf16_f32 v82, v76, v77
	v_lshlrev_b32_e32 v76, 16, v175
	v_and_b32_e32 v77, 0xffff0000, v175
	v_pk_add_f32 v[76:77], v[78:79], v[76:77]
	s_waitcnt vmcnt(8)
	v_lshlrev_b32_e32 v78, 16, v164
	v_and_b32_e32 v79, 0xffff0000, v164
	v_pk_add_f32 v[72:73], v[72:73], v[78:79]
	v_lshlrev_b32_e32 v78, 16, v165
	v_and_b32_e32 v79, 0xffff0000, v165
	v_pk_add_f32 v[74:75], v[74:75], v[78:79]
	v_cvt_pk_bf16_f32 v72, v72, v73
	v_cvt_pk_bf16_f32 v73, v74, v75
	v_lshlrev_b32_e32 v74, 16, v166
	v_and_b32_e32 v75, 0xffff0000, v166
	v_pk_add_f32 v[68:69], v[68:69], v[74:75]
	v_cvt_pk_bf16_f32 v83, v76, v77
	v_cvt_pk_bf16_f32 v74, v68, v69
	v_lshlrev_b32_e32 v68, 16, v167
	v_and_b32_e32 v69, 0xffff0000, v167
	v_pk_add_f32 v[68:69], v[70:71], v[68:69]
	v_lshl_add_u64 v[76:77], s[88:89], 0, v[212:213]
	v_cvt_pk_bf16_f32 v75, v68, v69
	s_waitcnt vmcnt(7)
	v_lshlrev_b32_e32 v68, 16, v160
	v_and_b32_e32 v69, 0xffff0000, v160
	v_pk_add_f32 v[64:65], v[64:65], v[68:69]
	v_lshlrev_b32_e32 v68, 16, v161
	v_and_b32_e32 v69, 0xffff0000, v161
	v_pk_add_f32 v[66:67], v[66:67], v[68:69]
	v_cvt_pk_bf16_f32 v64, v64, v65
	v_cvt_pk_bf16_f32 v65, v66, v67
	v_lshlrev_b32_e32 v66, 16, v162
	v_and_b32_e32 v67, 0xffff0000, v162
	v_pk_add_f32 v[60:61], v[60:61], v[66:67]
	v_lshl_add_u64 v[108:109], v[108:109], 0, v[202:203]
	v_cvt_pk_bf16_f32 v66, v60, v61
	v_lshlrev_b32_e32 v60, 16, v163
	v_and_b32_e32 v61, 0xffff0000, v163
	v_pk_add_f32 v[60:61], v[62:63], v[60:61]
	s_waitcnt vmcnt(6)
; __device__ __forceinline__ unsigned cvt_pk_bf16(float lo, float hi) { const f32x2 v = {lo, hi}; const bf16v2_ r = __builtin_convertvector(v, bf16v2_); return __builtin_bit_cast(unsigned, r); }
; __device__ __forceinline__ float bflo(unsigned w) { return __uint_as_float(w << 16); }
; __device__ __forceinline__ float bfhi(unsigned w) { return __uint_as_float(w & 0xffff0000u); }
;     __device__ __forceinline__ void operator()(const f32x4 (&acc)[2][2][4][2], const Unit& u, int wr, int wc, int, int) const {
;     ...
; #pragma unroll
;         for (int ai = 0; ai < 2; ++ai)
; #pragma unroll
;             for (int m = 0; m < 4; ++m)
; #pragma unroll
;                 for (int bj = 0; bj < 2; ++bj) { const u32x4 c = cin[ai][m][bj]; const f32x4 v0 = acc[ai][bj][m][0], v1 = acc[ai][bj][m][1];
;                     u32x4 w; w.x = cvt_pk_bf16(bflo(c.x) + v0[0], bfhi(c.x) + v0[1]); w.y = cvt_pk_bf16(bflo(c.y) + v0[2], bfhi(c.y) + v0[3]);
;                     w.z = cvt_pk_bf16(bflo(c.z) + v1[0], bfhi(c.z) + v1[1]); w.w = cvt_pk_bf16(bflo(c.w) + v1[2], bfhi(c.w) + v1[3]);
;                     *(u32x4*)(C + (size_t)(row0 + ai * HALF + m * 16) * ldc + col0 + bj * HALF) = w; }
	v_lshlrev_b32_e32 v62, 16, v156
	v_and_b32_e32 v63, 0xffff0000, v156
	v_pk_add_f32 v[56:57], v[56:57], v[62:63]
	v_lshlrev_b32_e32 v62, 16, v157
	v_and_b32_e32 v63, 0xffff0000, v157
	v_pk_add_f32 v[58:59], v[58:59], v[62:63]
	v_cvt_pk_bf16_f32 v56, v56, v57
	v_cvt_pk_bf16_f32 v57, v58, v59
	v_lshlrev_b32_e32 v58, 16, v158
	v_and_b32_e32 v59, 0xffff0000, v158
	v_pk_add_f32 v[48:49], v[48:49], v[58:59]
	v_cvt_pk_bf16_f32 v67, v60, v61
	v_cvt_pk_bf16_f32 v58, v48, v49
	v_lshlrev_b32_e32 v48, 16, v159
	v_and_b32_e32 v49, 0xffff0000, v159
	v_pk_add_f32 v[48:49], v[50:51], v[48:49]
	s_waitcnt vmcnt(5)
	v_lshlrev_b32_e32 v50, 16, v153
	v_cvt_pk_bf16_f32 v59, v48, v49
	v_lshlrev_b32_e32 v48, 16, v152
	v_and_b32_e32 v49, 0xffff0000, v152
	v_and_b32_e32 v51, 0xffff0000, v153
	v_pk_add_f32 v[48:49], v[52:53], v[48:49]
	v_pk_add_f32 v[50:51], v[54:55], v[50:51]
	v_cvt_pk_bf16_f32 v48, v48, v49
	v_cvt_pk_bf16_f32 v49, v50, v51
	v_lshlrev_b32_e32 v50, 16, v154
	v_and_b32_e32 v51, 0xffff0000, v154
	v_pk_add_f32 v[44:45], v[44:45], v[50:51]
	v_lshl_add_u64 v[60:61], s[88:89], 0, v[210:211]
	v_cvt_pk_bf16_f32 v50, v44, v45
	v_lshlrev_b32_e32 v44, 16, v155
	v_and_b32_e32 v45, 0xffff0000, v155
	v_pk_add_f32 v[44:45], v[46:47], v[44:45]
	s_waitcnt vmcnt(4)
	v_lshlrev_b32_e32 v46, 16, v148
	v_and_b32_e32 v47, 0xffff0000, v148
	v_pk_add_f32 v[40:41], v[40:41], v[46:47]
	v_lshlrev_b32_e32 v46, 16, v149
	v_and_b32_e32 v47, 0xffff0000, v149
	v_pk_add_f32 v[42:43], v[42:43], v[46:47]
	v_cvt_pk_bf16_f32 v40, v40, v41
	v_cvt_pk_bf16_f32 v41, v42, v43
	v_lshlrev_b32_e32 v42, 16, v150
	v_and_b32_e32 v43, 0xffff0000, v150
	v_pk_add_f32 v[32:33], v[32:33], v[42:43]
	v_cvt_pk_bf16_f32 v51, v44, v45
	v_cvt_pk_bf16_f32 v42, v32, v33
	v_lshlrev_b32_e32 v32, 16, v151
	v_and_b32_e32 v33, 0xffff0000, v151
	v_pk_add_f32 v[32:33], v[34:35], v[32:33]
	s_waitcnt vmcnt(3)
	v_lshlrev_b32_e32 v34, 16, v145
	v_cvt_pk_bf16_f32 v43, v32, v33
	v_lshlrev_b32_e32 v32, 16, v144
	v_and_b32_e32 v33, 0xffff0000, v144
	v_and_b32_e32 v35, 0xffff0000, v145
	v_pk_add_f32 v[32:33], v[36:37], v[32:33]
	v_pk_add_f32 v[34:35], v[38:39], v[34:35]
	v_cvt_pk_bf16_f32 v32, v32, v33
	v_cvt_pk_bf16_f32 v33, v34, v35
	v_lshlrev_b32_e32 v34, 16, v146
	v_and_b32_e32 v35, 0xffff0000, v146
	v_pk_add_f32 v[28:29], v[28:29], v[34:35]
	v_lshl_add_u64 v[44:45], s[88:89], 0, v[208:209]
	v_cvt_pk_bf16_f32 v34, v28, v29
	v_lshlrev_b32_e32 v28, 16, v147
	v_and_b32_e32 v29, 0xffff0000, v147
	v_pk_add_f32 v[28:29], v[30:31], v[28:29]
	s_waitcnt vmcnt(2)
	v_lshlrev_b32_e32 v30, 16, v140
	v_and_b32_e32 v31, 0xffff0000, v140
	v_pk_add_f32 v[24:25], v[24:25], v[30:31]
	v_lshlrev_b32_e32 v30, 16, v141
	v_and_b32_e32 v31, 0xffff0000, v141
	v_pk_add_f32 v[26:27], v[26:27], v[30:31]
	v_cvt_pk_bf16_f32 v24, v24, v25
	v_cvt_pk_bf16_f32 v25, v26, v27
	v_lshlrev_b32_e32 v26, 16, v142
	v_and_b32_e32 v27, 0xffff0000, v142
	v_pk_add_f32 v[16:17], v[16:17], v[26:27]
	v_cvt_pk_bf16_f32 v35, v28, v29
	v_cvt_pk_bf16_f32 v26, v16, v17
	v_lshlrev_b32_e32 v16, 16, v143
	v_and_b32_e32 v17, 0xffff0000, v143
	v_pk_add_f32 v[16:17], v[18:19], v[16:17]
	s_waitcnt vmcnt(1)
	v_lshlrev_b32_e32 v18, 16, v137
	v_cvt_pk_bf16_f32 v27, v16, v17
	v_lshlrev_b32_e32 v16, 16, v136
	v_and_b32_e32 v17, 0xffff0000, v136
	v_and_b32_e32 v19, 0xffff0000, v137
	v_pk_add_f32 v[16:17], v[20:21], v[16:17]
	v_pk_add_f32 v[18:19], v[22:23], v[18:19]
	v_cvt_pk_bf16_f32 v16, v16, v17
	v_cvt_pk_bf16_f32 v17, v18, v19
	v_lshlrev_b32_e32 v18, 16, v138
	v_and_b32_e32 v19, 0xffff0000, v138
	v_pk_add_f32 v[12:13], v[12:13], v[18:19]
	v_lshl_add_u64 v[28:29], s[88:89], 0, v[206:207]
	v_cvt_pk_bf16_f32 v18, v12, v13
	v_lshlrev_b32_e32 v12, 16, v139
	v_and_b32_e32 v13, 0xffff0000, v139
	v_pk_add_f32 v[12:13], v[14:15], v[12:13]
	s_waitcnt vmcnt(0)
; __device__ __forceinline__ unsigned cvt_pk_bf16(float lo, float hi) { const f32x2 v = {lo, hi}; const bf16v2_ r = __builtin_convertvector(v, bf16v2_); return __builtin_bit_cast(unsigned, r); }
; __device__ __forceinline__ float bflo(unsigned w) { return __uint_as_float(w << 16); }
; __device__ __forceinline__ float bfhi(unsigned w) { return __uint_as_float(w & 0xffff0000u); }
; __device__ __forceinline__ float wave_sum(float v) { v = row16_sum(v); v += shx(v, 16); v += shx(v, 32); return v; }
;     __device__ __forceinline__ void operator()(const f32x4 (&acc)[2][2][4][2], const Unit& u, int wr, int wc, int, int) const {
;     ...
; #pragma unroll
;         for (int ai = 0; ai < 2; ++ai)
; #pragma unroll
;             for (int m = 0; m < 4; ++m)
; #pragma unroll
;                 for (int bj = 0; bj < 2; ++bj) { const u32x4 c = cin[ai][m][bj]; const f32x4 v0 = acc[ai][bj][m][0], v1 = acc[ai][bj][m][1];
;                     u32x4 w; w.x = cvt_pk_bf16(bflo(c.x) + v0[0], bfhi(c.x) + v0[1]); w.y = cvt_pk_bf16(bflo(c.y) + v0[2], bfhi(c.y) + v0[3]);
;                     w.z = cvt_pk_bf16(bflo(c.z) + v1[0], bfhi(c.z) + v1[1]); w.w = cvt_pk_bf16(bflo(c.w) + v1[2], bfhi(c.w) + v1[3]);
;                     *(u32x4*)(C + (size_t)(row0 + ai * HALF + m * 16) * ldc + col0 + bj * HALF) = w; }
; __device__ __forceinline__ void rowstat_phase(const Frame& F, const bf16_t* __restrict__ res, float* __restrict__ rstd_out) {
;     ...
;         for (int r = 0; r < 4; ++r) { ss[r] = 0.f;
; #pragma unroll
;             for (int i = 0; i < 4; ++i) { const u32x4 x = v[r][i];
;                 ss[r] += bflo(x.x) * bflo(x.x) + bfhi(x.x) * bfhi(x.x) + bflo(x.y) * bflo(x.y) + bfhi(x.y) * bfhi(x.y) + bflo(x.z) * bflo(x.z) + bfhi(x.z) * bfhi(x.z) + bflo(x.w) * bflo(x.w) + bfhi(x.w) * bfhi(x.w); }
;             ss[r] = wave_sum(ss[r]); }
	v_lshlrev_b32_e32 v14, 16, v132
	v_and_b32_e32 v15, 0xffff0000, v132
	v_pk_add_f32 v[8:9], v[8:9], v[14:15]
	v_lshlrev_b32_e32 v14, 16, v133
	v_and_b32_e32 v15, 0xffff0000, v133
	v_pk_add_f32 v[10:11], v[10:11], v[14:15]
	v_cvt_pk_bf16_f32 v8, v8, v9
	v_cvt_pk_bf16_f32 v9, v10, v11
	v_lshlrev_b32_e32 v10, 16, v134
	v_and_b32_e32 v11, 0xffff0000, v134
	v_pk_add_f32 v[4:5], v[4:5], v[10:11]
	v_cvt_pk_bf16_f32 v19, v12, v13
	v_cvt_pk_bf16_f32 v10, v4, v5
	v_lshlrev_b32_e32 v4, 16, v135
	v_and_b32_e32 v5, 0xffff0000, v135
	v_lshl_add_u64 v[12:13], s[88:89], 0, v[204:205]
	v_pk_add_f32 v[4:5], v[6:7], v[4:5]
	v_lshl_add_u64 v[92:93], v[92:93], 0, v[202:203]
	v_lshl_add_u64 v[76:77], v[76:77], 0, v[202:203]
	v_lshl_add_u64 v[60:61], v[60:61], 0, v[202:203]
	v_lshl_add_u64 v[44:45], v[44:45], 0, v[202:203]
	v_lshl_add_u64 v[28:29], v[28:29], 0, v[202:203]
	v_lshl_add_u64 v[12:13], v[12:13], 0, v[202:203]
	v_cvt_pk_bf16_f32 v11, v4, v5
	global_store_dwordx4 v[124:125], v[128:131], off
	global_store_dwordx4 v[124:125], v[120:123], off offset:256
	global_store_dwordx4 v[108:109], v[112:115], off
	global_store_dwordx4 v[108:109], v[104:107], off offset:256
	global_store_dwordx4 v[92:93], v[96:99], off
	global_store_dwordx4 v[92:93], v[88:91], off offset:256
	global_store_dwordx4 v[76:77], v[80:83], off
	global_store_dwordx4 v[76:77], v[72:75], off offset:256
	global_store_dwordx4 v[60:61], v[64:67], off
	global_store_dwordx4 v[60:61], v[56:59], off offset:256
	global_store_dwordx4 v[44:45], v[48:51], off
	global_store_dwordx4 v[44:45], v[40:43], off offset:256
	global_store_dwordx4 v[28:29], v[32:35], off
	global_store_dwordx4 v[28:29], v[24:27], off offset:256
	global_store_dwordx4 v[12:13], v[16:19], off
	global_store_dwordx4 v[12:13], v[8:11], off offset:256
	v_subrev_u32_e32 v216, s88, v124
	v_bfe_u32 v217, v216, 4, 8
	v_lshrrev_b32_e32 v216, 12, v216
	v_and_b32_e32 v218, 15, v217
	v_lshrrev_b32_e32 v217, 5, v217
	v_lshl_or_b32 v217, v217, 4, v218
	v_lshlrev_b32_e32 v217, 17, v217
	v_and_b32_e32 v218, 15, v216
	v_and_b32_e32 v216, 0xffffffc0, v216
	v_lshl_or_b32 v216, v218, 2, v216
	v_lshl_add_u32 v216, v216, 2, v217
	v_add_u32_e32 v216, 0x1e000000, v216
	v_mov_b32_e32 v188, 0
	v_dot2c_f32_bf16_e32 v188, v128, v128
	v_dot2c_f32_bf16_e32 v188, v129, v129
	v_dot2c_f32_bf16_e32 v188, v130, v130
	v_dot2c_f32_bf16_e32 v188, v131, v131
	v_dot2c_f32_bf16_e32 v188, v120, v120
	v_dot2c_f32_bf16_e32 v188, v121, v121
	v_dot2c_f32_bf16_e32 v188, v122, v122
	v_dot2c_f32_bf16_e32 v188, v123, v123
	v_mov_b32_e32 v189, 0
	v_dot2c_f32_bf16_e32 v189, v112, v112
	v_dot2c_f32_bf16_e32 v189, v113, v113
	v_dot2c_f32_bf16_e32 v189, v114, v114
	v_dot2c_f32_bf16_e32 v189, v115, v115
	v_dot2c_f32_bf16_e32 v189, v104, v104
	v_dot2c_f32_bf16_e32 v189, v105, v105
	v_dot2c_f32_bf16_e32 v189, v106, v106
	v_dot2c_f32_bf16_e32 v189, v107, v107
	v_mov_b32_e32 v190, 0
	v_dot2c_f32_bf16_e32 v190, v96, v96
	v_dot2c_f32_bf16_e32 v190, v97, v97
	v_dot2c_f32_bf16_e32 v190, v98, v98
	v_dot2c_f32_bf16_e32 v190, v99, v99
	v_dot2c_f32_bf16_e32 v190, v88, v88
	v_dot2c_f32_bf16_e32 v190, v89, v89
	v_dot2c_f32_bf16_e32 v190, v90, v90
	v_dot2c_f32_bf16_e32 v190, v91, v91
	v_mov_b32_e32 v191, 0
	v_dot2c_f32_bf16_e32 v191, v80, v80
	v_dot2c_f32_bf16_e32 v191, v81, v81
	v_dot2c_f32_bf16_e32 v191, v82, v82
	v_dot2c_f32_bf16_e32 v191, v83, v83
	v_dot2c_f32_bf16_e32 v191, v72, v72
	v_dot2c_f32_bf16_e32 v191, v73, v73
	v_dot2c_f32_bf16_e32 v191, v74, v74
	v_dot2c_f32_bf16_e32 v191, v75, v75
	s_nop 2
	global_store_dwordx4 v216, v[188:191], s[88:89]
	s_nop 1
	v_mov_b32_e32 v188, 0
	v_dot2c_f32_bf16_e32 v188, v64, v64
	v_dot2c_f32_bf16_e32 v188, v65, v65
	v_dot2c_f32_bf16_e32 v188, v66, v66
	v_dot2c_f32_bf16_e32 v188, v67, v67
	v_dot2c_f32_bf16_e32 v188, v56, v56
	v_dot2c_f32_bf16_e32 v188, v57, v57
	v_dot2c_f32_bf16_e32 v188, v58, v58
	v_dot2c_f32_bf16_e32 v188, v59, v59
	v_mov_b32_e32 v189, 0
	v_dot2c_f32_bf16_e32 v189, v48, v48
	v_dot2c_f32_bf16_e32 v189, v49, v49
	v_dot2c_f32_bf16_e32 v189, v50, v50
	v_dot2c_f32_bf16_e32 v189, v51, v51
	v_dot2c_f32_bf16_e32 v189, v40, v40
	v_dot2c_f32_bf16_e32 v189, v41, v41
	v_dot2c_f32_bf16_e32 v189, v42, v42
	v_dot2c_f32_bf16_e32 v189, v43, v43
	v_mov_b32_e32 v190, 0
	v_dot2c_f32_bf16_e32 v190, v32, v32
	v_dot2c_f32_bf16_e32 v190, v33, v33
	v_dot2c_f32_bf16_e32 v190, v34, v34
	v_dot2c_f32_bf16_e32 v190, v35, v35
	v_dot2c_f32_bf16_e32 v190, v24, v24
	v_dot2c_f32_bf16_e32 v190, v25, v25
	v_dot2c_f32_bf16_e32 v190, v26, v26
	v_dot2c_f32_bf16_e32 v190, v27, v27
	v_mov_b32_e32 v191, 0
	v_dot2c_f32_bf16_e32 v191, v16, v16
	v_dot2c_f32_bf16_e32 v191, v17, v17
	v_dot2c_f32_bf16_e32 v191, v18, v18
	v_dot2c_f32_bf16_e32 v191, v19, v19
	v_dot2c_f32_bf16_e32 v191, v8, v8
	v_dot2c_f32_bf16_e32 v191, v9, v9
	v_dot2c_f32_bf16_e32 v191, v10, v10
	v_dot2c_f32_bf16_e32 v191, v11, v11
	s_nop 2
	global_store_dwordx4 v216, v[188:191], s[88:89] offset:512
	s_nop 1
	s_cbranch_vccz .LBB0_959
	s_waitcnt vmcnt(0)
	s_cmpk_gt_u32 s2, 0xff
	s_cbranch_scc1 .LBB0_970
	s_barrier

; __device__ __forceinline__ float bflo(unsigned w) { return __uint_as_float(w << 16); }
; __device__ __forceinline__ float bfhi(unsigned w) { return __uint_as_float(w & 0xffff0000u); }
; __device__ __forceinline__ float wave_sum(float v) { v = row16_sum(v); v += shx(v, 16); v += shx(v, 32); return v; }
; #define WAVE (__builtin_amdgcn_readfirstlane(opaque_tid() >> 6))
; __device__ __forceinline__ void rowstat_phase(const Frame& F, const bf16_t* __restrict__ res, float* __restrict__ rstd_out) {
;     for (int row0 = (F.bid * NWAVE + WAVE) * 4; row0 < M; row0 += F.G * NWAVE * 4) {
;         u32x4 v[4][4];
; #pragma unroll
;         for (int r = 0; r < 4; ++r)
; #pragma unroll
;             for (int i = 0; i < 4; ++i) v[r][i] = *(const u32x4*)(res + (size_t)(row0 + r) * D + LANE * 8 + i * 512);
;         float ss[4];
; #pragma unroll
;         for (int r = 0; r < 4; ++r) { ss[r] = 0.f;
; #pragma unroll
;             for (int i = 0; i < 4; ++i) { const u32x4 x = v[r][i];
;                 ss[r] += bflo(x.x) * bflo(x.x) + bfhi(x.x) * bfhi(x.x) + bflo(x.y) * bflo(x.y) + bfhi(x.y) * bfhi(x.y) + bflo(x.z) * bflo(x.z) + bfhi(x.z) * bfhi(x.z) + bflo(x.w) * bflo(x.w) + bfhi(x.w) * bfhi(x.w); }
;             ss[r] = wave_sum(ss[r]); }
;         if (LANE < 4) rstd_out[row0 + LANE] = rsqrtf((LANE == 0 ? ss[0] : LANE == 1 ? ss[1] : LANE == 2 ? ss[2] : ss[3]) * (1.f / D) + EPS);
;     }
.Lrsp_loop_a:
	s_cmp_lt_i32 s4, 0x8000
	s_cbranch_scc0 .Lrsp_done_a
	v_and_b32_e32 v1, 0x7f, v0
	v_lshrrev_b32_e32 v2, 7, v0
	v_add_u32_e32 v1, s4, v1
	v_lshlrev_b32_e32 v4, 22, v2
	v_and_b32_e32 v7, 15, v1
	v_bfe_u32 v8, v1, 4, 2
	v_lshl_or_b32 v7, v7, 2, v8
	v_and_b32_e32 v8, 0xffffffc0, v1
	v_or_b32_e32 v7, v7, v8
	v_lshl_add_u32 v4, v7, 2, v4
	v_add_u32_e32 v4, 0x1e000000, v4
	s_mov_b32 s6, s88
	s_mov_b32 s7, s89
	global_load_dword v10, v4, s[6:7]
	s_add_u32 s6, s6, 0x20000
	s_addc_u32 s7, s7, 0
	global_load_dword v11, v4, s[6:7]
	s_add_u32 s6, s6, 0x20000
	s_addc_u32 s7, s7, 0
	global_load_dword v12, v4, s[6:7]
	s_add_u32 s6, s6, 0x20000
	s_addc_u32 s7, s7, 0
	global_load_dword v13, v4, s[6:7]
	s_add_u32 s6, s6, 0x20000
	s_addc_u32 s7, s7, 0
	global_load_dword v14, v4, s[6:7]
	s_add_u32 s6, s6, 0x20000
	s_addc_u32 s7, s7, 0
	global_load_dword v15, v4, s[6:7]
	s_add_u32 s6, s6, 0x20000
	s_addc_u32 s7, s7, 0
	global_load_dword v16, v4, s[6:7]
	s_add_u32 s6, s6, 0x20000
	s_addc_u32 s7, s7, 0
	global_load_dword v17, v4, s[6:7]
	s_add_u32 s6, s6, 0x20000
	s_addc_u32 s7, s7, 0
	global_load_dword v18, v4, s[6:7]
	s_add_u32 s6, s6, 0x20000
	s_addc_u32 s7, s7, 0
	global_load_dword v19, v4, s[6:7]
	s_add_u32 s6, s6, 0x20000
	s_addc_u32 s7, s7, 0
	global_load_dword v20, v4, s[6:7]
	s_add_u32 s6, s6, 0x20000
	s_addc_u32 s7, s7, 0
	global_load_dword v21, v4, s[6:7]
	s_add_u32 s6, s6, 0x20000
	s_addc_u32 s7, s7, 0
	global_load_dword v22, v4, s[6:7]
	s_add_u32 s6, s6, 0x20000
	s_addc_u32 s7, s7, 0
	global_load_dword v23, v4, s[6:7]
	s_add_u32 s6, s6, 0x20000
	s_addc_u32 s7, s7, 0
	global_load_dword v24, v4, s[6:7]
	s_add_u32 s6, s6, 0x20000
	s_addc_u32 s7, s7, 0
	global_load_dword v25, v4, s[6:7]
	s_add_u32 s6, s6, 0x20000
	s_addc_u32 s7, s7, 0
	global_load_dword v26, v4, s[6:7]
	s_add_u32 s6, s6, 0x20000
	s_addc_u32 s7, s7, 0
	global_load_dword v27, v4, s[6:7]
	s_add_u32 s6, s6, 0x20000
	s_addc_u32 s7, s7, 0
	global_load_dword v28, v4, s[6:7]
	s_add_u32 s6, s6, 0x20000
	s_addc_u32 s7, s7, 0
	global_load_dword v29, v4, s[6:7]
	s_add_u32 s6, s6, 0x20000
	s_addc_u32 s7, s7, 0
	global_load_dword v30, v4, s[6:7]
	s_add_u32 s6, s6, 0x20000
	s_addc_u32 s7, s7, 0
	global_load_dword v31, v4, s[6:7]
	s_add_u32 s6, s6, 0x20000
	s_addc_u32 s7, s7, 0
	global_load_dword v32, v4, s[6:7]
	s_add_u32 s6, s6, 0x20000
	s_addc_u32 s7, s7, 0
	global_load_dword v33, v4, s[6:7]
	s_add_u32 s6, s6, 0x20000
	s_addc_u32 s7, s7, 0
	global_load_dword v34, v4, s[6:7]
	s_add_u32 s6, s6, 0x20000
	s_addc_u32 s7, s7, 0
	global_load_dword v35, v4, s[6:7]
	s_add_u32 s6, s6, 0x20000
	s_addc_u32 s7, s7, 0
	global_load_dword v36, v4, s[6:7]
	s_add_u32 s6, s6, 0x20000
	s_addc_u32 s7, s7, 0
	global_load_dword v37, v4, s[6:7]
	s_add_u32 s6, s6, 0x20000
	s_addc_u32 s7, s7, 0
	global_load_dword v38, v4, s[6:7]
	s_add_u32 s6, s6, 0x20000
	s_addc_u32 s7, s7, 0
	global_load_dword v39, v4, s[6:7]
	s_add_u32 s6, s6, 0x20000
	s_addc_u32 s7, s7, 0
	global_load_dword v40, v4, s[6:7]
	s_add_u32 s6, s6, 0x20000
	s_addc_u32 s7, s7, 0
	global_load_dword v41, v4, s[6:7]
	s_waitcnt vmcnt(0)
	v_add_f32_e32 v10, v10, v11
	v_add_f32_e32 v12, v12, v13
	v_add_f32_e32 v14, v14, v15
	v_add_f32_e32 v16, v16, v17
	v_add_f32_e32 v18, v18, v19
	v_add_f32_e32 v20, v20, v21
	v_add_f32_e32 v22, v22, v23
	v_add_f32_e32 v24, v24, v25
	v_add_f32_e32 v26, v26, v27
	v_add_f32_e32 v28, v28, v29
	v_add_f32_e32 v30, v30, v31
	v_add_f32_e32 v32, v32, v33
	v_add_f32_e32 v34, v34, v35
	v_add_f32_e32 v36, v36, v37
	v_add_f32_e32 v38, v38, v39
	v_add_f32_e32 v40, v40, v41
	v_add_f32_e32 v10, v10, v12
	v_add_f32_e32 v14, v14, v16
	v_add_f32_e32 v18, v18, v20
	v_add_f32_e32 v22, v22, v24
	v_add_f32_e32 v26, v26, v28
	v_add_f32_e32 v30, v30, v32
	v_add_f32_e32 v34, v34, v36
	v_add_f32_e32 v38, v38, v40
	v_add_f32_e32 v10, v10, v14
	v_add_f32_e32 v18, v18, v22
	v_add_f32_e32 v26, v26, v30
	v_add_f32_e32 v34, v34, v38
	v_add_f32_e32 v10, v10, v18
	v_add_f32_e32 v26, v26, v34
	v_add_f32_e32 v10, v10, v26
	v_lshlrev_b32_e32 v5, 2, v0
	ds_write_b32 v5, v10
	s_waitcnt lgkmcnt(0)
	s_barrier
	v_cmp_gt_u32_e32 vcc, 0x80, v0
	s_and_saveexec_b64 s[14:15], vcc
	s_cbranch_execz .Lrsp_skip_a
	ds_read_b32 v11, v5
	ds_read_b32 v12, v5 offset:512
	ds_read_b32 v13, v5 offset:1024
	ds_read_b32 v14, v5 offset:1536
	v_readlane_b32 s18, v252, 14
	v_readlane_b32 s19, v252, 15
	v_mov_b32_e32 v15, 0x358637bd
	v_lshlrev_b32_e32 v6, 2, v1
	s_waitcnt lgkmcnt(0)
	v_add_f32_e32 v11, v11, v12
	v_add_f32_e32 v13, v13, v14
	v_add_f32_e32 v11, v11, v13
	v_fmamk_f32 v11, v11, 0x3a000000, v15
	v_rsq_f32_e32 v11, v11
	s_nop 1
	global_store_dword v6, v11, s[18:19]

; #define PG8_STAGE(bufoff, gbase, voff) do { _Pragma("unroll") for (int _i = 0; _i < 2; ++_i) \
;         __builtin_amdgcn_global_load_lds((const unsigned*)((const char*)(gbase) + (voff)[_i]), (LAS unsigned*)(lds + (bufoff) + ldsw + _i * 8192), 16, 0, 0); } while (0)
; #define PG8_LDA(dst, b, h) do { _Pragma("unroll") for (int m = 0; m < 4; ++m) _Pragma("unroll") for (int k = 0; k < 2; ++k) dst[m][k] = *(const LAS bf16x8*)(lds + PG8_SA(b, h) + aoff + m * 2048 + k * 1024); } while (0)
; #define PG8_LDB(dst, b, h) do { _Pragma("unroll") for (int n = 0; n < 2; ++n) _Pragma("unroll") for (int k = 0; k < 2; ++k) dst[n][k] = *(const LAS bf16x8*)(lds + PG8_SB(b, h) + boff + n * 2048 + k * 1024); } while (0)
; #define PG8_MMA(ai, bj, At, Bt) do { __builtin_amdgcn_s_setprio(1); _Pragma("unroll") for (int m = 0; m < 4; ++m) _Pragma("unroll") for (int n = 0; n < 2; ++n) _Pragma("unroll") for (int k = 0; k < 2; ++k) \
;         acc[ai][bj][m][n] = __builtin_amdgcn_mfma_f32_16x16x32_bf16(Bt[n][k], At[m][k], acc[ai][bj][m][n], 0, 0, 0); __builtin_amdgcn_s_setprio(0); } while (0)
; #define PG8_WAIT_V(n) asm volatile("s_waitcnt vmcnt(" #n ")" ::: "memory")
; #define PG8_WAIT_L(n) asm volatile("s_waitcnt lgkmcnt(" #n ")" ::: "memory")
; #define PG8_BAR __builtin_amdgcn_s_barrier()
; #define PG8_SCHED __builtin_amdgcn_sched_barrier(0)
; template <class Epi, class Sched>
; __device__ __forceinline__ void gemm_phase(LAS unsigned char* lds, const Gemm g, const Sched& S, const Epi& E) {
;     ...
;             PG8_LDB(B0, 0, 0); PG8_SCHED; PG8_LDA(At, 0, 0); PG8_STAGE(PG8_SA(1, 1), a1 + hstepA, voffA);
;             PG8_WAIT_L(8); PG8_BAR; PG8_WAIT_L(0); PG8_MMA(0, 0, At, B0); PG8_BAR; PG8_SCHED;
;             PG8_LDB(B1, 0, 1); PG8_STAGE(PG8_SB(0, 0), b2, voffB);
;             PG8_BAR; PG8_WAIT_L(0); PG8_MMA(0, 1, At, B1); PG8_BAR;
;             PG8_LDA(At, 0, 1); PG8_STAGE(PG8_SA(0, 0), a2, voffA);
;             PG8_BAR; PG8_WAIT_L(0); PG8_MMA(1, 0, At, B0); PG8_BAR; PG8_SCHED;
;             PG8_STAGE(PG8_SB(0, 1), b2 + hstepB, voffB);
;             PG8_WAIT_V(6); PG8_BAR; PG8_MMA(1, 1, At, B1); PG8_BAR;
.LBB0_1396:
	s_setprio 0
	s_add_u32 s20, s6, 0xfff80080
	s_addc_u32 s21, s7, -1
	s_add_i32 s52, 0, 0x10000
	v_add_u32_e32 v144, s52, v1
	ds_read_b128 v[132:135], v144
	ds_read_b128 v[136:139], v144 offset:1024
	ds_read_b128 v[140:143], v144 offset:2048
	ds_read_b128 v[144:147], v144 offset:3072
	s_cmp_eq_u32 s51, 28
	s_cselect_b32 s25, s15, s21
	s_cselect_b32 s24, s47, s20
	s_cselect_b32 s21, s1, s50
	s_cselect_b32 s20, s48, s49
	ds_read_b128 v[148:151], v224
	ds_read_b128 v[152:155], v224 offset:1024
	ds_read_b128 v[156:159], v224 offset:2048
	ds_read_b128 v[160:163], v224 offset:3072
	ds_read_b128 v[164:167], v224 offset:4096
	ds_read_b128 v[168:171], v224 offset:5120
	ds_read_b128 v[172:175], v224 offset:6144
	ds_read_b128 v[176:179], v224 offset:7168
	s_add_i32 s54, 0, 0x14000
	v_add_u32_e32 v202, s54, v1
	ds_read_b128 v[180:183], v202
	ds_read_b128 v[184:187], v202 offset:1024
	ds_read_b128 v[188:191], v202 offset:2048
	ds_read_b128 v[202:205], v202 offset:3072
	s_add_i32 m0, s31, 0xc000
	s_nop 0
	global_load_lds_dwordx4 v198, s[6:7]
	s_add_i32 m0, s31, 0xe000
	s_nop 0
	global_load_lds_dwordx4 v200, s[6:7]
	s_waitcnt lgkmcnt(0)
	s_setprio 1
	s_barrier
	v_mfma_f32_16x16x32_bf16 v[128:131], v[132:135], v[148:151], v[128:131]
	v_mfma_f32_16x16x32_bf16 v[124:127], v[140:143], v[148:151], v[124:127]
	v_mfma_f32_16x16x32_bf16 v[112:115], v[132:135], v[156:159], v[112:115]
	v_mfma_f32_16x16x32_bf16 v[108:111], v[140:143], v[156:159], v[108:111]
	v_mfma_f32_16x16x32_bf16 v[100:103], v[132:135], v[164:167], v[100:103]
	v_mfma_f32_16x16x32_bf16 v[92:95], v[140:143], v[164:167], v[92:95]
	v_mfma_f32_16x16x32_bf16 v[84:87], v[132:135], v[172:175], v[84:87]
	v_mfma_f32_16x16x32_bf16 v[76:79], v[140:143], v[172:175], v[76:79]
	v_mfma_f32_16x16x32_bf16 v[128:131], v[136:139], v[152:155], v[128:131]
	v_mfma_f32_16x16x32_bf16 v[124:127], v[144:147], v[152:155], v[124:127]
	v_mfma_f32_16x16x32_bf16 v[112:115], v[136:139], v[160:163], v[112:115]
	v_mfma_f32_16x16x32_bf16 v[108:111], v[144:147], v[160:163], v[108:111]
	v_mfma_f32_16x16x32_bf16 v[100:103], v[136:139], v[168:171], v[100:103]
	v_mfma_f32_16x16x32_bf16 v[92:95], v[144:147], v[168:171], v[92:95]
	v_mfma_f32_16x16x32_bf16 v[84:87], v[136:139], v[176:179], v[84:87]
	v_mfma_f32_16x16x32_bf16 v[76:79], v[144:147], v[176:179], v[76:79]
	v_mfma_f32_16x16x32_bf16 v[120:123], v[180:183], v[148:151], v[120:123]
	v_mfma_f32_16x16x32_bf16 v[116:119], v[188:191], v[148:151], v[116:119]
	v_mfma_f32_16x16x32_bf16 v[104:107], v[180:183], v[156:159], v[104:107]
	v_mfma_f32_16x16x32_bf16 v[96:99], v[188:191], v[156:159], v[96:99]
	v_mfma_f32_16x16x32_bf16 v[88:91], v[180:183], v[164:167], v[88:91]
	v_mfma_f32_16x16x32_bf16 v[80:83], v[188:191], v[164:167], v[80:83]
	v_mfma_f32_16x16x32_bf16 v[72:75], v[180:183], v[172:175], v[72:75]
	v_mfma_f32_16x16x32_bf16 v[68:71], v[188:191], v[172:175], v[68:71]
	v_mfma_f32_16x16x32_bf16 v[120:123], v[184:187], v[152:155], v[120:123]
	v_mfma_f32_16x16x32_bf16 v[116:119], v[202:205], v[152:155], v[116:119]
	v_mfma_f32_16x16x32_bf16 v[104:107], v[184:187], v[160:163], v[104:107]
	v_mfma_f32_16x16x32_bf16 v[96:99], v[202:205], v[160:163], v[96:99]
	v_mfma_f32_16x16x32_bf16 v[88:91], v[184:187], v[168:171], v[88:91]
	v_mfma_f32_16x16x32_bf16 v[80:83], v[202:205], v[168:171], v[80:83]
	v_mfma_f32_16x16x32_bf16 v[72:75], v[184:187], v[176:179], v[72:75]
	v_mfma_f32_16x16x32_bf16 v[68:71], v[202:205], v[176:179], v[68:71]
	s_barrier
	s_setprio 0
	ds_read_b128 v[148:151], v224 offset:16384
	ds_read_b128 v[152:155], v224 offset:17408
	ds_read_b128 v[156:159], v224 offset:18432
	ds_read_b128 v[160:163], v224 offset:19456
	ds_read_b128 v[164:167], v224 offset:20480
	ds_read_b128 v[168:171], v224 offset:21504
	ds_read_b128 v[172:175], v224 offset:22528
	ds_read_b128 v[176:179], v224 offset:23552
	s_add_i32 s52, s52, s30
	v_lshl_add_u64 v[206:207], s[20:21], 0, v[2:3]
	s_mov_b32 m0, s52
	s_nop 0
	global_load_lds_dwordx4 v[206:207], off
	v_lshl_add_u64 v[208:209], s[20:21], 0, v[192:193]
	s_add_i32 m0, s52, 0x2000
	s_nop 0
	global_load_lds_dwordx4 v[208:209], off
	s_mov_b32 m0, s31
	v_lshl_add_u64 v[210:211], s[24:25], 0, v[196:197]
	global_load_lds_dwordx4 v[210:211], off
	v_lshl_add_u64 v[212:213], s[24:25], 0, v[194:195]
	s_mov_b32 m0, s35
	s_nop 0
	global_load_lds_dwordx4 v[212:213], off
	s_add_u32 s52, s20, 0x80000
	s_addc_u32 s53, s21, 0
	s_add_i32 s54, s54, s30
	s_mov_b32 m0, s54
	s_nop 0
	global_load_lds_dwordx4 v2, s[52:53]
	s_add_i32 m0, s54, 0x2000
	s_nop 0
	global_load_lds_dwordx4 v192, s[52:53]
	s_waitcnt lgkmcnt(0)
	s_waitcnt vmcnt(6)
	s_setprio 1
	s_barrier
; #define PG8_STAGE(bufoff, gbase, voff) do { _Pragma("unroll") for (int _i = 0; _i < 2; ++_i) \
;         __builtin_amdgcn_global_load_lds((const unsigned*)((const char*)(gbase) + (voff)[_i]), (LAS unsigned*)(lds + (bufoff) + ldsw + _i * 8192), 16, 0, 0); } while (0)
; #define PG8_LDA(dst, b, h) do { _Pragma("unroll") for (int m = 0; m < 4; ++m) _Pragma("unroll") for (int k = 0; k < 2; ++k) dst[m][k] = *(const LAS bf16x8*)(lds + PG8_SA(b, h) + aoff + m * 2048 + k * 1024); } while (0)
; #define PG8_LDB(dst, b, h) do { _Pragma("unroll") for (int n = 0; n < 2; ++n) _Pragma("unroll") for (int k = 0; k < 2; ++k) dst[n][k] = *(const LAS bf16x8*)(lds + PG8_SB(b, h) + boff + n * 2048 + k * 1024); } while (0)
; #define PG8_MMA(ai, bj, At, Bt) do { __builtin_amdgcn_s_setprio(1); _Pragma("unroll") for (int m = 0; m < 4; ++m) _Pragma("unroll") for (int n = 0; n < 2; ++n) _Pragma("unroll") for (int k = 0; k < 2; ++k) \
;         acc[ai][bj][m][n] = __builtin_amdgcn_mfma_f32_16x16x32_bf16(Bt[n][k], At[m][k], acc[ai][bj][m][n], 0, 0, 0); __builtin_amdgcn_s_setprio(0); } while (0)
; #define PG8_WAIT_V(n) asm volatile("s_waitcnt vmcnt(" #n ")" ::: "memory")
; #define PG8_WAIT_L(n) asm volatile("s_waitcnt lgkmcnt(" #n ")" ::: "memory")
; #define PG8_BAR __builtin_amdgcn_s_barrier()
; #define PG8_SCHED __builtin_amdgcn_sched_barrier(0)
; template <class Epi, class Sched>
; __device__ __forceinline__ void gemm_phase(LAS unsigned char* lds, const Gemm g, const Sched& S, const Epi& E) {
;     ...
;             PG8_BAR; PG8_WAIT_L(0); PG8_MMA(1, 0, At, B0); PG8_BAR; PG8_SCHED;
;             PG8_STAGE(PG8_SB(0, 1), b2 + hstepB, voffB);
;             PG8_WAIT_V(6); PG8_BAR; PG8_MMA(1, 1, At, B1); PG8_BAR;
;             PG8_LDB(B0, 1, 0); PG8_SCHED; PG8_LDA(At, 1, 0); PG8_STAGE(PG8_SA(0, 1), a2 + hstepA, voffA);
;             PG8_WAIT_L(8); PG8_BAR; PG8_WAIT_L(0); PG8_MMA(0, 0, At, B0); PG8_BAR; PG8_SCHED;
;             PG8_LDB(B1, 1, 1); PG8_STAGE(PG8_SB(1, 0), b3, voffB);
;             PG8_BAR; PG8_WAIT_L(0); PG8_MMA(0, 1, At, B1); PG8_BAR;
;             PG8_LDA(At, 1, 1); PG8_STAGE(PG8_SA(1, 0), a3, voffA);
;             PG8_BAR; PG8_WAIT_L(0); PG8_MMA(1, 0, At, B0); PG8_BAR; PG8_SCHED;
	v_mfma_f32_16x16x32_bf16 v[64:67], v[132:135], v[148:151], v[64:67]
	v_mfma_f32_16x16x32_bf16 v[60:63], v[140:143], v[148:151], v[60:63]
	v_mfma_f32_16x16x32_bf16 v[52:55], v[132:135], v[156:159], v[52:55]
	v_mfma_f32_16x16x32_bf16 v[44:47], v[140:143], v[156:159], v[44:47]
	v_mfma_f32_16x16x32_bf16 v[36:39], v[132:135], v[164:167], v[36:39]
	v_mfma_f32_16x16x32_bf16 v[28:31], v[140:143], v[164:167], v[28:31]
	v_mfma_f32_16x16x32_bf16 v[20:23], v[132:135], v[172:175], v[20:23]
	v_mfma_f32_16x16x32_bf16 v[12:15], v[140:143], v[172:175], v[12:15]
	v_mfma_f32_16x16x32_bf16 v[64:67], v[136:139], v[152:155], v[64:67]
	v_mfma_f32_16x16x32_bf16 v[60:63], v[144:147], v[152:155], v[60:63]
	v_mfma_f32_16x16x32_bf16 v[52:55], v[136:139], v[160:163], v[52:55]
	v_mfma_f32_16x16x32_bf16 v[44:47], v[144:147], v[160:163], v[44:47]
	v_mfma_f32_16x16x32_bf16 v[36:39], v[136:139], v[168:171], v[36:39]
	v_mfma_f32_16x16x32_bf16 v[28:31], v[144:147], v[168:171], v[28:31]
	v_mfma_f32_16x16x32_bf16 v[20:23], v[136:139], v[176:179], v[20:23]
	v_mfma_f32_16x16x32_bf16 v[12:15], v[144:147], v[176:179], v[12:15]
	v_mfma_f32_16x16x32_bf16 v[56:59], v[180:183], v[148:151], v[56:59]
	v_mfma_f32_16x16x32_bf16 v[48:51], v[188:191], v[148:151], v[48:51]
	v_mfma_f32_16x16x32_bf16 v[40:43], v[180:183], v[156:159], v[40:43]
	v_mfma_f32_16x16x32_bf16 v[32:35], v[188:191], v[156:159], v[32:35]
	v_mfma_f32_16x16x32_bf16 v[24:27], v[180:183], v[164:167], v[24:27]
	v_mfma_f32_16x16x32_bf16 v[16:19], v[188:191], v[164:167], v[16:19]
	v_mfma_f32_16x16x32_bf16 v[8:11], v[180:183], v[172:175], v[8:11]
	v_mfma_f32_16x16x32_bf16 v[4:7], v[188:191], v[172:175], v[4:7]
	v_mfma_f32_16x16x32_bf16 v[56:59], v[184:187], v[152:155], v[56:59]
	v_mfma_f32_16x16x32_bf16 v[48:51], v[202:205], v[152:155], v[48:51]
	v_mfma_f32_16x16x32_bf16 v[40:43], v[184:187], v[160:163], v[40:43]
	v_mfma_f32_16x16x32_bf16 v[32:35], v[202:205], v[160:163], v[32:35]
	v_mfma_f32_16x16x32_bf16 v[24:27], v[184:187], v[168:171], v[24:27]
	v_mfma_f32_16x16x32_bf16 v[16:19], v[202:205], v[168:171], v[16:19]
	v_mfma_f32_16x16x32_bf16 v[8:11], v[184:187], v[176:179], v[8:11]
	v_mfma_f32_16x16x32_bf16 v[4:7], v[202:205], v[176:179], v[4:7]
	s_barrier
	s_setprio 0
	s_add_i32 s52, 0, 0x18000
	v_add_u32_e32 v144, s52, v1
	ds_read_b128 v[132:135], v144
	ds_read_b128 v[136:139], v144 offset:1024
	ds_read_b128 v[140:143], v144 offset:2048
	ds_read_b128 v[144:147], v144 offset:3072
	s_add_u32 s24, s24, 0x80000
	s_addc_u32 s25, s25, 0
	ds_read_b128 v[148:151], v224 offset:32768
	ds_read_b128 v[152:155], v224 offset:33792
	ds_read_b128 v[156:159], v224 offset:34816
	ds_read_b128 v[160:163], v224 offset:35840
	ds_read_b128 v[164:167], v224 offset:36864
	ds_read_b128 v[168:171], v224 offset:37888
	ds_read_b128 v[172:175], v224 offset:38912
	ds_read_b128 v[176:179], v224 offset:39936
	s_mov_b32 m0, s36
	s_nop 0
	global_load_lds_dwordx4 v196, s[24:25]
	s_mov_b32 m0, s37
	s_nop 0
	global_load_lds_dwordx4 v194, s[24:25]
	s_add_i32 s24, 0, 0x1c000
	v_add_u32_e32 v202, s24, v1
	ds_read_b128 v[180:183], v202
	ds_read_b128 v[184:187], v202 offset:1024
	ds_read_b128 v[188:191], v202 offset:2048
	ds_read_b128 v[202:205], v202 offset:3072
	s_waitcnt lgkmcnt(0)
	s_setprio 1
	s_barrier
	v_mfma_f32_16x16x32_bf16 v[128:131], v[132:135], v[148:151], v[128:131]
	v_mfma_f32_16x16x32_bf16 v[124:127], v[140:143], v[148:151], v[124:127]
	v_mfma_f32_16x16x32_bf16 v[112:115], v[132:135], v[156:159], v[112:115]
	v_mfma_f32_16x16x32_bf16 v[108:111], v[140:143], v[156:159], v[108:111]
	v_mfma_f32_16x16x32_bf16 v[100:103], v[132:135], v[164:167], v[100:103]
	v_mfma_f32_16x16x32_bf16 v[92:95], v[140:143], v[164:167], v[92:95]
	v_mfma_f32_16x16x32_bf16 v[84:87], v[132:135], v[172:175], v[84:87]
	v_mfma_f32_16x16x32_bf16 v[76:79], v[140:143], v[172:175], v[76:79]
	v_mfma_f32_16x16x32_bf16 v[128:131], v[136:139], v[152:155], v[128:131]
	v_mfma_f32_16x16x32_bf16 v[124:127], v[144:147], v[152:155], v[124:127]
	v_mfma_f32_16x16x32_bf16 v[112:115], v[136:139], v[160:163], v[112:115]
	v_mfma_f32_16x16x32_bf16 v[108:111], v[144:147], v[160:163], v[108:111]
	v_mfma_f32_16x16x32_bf16 v[100:103], v[136:139], v[168:171], v[100:103]
	v_mfma_f32_16x16x32_bf16 v[92:95], v[144:147], v[168:171], v[92:95]
	v_mfma_f32_16x16x32_bf16 v[84:87], v[136:139], v[176:179], v[84:87]
	v_mfma_f32_16x16x32_bf16 v[76:79], v[144:147], v[176:179], v[76:79]
	v_mfma_f32_16x16x32_bf16 v[120:123], v[180:183], v[148:151], v[120:123]
	v_mfma_f32_16x16x32_bf16 v[116:119], v[188:191], v[148:151], v[116:119]
	v_mfma_f32_16x16x32_bf16 v[104:107], v[180:183], v[156:159], v[104:107]
	v_mfma_f32_16x16x32_bf16 v[96:99], v[188:191], v[156:159], v[96:99]
	v_mfma_f32_16x16x32_bf16 v[88:91], v[180:183], v[164:167], v[88:91]
	v_mfma_f32_16x16x32_bf16 v[80:83], v[188:191], v[164:167], v[80:83]
	v_mfma_f32_16x16x32_bf16 v[72:75], v[180:183], v[172:175], v[72:75]
	v_mfma_f32_16x16x32_bf16 v[68:71], v[188:191], v[172:175], v[68:71]
	v_mfma_f32_16x16x32_bf16 v[120:123], v[184:187], v[152:155], v[120:123]
	v_mfma_f32_16x16x32_bf16 v[116:119], v[202:205], v[152:155], v[116:119]
	v_mfma_f32_16x16x32_bf16 v[104:107], v[184:187], v[160:163], v[104:107]
	v_mfma_f32_16x16x32_bf16 v[96:99], v[202:205], v[160:163], v[96:99]
	v_mfma_f32_16x16x32_bf16 v[88:91], v[184:187], v[168:171], v[88:91]
	v_mfma_f32_16x16x32_bf16 v[80:83], v[202:205], v[168:171], v[80:83]
	v_mfma_f32_16x16x32_bf16 v[72:75], v[184:187], v[176:179], v[72:75]
	v_mfma_f32_16x16x32_bf16 v[68:71], v[202:205], v[176:179], v[68:71]
	s_barrier
; __device__ __forceinline__ int opaque_tid() { int t = threadIdx.x; asm volatile("" : "+v"(t)); return t; }
; #define PG8_STAGE(bufoff, gbase, voff) do { _Pragma("unroll") for (int _i = 0; _i < 2; ++_i) \
;         __builtin_amdgcn_global_load_lds((const unsigned*)((const char*)(gbase) + (voff)[_i]), (LAS unsigned*)(lds + (bufoff) + ldsw + _i * 8192), 16, 0, 0); } while (0)
; #define PG8_LDA(dst, b, h) do { _Pragma("unroll") for (int m = 0; m < 4; ++m) _Pragma("unroll") for (int k = 0; k < 2; ++k) dst[m][k] = *(const LAS bf16x8*)(lds + PG8_SA(b, h) + aoff + m * 2048 + k * 1024); } while (0)
; #define PG8_MMA(ai, bj, At, Bt) do { __builtin_amdgcn_s_setprio(1); _Pragma("unroll") for (int m = 0; m < 4; ++m) _Pragma("unroll") for (int n = 0; n < 2; ++n) _Pragma("unroll") for (int k = 0; k < 2; ++k) \
;         acc[ai][bj][m][n] = __builtin_amdgcn_mfma_f32_16x16x32_bf16(Bt[n][k], At[m][k], acc[ai][bj][m][n], 0, 0, 0); __builtin_amdgcn_s_setprio(0); } while (0)
; #define PG8_WAIT_V(n) asm volatile("s_waitcnt vmcnt(" #n ")" ::: "memory")
; #define PG8_WAIT_L(n) asm volatile("s_waitcnt lgkmcnt(" #n ")" ::: "memory")
; #define PG8_BAR __builtin_amdgcn_s_barrier()
; #define PG8_SCHED __builtin_amdgcn_sched_barrier(0)
;     __device__ __forceinline__ void operator()(const f32x4 (&acc)[2][2][4][2], const Unit& u, int wr, int wc, int, int) const {
;         const int ol_ = opaque_tid() & 63, fr = ol_ & 15, fq = ol_ >> 4;
;         const int row0 = u.pm * BM + wr * 64 + fr, col0 = u.pn * BM + wc * 32 + 8 * fq;
;         u32x4 cin[2][4][2];
; #pragma unroll
;         for (int ai = 0; ai < 2; ++ai)
; #pragma unroll
;             for (int m = 0; m < 4; ++m)
; #pragma unroll
;                 for (int bj = 0; bj < 2; ++bj) cin[ai][m][bj] = *(const u32x4*)(C + (size_t)(row0 + ai * HALF + m * 16) * ldc + col0 + bj * HALF);
; template <class Epi, class Sched>
; __device__ __forceinline__ void gemm_phase(LAS unsigned char* lds, const Gemm g, const Sched& S, const Epi& E) {
;     ...
;             PG8_LDA(At, 1, 1); PG8_STAGE(PG8_SA(1, 0), a3, voffA);
;             PG8_BAR; PG8_WAIT_L(0); PG8_MMA(1, 0, At, B0); PG8_BAR; PG8_SCHED;
;             PG8_STAGE(PG8_SB(1, 1), b3 + hstepB, voffB);
;             PG8_WAIT_V(6); PG8_BAR; PG8_MMA(1, 1, At, B1); PG8_BAR;
;         }
;         E(acc, cur, wr, wc, ui, fq);
;         S.done(cur);
;         if (!has_next) break;
	s_setprio 0
	ds_read_b128 v[148:151], v224 offset:49152
	ds_read_b128 v[152:155], v224 offset:50176
	ds_read_b128 v[156:159], v224 offset:51200
	ds_read_b128 v[160:163], v224 offset:52224
	ds_read_b128 v[164:167], v224 offset:53248
	ds_read_b128 v[168:171], v224 offset:54272
	ds_read_b128 v[172:175], v224 offset:55296
	ds_read_b128 v[176:179], v224 offset:56320
	s_add_i32 s25, s52, s30
	v_lshl_add_u64 v[206:207], v[206:207], 0, s[8:9]
	s_mov_b32 m0, s25
	s_nop 0
	global_load_lds_dwordx4 v[206:207], off
	v_lshl_add_u64 v[206:207], v[208:209], 0, s[8:9]
	s_add_i32 m0, s25, 0x2000
	s_nop 0
	global_load_lds_dwordx4 v[206:207], off
	s_mov_b32 m0, s42
	v_lshl_add_u64 v[206:207], v[210:211], 0, s[8:9]
	global_load_lds_dwordx4 v[206:207], off
	v_lshl_add_u64 v[206:207], v[212:213], 0, s[8:9]
	s_mov_b32 m0, s43
	s_nop 0
	global_load_lds_dwordx4 v[206:207], off
	s_add_u32 s20, s20, 0x80080
	s_addc_u32 s21, s21, 0
	s_add_i32 s24, s24, s30
	s_mov_b32 m0, s24
	s_nop 0
	global_load_lds_dwordx4 v2, s[20:21]
	s_add_i32 m0, s24, 0x2000
	s_nop 0
	global_load_lds_dwordx4 v192, s[20:21]
	s_add_i32 s51, s51, 2
	s_add_u32 s6, s6, 0x100
	s_addc_u32 s7, s7, 0
	s_add_u32 s49, s49, 0x100
	s_addc_u32 s50, s50, 0
	s_cmp_gt_u32 s51, 29
	s_waitcnt lgkmcnt(0)
	s_waitcnt vmcnt(6)
	s_setprio 1
	s_barrier
	v_mfma_f32_16x16x32_bf16 v[64:67], v[132:135], v[148:151], v[64:67]
	v_mfma_f32_16x16x32_bf16 v[60:63], v[140:143], v[148:151], v[60:63]
	v_mfma_f32_16x16x32_bf16 v[52:55], v[132:135], v[156:159], v[52:55]
	v_mfma_f32_16x16x32_bf16 v[44:47], v[140:143], v[156:159], v[44:47]
	v_mfma_f32_16x16x32_bf16 v[36:39], v[132:135], v[164:167], v[36:39]
	v_mfma_f32_16x16x32_bf16 v[28:31], v[140:143], v[164:167], v[28:31]
	v_mfma_f32_16x16x32_bf16 v[20:23], v[132:135], v[172:175], v[20:23]
	v_mfma_f32_16x16x32_bf16 v[12:15], v[140:143], v[172:175], v[12:15]
	v_mfma_f32_16x16x32_bf16 v[64:67], v[136:139], v[152:155], v[64:67]
	v_mfma_f32_16x16x32_bf16 v[60:63], v[144:147], v[152:155], v[60:63]
	v_mfma_f32_16x16x32_bf16 v[52:55], v[136:139], v[160:163], v[52:55]
	v_mfma_f32_16x16x32_bf16 v[44:47], v[144:147], v[160:163], v[44:47]
	v_mfma_f32_16x16x32_bf16 v[36:39], v[136:139], v[168:171], v[36:39]
	v_mfma_f32_16x16x32_bf16 v[28:31], v[144:147], v[168:171], v[28:31]
	v_mfma_f32_16x16x32_bf16 v[20:23], v[136:139], v[176:179], v[20:23]
	v_mfma_f32_16x16x32_bf16 v[12:15], v[144:147], v[176:179], v[12:15]
	v_mfma_f32_16x16x32_bf16 v[56:59], v[180:183], v[148:151], v[56:59]
	v_mfma_f32_16x16x32_bf16 v[48:51], v[188:191], v[148:151], v[48:51]
	v_mfma_f32_16x16x32_bf16 v[40:43], v[180:183], v[156:159], v[40:43]
	v_mfma_f32_16x16x32_bf16 v[32:35], v[188:191], v[156:159], v[32:35]
	v_mfma_f32_16x16x32_bf16 v[24:27], v[180:183], v[164:167], v[24:27]
	v_mfma_f32_16x16x32_bf16 v[16:19], v[188:191], v[164:167], v[16:19]
	v_mfma_f32_16x16x32_bf16 v[8:11], v[180:183], v[172:175], v[8:11]
	v_mfma_f32_16x16x32_bf16 v[4:7], v[188:191], v[172:175], v[4:7]
	v_mfma_f32_16x16x32_bf16 v[56:59], v[184:187], v[152:155], v[56:59]
	v_mfma_f32_16x16x32_bf16 v[48:51], v[202:205], v[152:155], v[48:51]
	v_mfma_f32_16x16x32_bf16 v[40:43], v[184:187], v[160:163], v[40:43]
	v_mfma_f32_16x16x32_bf16 v[32:35], v[202:205], v[160:163], v[32:35]
	v_mfma_f32_16x16x32_bf16 v[24:27], v[184:187], v[168:171], v[24:27]
	v_mfma_f32_16x16x32_bf16 v[16:19], v[202:205], v[168:171], v[16:19]
	v_mfma_f32_16x16x32_bf16 v[8:11], v[184:187], v[176:179], v[8:11]
	v_mfma_f32_16x16x32_bf16 v[4:7], v[202:205], v[176:179], v[4:7]
	s_barrier
	s_cbranch_scc0 .LBB0_1396
	s_setprio 0
	v_mov_b32_e32 v133, v0
	s_lshl_b32 s1, s46, 8
	s_add_i32 s1, s1, s38
	v_and_or_b32 v132, v133, 15, s1
	s_lshl_b32 s1, s45, 8
	v_lshrrev_b32_e32 v133, 1, v133
	v_and_or_b32 v133, v133, 24, s1
	v_or_b32_e32 v134, s39, v133
	v_ashrrev_i32_e32 v135, 31, v134
	v_lshlrev_b64 v[202:203], 1, v[134:135]
	v_ashrrev_i32_e32 v133, 31, v132
	v_lshl_add_u64 v[134:135], s[88:89], 0, v[202:203]
	v_lshlrev_b64 v[216:217], 12, v[132:133]
	v_lshl_add_u64 v[136:137], v[134:135], 0, v[216:217]
	global_load_dwordx4 v[226:229], v[136:137], off
	global_load_dwordx4 v[188:191], v[136:137], off offset:256
	v_or_b32_e32 v136, 16, v132
	v_ashrrev_i32_e32 v137, 31, v136
	v_lshlrev_b64 v[222:223], 12, v[136:137]
	v_lshl_add_u64 v[136:137], v[134:135], 0, v[222:223]
	global_load_dwordx4 v[184:187], v[136:137], off
	global_load_dwordx4 v[180:183], v[136:137], off offset:256
	v_or_b32_e32 v136, 32, v132
	v_ashrrev_i32_e32 v137, 31, v136
	v_lshlrev_b64 v[220:221], 12, v[136:137]
	v_lshl_add_u64 v[136:137], v[134:135], 0, v[220:221]
	global_load_dwordx4 v[176:179], v[136:137], off
	global_load_dwordx4 v[168:171], v[136:137], off offset:256
	v_or_b32_e32 v132, 48, v132
	v_ashrrev_i32_e32 v133, 31, v132
	v_lshlrev_b64 v[212:213], 12, v[132:133]
	v_lshl_add_u64 v[132:133], v[134:135], 0, v[212:213]
	global_load_dwordx4 v[172:175], v[132:133], off
	global_load_dwordx4 v[164:167], v[132:133], off offset:256
	s_mov_b64 s[6:7], 0x80000
	v_lshl_add_u64 v[210:211], v[216:217], 0, s[6:7]
	v_lshl_add_u64 v[132:133], v[134:135], 0, v[210:211]
	global_load_dwordx4 v[160:163], v[132:133], off
	global_load_dwordx4 v[156:159], v[132:133], off offset:256
	s_mov_b64 s[6:7], 0x90000
	v_lshl_add_u64 v[208:209], v[216:217], 0, s[6:7]
	v_lshl_add_u64 v[132:133], v[134:135], 0, v[208:209]
	global_load_dwordx4 v[152:155], v[132:133], off
	global_load_dwordx4 v[148:151], v[132:133], off offset:256
	s_mov_b64 s[6:7], 0xa0000
	v_lshl_add_u64 v[206:207], v[216:217], 0, s[6:7]
	v_lshl_add_u64 v[132:133], v[134:135], 0, v[206:207]
	global_load_dwordx4 v[144:147], v[132:133], off
	global_load_dwordx4 v[140:143], v[132:133], off offset:256
	s_mov_b64 s[6:7], 0xb0000
	v_lshl_add_u64 v[204:205], v[216:217], 0, s[6:7]
	v_lshl_add_u64 v[132:133], v[134:135], 0, v[204:205]
	global_load_dwordx4 v[136:139], v[132:133], off
	s_nop 0
	global_load_dwordx4 v[132:135], v[132:133], off offset:256
	s_and_b64 vcc, exec, s[40:41]
	s_mov_b32 s45, s0
	s_mov_b32 s46, s14
	s_mov_b64 s[20:21], s[18:19]
	s_mov_b64 s[6:7], s[4:5]
	s_waitcnt vmcnt(15)
; __device__ __forceinline__ unsigned cvt_pk_bf16(float lo, float hi) { const f32x2 v = {lo, hi}; const bf16v2_ r = __builtin_convertvector(v, bf16v2_); return __builtin_bit_cast(unsigned, r); }
; __device__ __forceinline__ float bflo(unsigned w) { return __uint_as_float(w << 16); }
; __device__ __forceinline__ float bfhi(unsigned w) { return __uint_as_float(w & 0xffff0000u); }
;     __device__ __forceinline__ void operator()(const f32x4 (&acc)[2][2][4][2], const Unit& u, int wr, int wc, int, int) const {
;     ...
;         for (int ai = 0; ai < 2; ++ai)
; #pragma unroll
;             for (int m = 0; m < 4; ++m)
; #pragma unroll
;                 for (int bj = 0; bj < 2; ++bj) { const u32x4 c = cin[ai][m][bj]; const f32x4 v0 = acc[ai][bj][m][0], v1 = acc[ai][bj][m][1];
;                     u32x4 w; w.x = cvt_pk_bf16(bflo(c.x) + v0[0], bfhi(c.x) + v0[1]); w.y = cvt_pk_bf16(bflo(c.y) + v0[2], bfhi(c.y) + v0[3]);
;                     w.z = cvt_pk_bf16(bflo(c.z) + v1[0], bfhi(c.z) + v1[1]); w.w = cvt_pk_bf16(bflo(c.w) + v1[2], bfhi(c.w) + v1[3]);
;                     *(u32x4*)(C + (size_t)(row0 + ai * HALF + m * 16) * ldc + col0 + bj * HALF) = w; }
	v_lshlrev_b32_e32 v218, 16, v226
	v_and_b32_e32 v219, 0xffff0000, v226
	v_pk_add_f32 v[128:129], v[128:129], v[218:219]
	v_lshlrev_b32_e32 v218, 16, v227
	v_and_b32_e32 v219, 0xffff0000, v227
	v_pk_add_f32 v[130:131], v[130:131], v[218:219]
	v_cvt_pk_bf16_f32 v128, v128, v129
	v_cvt_pk_bf16_f32 v129, v130, v131
	v_lshlrev_b32_e32 v130, 16, v228
	v_and_b32_e32 v131, 0xffff0000, v228
	v_pk_add_f32 v[124:125], v[124:125], v[130:131]
	s_nop 0
	v_cvt_pk_bf16_f32 v130, v124, v125
	v_lshlrev_b32_e32 v124, 16, v229
	v_and_b32_e32 v125, 0xffff0000, v229
	v_pk_add_f32 v[124:125], v[126:127], v[124:125]
	s_waitcnt vmcnt(14)
	v_lshlrev_b32_e32 v126, 16, v188
	v_and_b32_e32 v127, 0xffff0000, v188
	v_pk_add_f32 v[120:121], v[120:121], v[126:127]
	v_lshlrev_b32_e32 v126, 16, v189
	v_and_b32_e32 v127, 0xffff0000, v189
	v_pk_add_f32 v[122:123], v[122:123], v[126:127]
	v_cvt_pk_bf16_f32 v120, v120, v121
	v_cvt_pk_bf16_f32 v121, v122, v123
	v_lshlrev_b32_e32 v122, 16, v190
	v_and_b32_e32 v123, 0xffff0000, v190
	v_pk_add_f32 v[116:117], v[116:117], v[122:123]
	v_cvt_pk_bf16_f32 v131, v124, v125
	v_cvt_pk_bf16_f32 v122, v116, v117
	v_lshlrev_b32_e32 v116, 16, v191
	v_and_b32_e32 v117, 0xffff0000, v191
	v_pk_add_f32 v[116:117], v[118:119], v[116:117]
	v_lshl_add_u64 v[124:125], s[88:89], 0, v[216:217]
	v_cvt_pk_bf16_f32 v123, v116, v117
	s_waitcnt vmcnt(13)
	v_lshlrev_b32_e32 v116, 16, v184
	v_and_b32_e32 v117, 0xffff0000, v184
	v_pk_add_f32 v[112:113], v[112:113], v[116:117]
	v_lshlrev_b32_e32 v116, 16, v185
	v_and_b32_e32 v117, 0xffff0000, v185
	v_pk_add_f32 v[114:115], v[114:115], v[116:117]
	v_cvt_pk_bf16_f32 v112, v112, v113
	v_cvt_pk_bf16_f32 v113, v114, v115
	v_lshlrev_b32_e32 v114, 16, v186
	v_and_b32_e32 v115, 0xffff0000, v186
	v_pk_add_f32 v[108:109], v[108:109], v[114:115]
	v_lshl_add_u64 v[124:125], v[124:125], 0, v[202:203]
	v_cvt_pk_bf16_f32 v114, v108, v109
	v_lshlrev_b32_e32 v108, 16, v187
	v_and_b32_e32 v109, 0xffff0000, v187
	v_pk_add_f32 v[108:109], v[110:111], v[108:109]
	s_waitcnt vmcnt(12)
	v_lshlrev_b32_e32 v110, 16, v180
	v_and_b32_e32 v111, 0xffff0000, v180
	v_pk_add_f32 v[104:105], v[104:105], v[110:111]
	v_lshlrev_b32_e32 v110, 16, v181
	v_and_b32_e32 v111, 0xffff0000, v181
	v_pk_add_f32 v[106:107], v[106:107], v[110:111]
	v_cvt_pk_bf16_f32 v104, v104, v105
	v_cvt_pk_bf16_f32 v105, v106, v107
	v_lshlrev_b32_e32 v106, 16, v182
	v_and_b32_e32 v107, 0xffff0000, v182
	v_pk_add_f32 v[96:97], v[96:97], v[106:107]
	v_cvt_pk_bf16_f32 v115, v108, v109
	v_cvt_pk_bf16_f32 v106, v96, v97
	v_lshlrev_b32_e32 v96, 16, v183
	v_and_b32_e32 v97, 0xffff0000, v183
	v_pk_add_f32 v[96:97], v[98:99], v[96:97]
	s_waitcnt vmcnt(11)
	v_lshlrev_b32_e32 v98, 16, v177
	v_cvt_pk_bf16_f32 v107, v96, v97
	v_lshlrev_b32_e32 v96, 16, v176
	v_and_b32_e32 v97, 0xffff0000, v176
	v_and_b32_e32 v99, 0xffff0000, v177
	v_pk_add_f32 v[96:97], v[100:101], v[96:97]
	v_pk_add_f32 v[98:99], v[102:103], v[98:99]
	v_cvt_pk_bf16_f32 v96, v96, v97
	v_cvt_pk_bf16_f32 v97, v98, v99
	v_lshlrev_b32_e32 v98, 16, v178
	v_and_b32_e32 v99, 0xffff0000, v178
	v_pk_add_f32 v[92:93], v[92:93], v[98:99]
	v_lshl_add_u64 v[108:109], s[88:89], 0, v[222:223]
	v_cvt_pk_bf16_f32 v98, v92, v93
	v_lshlrev_b32_e32 v92, 16, v179
	v_and_b32_e32 v93, 0xffff0000, v179
	v_pk_add_f32 v[92:93], v[94:95], v[92:93]
	s_waitcnt vmcnt(10)
	v_lshlrev_b32_e32 v94, 16, v168
	v_and_b32_e32 v95, 0xffff0000, v168
	v_pk_add_f32 v[88:89], v[88:89], v[94:95]
	v_lshlrev_b32_e32 v94, 16, v169
	v_and_b32_e32 v95, 0xffff0000, v169
	v_pk_add_f32 v[90:91], v[90:91], v[94:95]
	v_cvt_pk_bf16_f32 v88, v88, v89
	v_cvt_pk_bf16_f32 v89, v90, v91
	v_lshlrev_b32_e32 v90, 16, v170
	v_and_b32_e32 v91, 0xffff0000, v170
	v_pk_add_f32 v[80:81], v[80:81], v[90:91]
	v_cvt_pk_bf16_f32 v99, v92, v93
	v_cvt_pk_bf16_f32 v90, v80, v81
	v_lshlrev_b32_e32 v80, 16, v171
	v_and_b32_e32 v81, 0xffff0000, v171
	v_pk_add_f32 v[80:81], v[82:83], v[80:81]
	s_waitcnt vmcnt(9)
	v_lshlrev_b32_e32 v82, 16, v173
	v_cvt_pk_bf16_f32 v91, v80, v81
	v_lshlrev_b32_e32 v80, 16, v172
	v_and_b32_e32 v81, 0xffff0000, v172
	v_and_b32_e32 v83, 0xffff0000, v173
	v_pk_add_f32 v[80:81], v[84:85], v[80:81]
	v_pk_add_f32 v[82:83], v[86:87], v[82:83]
	v_cvt_pk_bf16_f32 v80, v80, v81
	v_cvt_pk_bf16_f32 v81, v82, v83
	v_lshlrev_b32_e32 v82, 16, v174
	v_and_b32_e32 v83, 0xffff0000, v174
	v_pk_add_f32 v[76:77], v[76:77], v[82:83]
	v_lshl_add_u64 v[92:93], s[88:89], 0, v[220:221]
	v_cvt_pk_bf16_f32 v82, v76, v77
	v_lshlrev_b32_e32 v76, 16, v175
	v_and_b32_e32 v77, 0xffff0000, v175
	v_pk_add_f32 v[76:77], v[78:79], v[76:77]
	s_waitcnt vmcnt(8)
	v_lshlrev_b32_e32 v78, 16, v164
	v_and_b32_e32 v79, 0xffff0000, v164
	v_pk_add_f32 v[72:73], v[72:73], v[78:79]
	v_lshlrev_b32_e32 v78, 16, v165
	v_and_b32_e32 v79, 0xffff0000, v165
	v_pk_add_f32 v[74:75], v[74:75], v[78:79]
	v_cvt_pk_bf16_f32 v72, v72, v73
	v_cvt_pk_bf16_f32 v73, v74, v75
	v_lshlrev_b32_e32 v74, 16, v166
	v_and_b32_e32 v75, 0xffff0000, v166
	v_pk_add_f32 v[68:69], v[68:69], v[74:75]
	v_cvt_pk_bf16_f32 v83, v76, v77
	v_cvt_pk_bf16_f32 v74, v68, v69
	v_lshlrev_b32_e32 v68, 16, v167
	v_and_b32_e32 v69, 0xffff0000, v167
	v_pk_add_f32 v[68:69], v[70:71], v[68:69]
	v_lshl_add_u64 v[76:77], s[88:89], 0, v[212:213]
	v_cvt_pk_bf16_f32 v75, v68, v69
	s_waitcnt vmcnt(7)
	v_lshlrev_b32_e32 v68, 16, v160
	v_and_b32_e32 v69, 0xffff0000, v160
	v_pk_add_f32 v[64:65], v[64:65], v[68:69]
	v_lshlrev_b32_e32 v68, 16, v161
	v_and_b32_e32 v69, 0xffff0000, v161
	v_pk_add_f32 v[66:67], v[66:67], v[68:69]
	v_cvt_pk_bf16_f32 v64, v64, v65
	v_cvt_pk_bf16_f32 v65, v66, v67
	v_lshlrev_b32_e32 v66, 16, v162
	v_and_b32_e32 v67, 0xffff0000, v162
	v_pk_add_f32 v[60:61], v[60:61], v[66:67]
	v_lshl_add_u64 v[108:109], v[108:109], 0, v[202:203]
	v_cvt_pk_bf16_f32 v66, v60, v61
	v_lshlrev_b32_e32 v60, 16, v163
	v_and_b32_e32 v61, 0xffff0000, v163
	v_pk_add_f32 v[60:61], v[62:63], v[60:61]
	s_waitcnt vmcnt(6)
; __device__ __forceinline__ unsigned cvt_pk_bf16(float lo, float hi) { const f32x2 v = {lo, hi}; const bf16v2_ r = __builtin_convertvector(v, bf16v2_); return __builtin_bit_cast(unsigned, r); }
; __device__ __forceinline__ float bflo(unsigned w) { return __uint_as_float(w << 16); }
; __device__ __forceinline__ float bfhi(unsigned w) { return __uint_as_float(w & 0xffff0000u); }
;     __device__ __forceinline__ void operator()(const f32x4 (&acc)[2][2][4][2], const Unit& u, int wr, int wc, int, int) const {
;     ...
;         for (int ai = 0; ai < 2; ++ai)
; #pragma unroll
;             for (int m = 0; m < 4; ++m)
; #pragma unroll
;                 for (int bj = 0; bj < 2; ++bj) { const u32x4 c = cin[ai][m][bj]; const f32x4 v0 = acc[ai][bj][m][0], v1 = acc[ai][bj][m][1];
;                     u32x4 w; w.x = cvt_pk_bf16(bflo(c.x) + v0[0], bfhi(c.x) + v0[1]); w.y = cvt_pk_bf16(bflo(c.y) + v0[2], bfhi(c.y) + v0[3]);
;                     w.z = cvt_pk_bf16(bflo(c.z) + v1[0], bfhi(c.z) + v1[1]); w.w = cvt_pk_bf16(bflo(c.w) + v1[2], bfhi(c.w) + v1[3]);
;                     *(u32x4*)(C + (size_t)(row0 + ai * HALF + m * 16) * ldc + col0 + bj * HALF) = w; }
	v_lshlrev_b32_e32 v62, 16, v156
	v_and_b32_e32 v63, 0xffff0000, v156
	v_pk_add_f32 v[56:57], v[56:57], v[62:63]
	v_lshlrev_b32_e32 v62, 16, v157
	v_and_b32_e32 v63, 0xffff0000, v157
	v_pk_add_f32 v[58:59], v[58:59], v[62:63]
	v_cvt_pk_bf16_f32 v56, v56, v57
	v_cvt_pk_bf16_f32 v57, v58, v59
	v_lshlrev_b32_e32 v58, 16, v158
	v_and_b32_e32 v59, 0xffff0000, v158
	v_pk_add_f32 v[48:49], v[48:49], v[58:59]
	v_cvt_pk_bf16_f32 v67, v60, v61
	v_cvt_pk_bf16_f32 v58, v48, v49
	v_lshlrev_b32_e32 v48, 16, v159
	v_and_b32_e32 v49, 0xffff0000, v159
	v_pk_add_f32 v[48:49], v[50:51], v[48:49]
	s_waitcnt vmcnt(5)
	v_lshlrev_b32_e32 v50, 16, v153
	v_cvt_pk_bf16_f32 v59, v48, v49
	v_lshlrev_b32_e32 v48, 16, v152
	v_and_b32_e32 v49, 0xffff0000, v152
	v_and_b32_e32 v51, 0xffff0000, v153
	v_pk_add_f32 v[48:49], v[52:53], v[48:49]
	v_pk_add_f32 v[50:51], v[54:55], v[50:51]
	v_cvt_pk_bf16_f32 v48, v48, v49
	v_cvt_pk_bf16_f32 v49, v50, v51
	v_lshlrev_b32_e32 v50, 16, v154
	v_and_b32_e32 v51, 0xffff0000, v154
	v_pk_add_f32 v[44:45], v[44:45], v[50:51]
	v_lshl_add_u64 v[60:61], s[88:89], 0, v[210:211]
	v_cvt_pk_bf16_f32 v50, v44, v45
	v_lshlrev_b32_e32 v44, 16, v155
	v_and_b32_e32 v45, 0xffff0000, v155
	v_pk_add_f32 v[44:45], v[46:47], v[44:45]
	s_waitcnt vmcnt(4)
	v_lshlrev_b32_e32 v46, 16, v148
	v_and_b32_e32 v47, 0xffff0000, v148
	v_pk_add_f32 v[40:41], v[40:41], v[46:47]
	v_lshlrev_b32_e32 v46, 16, v149
	v_and_b32_e32 v47, 0xffff0000, v149
	v_pk_add_f32 v[42:43], v[42:43], v[46:47]
	v_cvt_pk_bf16_f32 v40, v40, v41
	v_cvt_pk_bf16_f32 v41, v42, v43
	v_lshlrev_b32_e32 v42, 16, v150
	v_and_b32_e32 v43, 0xffff0000, v150
	v_pk_add_f32 v[32:33], v[32:33], v[42:43]
	v_cvt_pk_bf16_f32 v51, v44, v45
	v_cvt_pk_bf16_f32 v42, v32, v33
	v_lshlrev_b32_e32 v32, 16, v151
	v_and_b32_e32 v33, 0xffff0000, v151
	v_pk_add_f32 v[32:33], v[34:35], v[32:33]
	s_waitcnt vmcnt(3)
	v_lshlrev_b32_e32 v34, 16, v145
	v_cvt_pk_bf16_f32 v43, v32, v33
	v_lshlrev_b32_e32 v32, 16, v144
	v_and_b32_e32 v33, 0xffff0000, v144
	v_and_b32_e32 v35, 0xffff0000, v145
	v_pk_add_f32 v[32:33], v[36:37], v[32:33]
	v_pk_add_f32 v[34:35], v[38:39], v[34:35]
	v_cvt_pk_bf16_f32 v32, v32, v33
	v_cvt_pk_bf16_f32 v33, v34, v35
	v_lshlrev_b32_e32 v34, 16, v146
	v_and_b32_e32 v35, 0xffff0000, v146
	v_pk_add_f32 v[28:29], v[28:29], v[34:35]
	v_lshl_add_u64 v[44:45], s[88:89], 0, v[208:209]
	v_cvt_pk_bf16_f32 v34, v28, v29
	v_lshlrev_b32_e32 v28, 16, v147
	v_and_b32_e32 v29, 0xffff0000, v147
	v_pk_add_f32 v[28:29], v[30:31], v[28:29]
	s_waitcnt vmcnt(2)
	v_lshlrev_b32_e32 v30, 16, v140
	v_and_b32_e32 v31, 0xffff0000, v140
	v_pk_add_f32 v[24:25], v[24:25], v[30:31]
	v_lshlrev_b32_e32 v30, 16, v141
	v_and_b32_e32 v31, 0xffff0000, v141
	v_pk_add_f32 v[26:27], v[26:27], v[30:31]
	v_cvt_pk_bf16_f32 v24, v24, v25
	v_cvt_pk_bf16_f32 v25, v26, v27
	v_lshlrev_b32_e32 v26, 16, v142
	v_and_b32_e32 v27, 0xffff0000, v142
	v_pk_add_f32 v[16:17], v[16:17], v[26:27]
	v_cvt_pk_bf16_f32 v35, v28, v29
	v_cvt_pk_bf16_f32 v26, v16, v17
	v_lshlrev_b32_e32 v16, 16, v143
	v_and_b32_e32 v17, 0xffff0000, v143
	v_pk_add_f32 v[16:17], v[18:19], v[16:17]
	s_waitcnt vmcnt(1)
	v_lshlrev_b32_e32 v18, 16, v137
	v_cvt_pk_bf16_f32 v27, v16, v17
	v_lshlrev_b32_e32 v16, 16, v136
	v_and_b32_e32 v17, 0xffff0000, v136
	v_and_b32_e32 v19, 0xffff0000, v137
	v_pk_add_f32 v[16:17], v[20:21], v[16:17]
	v_pk_add_f32 v[18:19], v[22:23], v[18:19]
	v_cvt_pk_bf16_f32 v16, v16, v17
	v_cvt_pk_bf16_f32 v17, v18, v19
	v_lshlrev_b32_e32 v18, 16, v138
	v_and_b32_e32 v19, 0xffff0000, v138
	v_pk_add_f32 v[12:13], v[12:13], v[18:19]
	v_lshl_add_u64 v[28:29], s[88:89], 0, v[206:207]
	v_cvt_pk_bf16_f32 v18, v12, v13
	v_lshlrev_b32_e32 v12, 16, v139
	v_and_b32_e32 v13, 0xffff0000, v139
	v_pk_add_f32 v[12:13], v[14:15], v[12:13]
	s_waitcnt vmcnt(0)
; __device__ __forceinline__ unsigned cvt_pk_bf16(float lo, float hi) { const f32x2 v = {lo, hi}; const bf16v2_ r = __builtin_convertvector(v, bf16v2_); return __builtin_bit_cast(unsigned, r); }
; __device__ __forceinline__ float bflo(unsigned w) { return __uint_as_float(w << 16); }
; __device__ __forceinline__ float bfhi(unsigned w) { return __uint_as_float(w & 0xffff0000u); }
; __device__ __forceinline__ float wave_sum(float v) { v = row16_sum(v); v += shx(v, 16); v += shx(v, 32); return v; }
;     __device__ __forceinline__ void operator()(const f32x4 (&acc)[2][2][4][2], const Unit& u, int wr, int wc, int, int) const {
;     ...
;                 for (int bj = 0; bj < 2; ++bj) { const u32x4 c = cin[ai][m][bj]; const f32x4 v0 = acc[ai][bj][m][0], v1 = acc[ai][bj][m][1];
;                     u32x4 w; w.x = cvt_pk_bf16(bflo(c.x) + v0[0], bfhi(c.x) + v0[1]); w.y = cvt_pk_bf16(bflo(c.y) + v0[2], bfhi(c.y) + v0[3]);
;                     w.z = cvt_pk_bf16(bflo(c.z) + v1[0], bfhi(c.z) + v1[1]); w.w = cvt_pk_bf16(bflo(c.w) + v1[2], bfhi(c.w) + v1[3]);
;                     *(u32x4*)(C + (size_t)(row0 + ai * HALF + m * 16) * ldc + col0 + bj * HALF) = w; }
; __device__ __forceinline__ void rowstat_phase(const Frame& F, const bf16_t* __restrict__ res, float* __restrict__ rstd_out) {
;     ...
;         for (int r = 0; r < 4; ++r) { ss[r] = 0.f;
; #pragma unroll
;             for (int i = 0; i < 4; ++i) { const u32x4 x = v[r][i];
;                 ss[r] += bflo(x.x) * bflo(x.x) + bfhi(x.x) * bfhi(x.x) + bflo(x.y) * bflo(x.y) + bfhi(x.y) * bfhi(x.y) + bflo(x.z) * bflo(x.z) + bfhi(x.z) * bfhi(x.z) + bflo(x.w) * bflo(x.w) + bfhi(x.w) * bfhi(x.w); }
;             ss[r] = wave_sum(ss[r]); }
	v_lshlrev_b32_e32 v14, 16, v132
	v_and_b32_e32 v15, 0xffff0000, v132
	v_pk_add_f32 v[8:9], v[8:9], v[14:15]
	v_lshlrev_b32_e32 v14, 16, v133
	v_and_b32_e32 v15, 0xffff0000, v133
	v_pk_add_f32 v[10:11], v[10:11], v[14:15]
	v_cvt_pk_bf16_f32 v8, v8, v9
	v_cvt_pk_bf16_f32 v9, v10, v11
	v_lshlrev_b32_e32 v10, 16, v134
	v_and_b32_e32 v11, 0xffff0000, v134
	v_pk_add_f32 v[4:5], v[4:5], v[10:11]
	v_cvt_pk_bf16_f32 v19, v12, v13
	v_cvt_pk_bf16_f32 v10, v4, v5
	v_lshlrev_b32_e32 v4, 16, v135
	v_and_b32_e32 v5, 0xffff0000, v135
	v_lshl_add_u64 v[12:13], s[88:89], 0, v[204:205]
	v_pk_add_f32 v[4:5], v[6:7], v[4:5]
	v_lshl_add_u64 v[92:93], v[92:93], 0, v[202:203]
	v_lshl_add_u64 v[76:77], v[76:77], 0, v[202:203]
	v_lshl_add_u64 v[60:61], v[60:61], 0, v[202:203]
	v_lshl_add_u64 v[44:45], v[44:45], 0, v[202:203]
	v_lshl_add_u64 v[28:29], v[28:29], 0, v[202:203]
	v_lshl_add_u64 v[12:13], v[12:13], 0, v[202:203]
	v_cvt_pk_bf16_f32 v11, v4, v5
	global_store_dwordx4 v[124:125], v[128:131], off
	global_store_dwordx4 v[124:125], v[120:123], off offset:256
	global_store_dwordx4 v[108:109], v[112:115], off
	global_store_dwordx4 v[108:109], v[104:107], off offset:256
	global_store_dwordx4 v[92:93], v[96:99], off
	global_store_dwordx4 v[92:93], v[88:91], off offset:256
	global_store_dwordx4 v[76:77], v[80:83], off
	global_store_dwordx4 v[76:77], v[72:75], off offset:256
	global_store_dwordx4 v[60:61], v[64:67], off
	global_store_dwordx4 v[60:61], v[56:59], off offset:256
	global_store_dwordx4 v[44:45], v[48:51], off
	global_store_dwordx4 v[44:45], v[40:43], off offset:256
	global_store_dwordx4 v[28:29], v[32:35], off
	global_store_dwordx4 v[28:29], v[24:27], off offset:256
	global_store_dwordx4 v[12:13], v[16:19], off
	global_store_dwordx4 v[12:13], v[8:11], off offset:256
	v_subrev_u32_e32 v226, s88, v124
	v_bfe_u32 v227, v226, 4, 8
	v_lshrrev_b32_e32 v226, 12, v226
	v_and_b32_e32 v228, 15, v227
	v_lshrrev_b32_e32 v227, 5, v227
	v_lshl_or_b32 v227, v227, 4, v228
	v_lshlrev_b32_e32 v227, 17, v227
	v_and_b32_e32 v228, 15, v226
	v_and_b32_e32 v226, 0xffffffc0, v226
	v_lshl_or_b32 v226, v228, 2, v226
	v_lshl_add_u32 v226, v226, 2, v227
	v_add_u32_e32 v226, 0x1e000000, v226
	v_mov_b32_e32 v188, 0
	v_dot2c_f32_bf16_e32 v188, v128, v128
	v_dot2c_f32_bf16_e32 v188, v129, v129
	v_dot2c_f32_bf16_e32 v188, v130, v130
	v_dot2c_f32_bf16_e32 v188, v131, v131
	v_dot2c_f32_bf16_e32 v188, v120, v120
	v_dot2c_f32_bf16_e32 v188, v121, v121
	v_dot2c_f32_bf16_e32 v188, v122, v122
	v_dot2c_f32_bf16_e32 v188, v123, v123
	v_mov_b32_e32 v189, 0
	v_dot2c_f32_bf16_e32 v189, v112, v112
	v_dot2c_f32_bf16_e32 v189, v113, v113
	v_dot2c_f32_bf16_e32 v189, v114, v114
	v_dot2c_f32_bf16_e32 v189, v115, v115
	v_dot2c_f32_bf16_e32 v189, v104, v104
	v_dot2c_f32_bf16_e32 v189, v105, v105
	v_dot2c_f32_bf16_e32 v189, v106, v106
	v_dot2c_f32_bf16_e32 v189, v107, v107
	v_mov_b32_e32 v190, 0
	v_dot2c_f32_bf16_e32 v190, v96, v96
	v_dot2c_f32_bf16_e32 v190, v97, v97
	v_dot2c_f32_bf16_e32 v190, v98, v98
	v_dot2c_f32_bf16_e32 v190, v99, v99
	v_dot2c_f32_bf16_e32 v190, v88, v88
	v_dot2c_f32_bf16_e32 v190, v89, v89
	v_dot2c_f32_bf16_e32 v190, v90, v90
	v_dot2c_f32_bf16_e32 v190, v91, v91
	v_mov_b32_e32 v191, 0
	v_dot2c_f32_bf16_e32 v191, v80, v80
	v_dot2c_f32_bf16_e32 v191, v81, v81
	v_dot2c_f32_bf16_e32 v191, v82, v82
	v_dot2c_f32_bf16_e32 v191, v83, v83
	v_dot2c_f32_bf16_e32 v191, v72, v72
	v_dot2c_f32_bf16_e32 v191, v73, v73
	v_dot2c_f32_bf16_e32 v191, v74, v74
	v_dot2c_f32_bf16_e32 v191, v75, v75
	s_nop 2
	global_store_dwordx4 v226, v[188:191], s[88:89]
	s_nop 1
	v_mov_b32_e32 v188, 0
	v_dot2c_f32_bf16_e32 v188, v64, v64
	v_dot2c_f32_bf16_e32 v188, v65, v65
	v_dot2c_f32_bf16_e32 v188, v66, v66
	v_dot2c_f32_bf16_e32 v188, v67, v67
	v_dot2c_f32_bf16_e32 v188, v56, v56
	v_dot2c_f32_bf16_e32 v188, v57, v57
	v_dot2c_f32_bf16_e32 v188, v58, v58
	v_dot2c_f32_bf16_e32 v188, v59, v59
	v_mov_b32_e32 v189, 0
	v_dot2c_f32_bf16_e32 v189, v48, v48
	v_dot2c_f32_bf16_e32 v189, v49, v49
	v_dot2c_f32_bf16_e32 v189, v50, v50
	v_dot2c_f32_bf16_e32 v189, v51, v51
	v_dot2c_f32_bf16_e32 v189, v40, v40
	v_dot2c_f32_bf16_e32 v189, v41, v41
	v_dot2c_f32_bf16_e32 v189, v42, v42
	v_dot2c_f32_bf16_e32 v189, v43, v43
	v_mov_b32_e32 v190, 0
	v_dot2c_f32_bf16_e32 v190, v32, v32
	v_dot2c_f32_bf16_e32 v190, v33, v33
	v_dot2c_f32_bf16_e32 v190, v34, v34
	v_dot2c_f32_bf16_e32 v190, v35, v35
	v_dot2c_f32_bf16_e32 v190, v24, v24
	v_dot2c_f32_bf16_e32 v190, v25, v25
	v_dot2c_f32_bf16_e32 v190, v26, v26
	v_dot2c_f32_bf16_e32 v190, v27, v27
	v_mov_b32_e32 v191, 0
	v_dot2c_f32_bf16_e32 v191, v16, v16
	v_dot2c_f32_bf16_e32 v191, v17, v17
	v_dot2c_f32_bf16_e32 v191, v18, v18
	v_dot2c_f32_bf16_e32 v191, v19, v19
	v_dot2c_f32_bf16_e32 v191, v8, v8
	v_dot2c_f32_bf16_e32 v191, v9, v9
	v_dot2c_f32_bf16_e32 v191, v10, v10
	v_dot2c_f32_bf16_e32 v191, v11, v11
	s_nop 2
	global_store_dwordx4 v226, v[188:191], s[88:89] offset:512
	s_nop 1
	s_cbranch_vccz .LBB0_1389
	s_waitcnt vmcnt(0)
	s_cmpk_gt_u32 s2, 0xff
	s_cbranch_scc1 .LBB0_1400
	s_barrier

; #define PG8_STAGE(bufoff, gbase, voff) do { _Pragma("unroll") for (int _i = 0; _i < 2; ++_i) \
;         __builtin_amdgcn_global_load_lds((const unsigned*)((const char*)(gbase) + (voff)[_i]), (LAS unsigned*)(lds + (bufoff) + ldsw + _i * 8192), 16, 0, 0); } while (0)
; #define PG8_LDA(dst, b, h) do { _Pragma("unroll") for (int m = 0; m < 4; ++m) _Pragma("unroll") for (int k = 0; k < 2; ++k) dst[m][k] = *(const LAS bf16x8*)(lds + PG8_SA(b, h) + aoff + m * 2048 + k * 1024); } while (0)
; #define PG8_LDB(dst, b, h) do { _Pragma("unroll") for (int n = 0; n < 2; ++n) _Pragma("unroll") for (int k = 0; k < 2; ++k) dst[n][k] = *(const LAS bf16x8*)(lds + PG8_SB(b, h) + boff + n * 2048 + k * 1024); } while (0)
; #define PG8_MMA(ai, bj, At, Bt) do { __builtin_amdgcn_s_setprio(1); _Pragma("unroll") for (int m = 0; m < 4; ++m) _Pragma("unroll") for (int n = 0; n < 2; ++n) _Pragma("unroll") for (int k = 0; k < 2; ++k) \
;         acc[ai][bj][m][n] = __builtin_amdgcn_mfma_f32_16x16x32_bf16(Bt[n][k], At[m][k], acc[ai][bj][m][n], 0, 0, 0); __builtin_amdgcn_s_setprio(0); } while (0)
; #define PG8_WAIT_V(n) asm volatile("s_waitcnt vmcnt(" #n ")" ::: "memory")
; #define PG8_BAR __builtin_amdgcn_s_barrier()
; template <class Epi, class Sched>
; __device__ __forceinline__ void gemm_phase(LAS unsigned char* lds, const Gemm g, const Sched& S, const Epi& E) {
;     ...
;         for (int t = 0; t < nt; t += 2) {
;             const bool last = (t == nt - 2);
;             const char* a1 = cA + (size_t)(t + 1) * kstep;
;             const char* a2 = last ? nA : cA + (size_t)(t + 2) * kstep; const char* b2 = last ? nB : cB + (size_t)(t + 2) * kstep;
;             const char* a3 = a2 + kstep; const char* b3 = b2 + kstep;
;             if (last && has_next) S.a_ready(nxt);
;             PG8_LDB(B0, 0, 0); PG8_SCHED; PG8_LDA(At, 0, 0); PG8_STAGE(PG8_SA(1, 1), a1 + hstepA, voffA);
;             PG8_WAIT_L(8); PG8_BAR; PG8_WAIT_L(0); PG8_MMA(0, 0, At, B0); PG8_BAR; PG8_SCHED;
;             PG8_LDB(B1, 0, 1); PG8_STAGE(PG8_SB(0, 0), b2, voffB);
;             PG8_BAR; PG8_WAIT_L(0); PG8_MMA(0, 1, At, B1); PG8_BAR;
;             PG8_LDA(At, 0, 1); PG8_STAGE(PG8_SA(0, 0), a2, voffA);
;             PG8_BAR; PG8_WAIT_L(0); PG8_MMA(1, 0, At, B0); PG8_BAR; PG8_SCHED;
;             PG8_STAGE(PG8_SB(0, 1), b2 + hstepB, voffB);
;             PG8_WAIT_V(6); PG8_BAR; PG8_MMA(1, 1, At, B1); PG8_BAR;
.LBB0_1666:
	s_setprio 0
	s_add_u32 s14, s6, 0x100
	s_addc_u32 s15, s7, 0
	s_add_i32 s45, 0, 0x10000
	v_add_u32_e32 v144, s45, v1
	ds_read_b128 v[132:135], v144
	ds_read_b128 v[136:139], v144 offset:1024
	ds_read_b128 v[140:143], v144 offset:2048
	ds_read_b128 v[144:147], v144 offset:3072
	s_cmpk_eq_i32 s44, 0x54
	s_cselect_b32 s21, s1, s15
	s_cselect_b32 s20, s0, s14
	s_cselect_b32 s19, s5, s43
	s_cselect_b32 s18, s4, s42
	ds_read_b128 v[148:151], v224
	ds_read_b128 v[152:155], v224 offset:1024
	ds_read_b128 v[156:159], v224 offset:2048
	ds_read_b128 v[160:163], v224 offset:3072
	ds_read_b128 v[164:167], v224 offset:4096
	ds_read_b128 v[168:171], v224 offset:5120
	ds_read_b128 v[172:175], v224 offset:6144
	ds_read_b128 v[176:179], v224 offset:7168
	s_add_i32 s51, 0, 0x14000
	v_add_u32_e32 v202, s51, v1
	ds_read_b128 v[180:183], v202
	ds_read_b128 v[184:187], v202 offset:1024
	ds_read_b128 v[188:191], v202 offset:2048
	ds_read_b128 v[202:205], v202 offset:3072
	s_add_i32 m0, s29, 0xc000
	s_nop 0
	global_load_lds_dwordx4 v198, s[6:7]
	s_add_i32 m0, s29, 0xe000
	s_nop 0
	global_load_lds_dwordx4 v200, s[6:7]
	s_waitcnt lgkmcnt(0)
	s_setprio 1
	s_barrier
	v_mfma_f32_16x16x32_bf16 v[128:131], v[132:135], v[148:151], v[128:131]
	v_mfma_f32_16x16x32_bf16 v[124:127], v[140:143], v[148:151], v[124:127]
	v_mfma_f32_16x16x32_bf16 v[112:115], v[132:135], v[156:159], v[112:115]
	v_mfma_f32_16x16x32_bf16 v[108:111], v[140:143], v[156:159], v[108:111]
	v_mfma_f32_16x16x32_bf16 v[100:103], v[132:135], v[164:167], v[100:103]
	v_mfma_f32_16x16x32_bf16 v[92:95], v[140:143], v[164:167], v[92:95]
	v_mfma_f32_16x16x32_bf16 v[84:87], v[132:135], v[172:175], v[84:87]
	v_mfma_f32_16x16x32_bf16 v[76:79], v[140:143], v[172:175], v[76:79]
	v_mfma_f32_16x16x32_bf16 v[128:131], v[136:139], v[152:155], v[128:131]
	v_mfma_f32_16x16x32_bf16 v[124:127], v[144:147], v[152:155], v[124:127]
	v_mfma_f32_16x16x32_bf16 v[112:115], v[136:139], v[160:163], v[112:115]
	v_mfma_f32_16x16x32_bf16 v[108:111], v[144:147], v[160:163], v[108:111]
	v_mfma_f32_16x16x32_bf16 v[100:103], v[136:139], v[168:171], v[100:103]
	v_mfma_f32_16x16x32_bf16 v[92:95], v[144:147], v[168:171], v[92:95]
	v_mfma_f32_16x16x32_bf16 v[84:87], v[136:139], v[176:179], v[84:87]
	v_mfma_f32_16x16x32_bf16 v[76:79], v[144:147], v[176:179], v[76:79]
	v_mfma_f32_16x16x32_bf16 v[120:123], v[180:183], v[148:151], v[120:123]
	v_mfma_f32_16x16x32_bf16 v[116:119], v[188:191], v[148:151], v[116:119]
	v_mfma_f32_16x16x32_bf16 v[104:107], v[180:183], v[156:159], v[104:107]
	v_mfma_f32_16x16x32_bf16 v[96:99], v[188:191], v[156:159], v[96:99]
	v_mfma_f32_16x16x32_bf16 v[88:91], v[180:183], v[164:167], v[88:91]
	v_mfma_f32_16x16x32_bf16 v[80:83], v[188:191], v[164:167], v[80:83]
	v_mfma_f32_16x16x32_bf16 v[72:75], v[180:183], v[172:175], v[72:75]
	v_mfma_f32_16x16x32_bf16 v[68:71], v[188:191], v[172:175], v[68:71]
	v_mfma_f32_16x16x32_bf16 v[120:123], v[184:187], v[152:155], v[120:123]
	v_mfma_f32_16x16x32_bf16 v[116:119], v[202:205], v[152:155], v[116:119]
	v_mfma_f32_16x16x32_bf16 v[104:107], v[184:187], v[160:163], v[104:107]
	v_mfma_f32_16x16x32_bf16 v[96:99], v[202:205], v[160:163], v[96:99]
	v_mfma_f32_16x16x32_bf16 v[88:91], v[184:187], v[168:171], v[88:91]
	v_mfma_f32_16x16x32_bf16 v[80:83], v[202:205], v[168:171], v[80:83]
	v_mfma_f32_16x16x32_bf16 v[72:75], v[184:187], v[176:179], v[72:75]
	v_mfma_f32_16x16x32_bf16 v[68:71], v[202:205], v[176:179], v[68:71]
	s_barrier
	s_setprio 0
	ds_read_b128 v[148:151], v224 offset:16384
	ds_read_b128 v[152:155], v224 offset:17408
	ds_read_b128 v[156:159], v224 offset:18432
	ds_read_b128 v[160:163], v224 offset:19456
	ds_read_b128 v[164:167], v224 offset:20480
	ds_read_b128 v[168:171], v224 offset:21504
	ds_read_b128 v[172:175], v224 offset:22528
	ds_read_b128 v[176:179], v224 offset:23552
	s_add_i32 s6, s45, s28
	v_lshl_add_u64 v[206:207], s[18:19], 0, v[2:3]
	s_mov_b32 m0, s6
	s_nop 0
	global_load_lds_dwordx4 v[206:207], off
	v_lshl_add_u64 v[208:209], s[18:19], 0, v[192:193]
	s_add_i32 m0, s6, 0x2000
	s_nop 0
	global_load_lds_dwordx4 v[208:209], off
	s_mov_b32 m0, s29
	v_lshl_add_u64 v[210:211], s[20:21], 0, v[196:197]
	global_load_lds_dwordx4 v[210:211], off
	v_lshl_add_u64 v[212:213], s[20:21], 0, v[194:195]
	s_mov_b32 m0, s30
	s_nop 0
	global_load_lds_dwordx4 v[212:213], off
	s_add_u32 s6, s18, 0x160000
	s_addc_u32 s7, s19, 0
	s_add_i32 s45, s51, s28
	s_mov_b32 m0, s45
	s_nop 0
	global_load_lds_dwordx4 v2, s[6:7]
	s_add_i32 m0, s45, 0x2000
	s_nop 0
	global_load_lds_dwordx4 v192, s[6:7]
	s_waitcnt lgkmcnt(0)
	s_waitcnt vmcnt(6)
	s_setprio 1
	s_barrier
; #define PG8_STAGE(bufoff, gbase, voff) do { _Pragma("unroll") for (int _i = 0; _i < 2; ++_i) \
;         __builtin_amdgcn_global_load_lds((const unsigned*)((const char*)(gbase) + (voff)[_i]), (LAS unsigned*)(lds + (bufoff) + ldsw + _i * 8192), 16, 0, 0); } while (0)
; #define PG8_LDA(dst, b, h) do { _Pragma("unroll") for (int m = 0; m < 4; ++m) _Pragma("unroll") for (int k = 0; k < 2; ++k) dst[m][k] = *(const LAS bf16x8*)(lds + PG8_SA(b, h) + aoff + m * 2048 + k * 1024); } while (0)
; #define PG8_LDB(dst, b, h) do { _Pragma("unroll") for (int n = 0; n < 2; ++n) _Pragma("unroll") for (int k = 0; k < 2; ++k) dst[n][k] = *(const LAS bf16x8*)(lds + PG8_SB(b, h) + boff + n * 2048 + k * 1024); } while (0)
; #define PG8_MMA(ai, bj, At, Bt) do { __builtin_amdgcn_s_setprio(1); _Pragma("unroll") for (int m = 0; m < 4; ++m) _Pragma("unroll") for (int n = 0; n < 2; ++n) _Pragma("unroll") for (int k = 0; k < 2; ++k) \
;         acc[ai][bj][m][n] = __builtin_amdgcn_mfma_f32_16x16x32_bf16(Bt[n][k], At[m][k], acc[ai][bj][m][n], 0, 0, 0); __builtin_amdgcn_s_setprio(0); } while (0)
; #define PG8_WAIT_V(n) asm volatile("s_waitcnt vmcnt(" #n ")" ::: "memory")
; #define PG8_WAIT_L(n) asm volatile("s_waitcnt lgkmcnt(" #n ")" ::: "memory")
; #define PG8_BAR __builtin_amdgcn_s_barrier()
; #define PG8_SCHED __builtin_amdgcn_sched_barrier(0)
; template <class Epi, class Sched>
; __device__ __forceinline__ void gemm_phase(LAS unsigned char* lds, const Gemm g, const Sched& S, const Epi& E) {
;     ...
;             PG8_WAIT_V(6); PG8_BAR; PG8_MMA(1, 1, At, B1); PG8_BAR;
;             PG8_LDB(B0, 1, 0); PG8_SCHED; PG8_LDA(At, 1, 0); PG8_STAGE(PG8_SA(0, 1), a2 + hstepA, voffA);
;             PG8_WAIT_L(8); PG8_BAR; PG8_WAIT_L(0); PG8_MMA(0, 0, At, B0); PG8_BAR; PG8_SCHED;
;             PG8_LDB(B1, 1, 1); PG8_STAGE(PG8_SB(1, 0), b3, voffB);
;             PG8_BAR; PG8_WAIT_L(0); PG8_MMA(0, 1, At, B1); PG8_BAR;
;             PG8_LDA(At, 1, 1); PG8_STAGE(PG8_SA(1, 0), a3, voffA);
;             PG8_BAR; PG8_WAIT_L(0); PG8_MMA(1, 0, At, B0); PG8_BAR; PG8_SCHED;
	v_mfma_f32_16x16x32_bf16 v[64:67], v[132:135], v[148:151], v[64:67]
	v_mfma_f32_16x16x32_bf16 v[60:63], v[140:143], v[148:151], v[60:63]
	v_mfma_f32_16x16x32_bf16 v[52:55], v[132:135], v[156:159], v[52:55]
	v_mfma_f32_16x16x32_bf16 v[44:47], v[140:143], v[156:159], v[44:47]
	v_mfma_f32_16x16x32_bf16 v[36:39], v[132:135], v[164:167], v[36:39]
	v_mfma_f32_16x16x32_bf16 v[28:31], v[140:143], v[164:167], v[28:31]
	v_mfma_f32_16x16x32_bf16 v[20:23], v[132:135], v[172:175], v[20:23]
	v_mfma_f32_16x16x32_bf16 v[12:15], v[140:143], v[172:175], v[12:15]
	v_mfma_f32_16x16x32_bf16 v[64:67], v[136:139], v[152:155], v[64:67]
	v_mfma_f32_16x16x32_bf16 v[60:63], v[144:147], v[152:155], v[60:63]
	v_mfma_f32_16x16x32_bf16 v[52:55], v[136:139], v[160:163], v[52:55]
	v_mfma_f32_16x16x32_bf16 v[44:47], v[144:147], v[160:163], v[44:47]
	v_mfma_f32_16x16x32_bf16 v[36:39], v[136:139], v[168:171], v[36:39]
	v_mfma_f32_16x16x32_bf16 v[28:31], v[144:147], v[168:171], v[28:31]
	v_mfma_f32_16x16x32_bf16 v[20:23], v[136:139], v[176:179], v[20:23]
	v_mfma_f32_16x16x32_bf16 v[12:15], v[144:147], v[176:179], v[12:15]
	v_mfma_f32_16x16x32_bf16 v[56:59], v[180:183], v[148:151], v[56:59]
	v_mfma_f32_16x16x32_bf16 v[48:51], v[188:191], v[148:151], v[48:51]
	v_mfma_f32_16x16x32_bf16 v[40:43], v[180:183], v[156:159], v[40:43]
	v_mfma_f32_16x16x32_bf16 v[32:35], v[188:191], v[156:159], v[32:35]
	v_mfma_f32_16x16x32_bf16 v[24:27], v[180:183], v[164:167], v[24:27]
	v_mfma_f32_16x16x32_bf16 v[16:19], v[188:191], v[164:167], v[16:19]
	v_mfma_f32_16x16x32_bf16 v[8:11], v[180:183], v[172:175], v[8:11]
	v_mfma_f32_16x16x32_bf16 v[4:7], v[188:191], v[172:175], v[4:7]
	v_mfma_f32_16x16x32_bf16 v[56:59], v[184:187], v[152:155], v[56:59]
	v_mfma_f32_16x16x32_bf16 v[48:51], v[202:205], v[152:155], v[48:51]
	v_mfma_f32_16x16x32_bf16 v[40:43], v[184:187], v[160:163], v[40:43]
	v_mfma_f32_16x16x32_bf16 v[32:35], v[202:205], v[160:163], v[32:35]
	v_mfma_f32_16x16x32_bf16 v[24:27], v[184:187], v[168:171], v[24:27]
	v_mfma_f32_16x16x32_bf16 v[16:19], v[202:205], v[168:171], v[16:19]
	v_mfma_f32_16x16x32_bf16 v[8:11], v[184:187], v[176:179], v[8:11]
	v_mfma_f32_16x16x32_bf16 v[4:7], v[202:205], v[176:179], v[4:7]
	s_barrier
	s_setprio 0
	s_add_i32 s45, 0, 0x18000
	v_add_u32_e32 v144, s45, v1
	ds_read_b128 v[132:135], v144
	ds_read_b128 v[136:139], v144 offset:1024
	ds_read_b128 v[140:143], v144 offset:2048
	ds_read_b128 v[144:147], v144 offset:3072
	s_add_u32 s6, s20, 0x160000
	s_addc_u32 s7, s21, 0
	ds_read_b128 v[148:151], v224 offset:32768
	ds_read_b128 v[152:155], v224 offset:33792
	ds_read_b128 v[156:159], v224 offset:34816
	ds_read_b128 v[160:163], v224 offset:35840
	ds_read_b128 v[164:167], v224 offset:36864
	ds_read_b128 v[168:171], v224 offset:37888
	ds_read_b128 v[172:175], v224 offset:38912
	ds_read_b128 v[176:179], v224 offset:39936
	s_mov_b32 m0, s31
	s_nop 0
	global_load_lds_dwordx4 v196, s[6:7]
	s_mov_b32 m0, s35
	s_nop 0
	global_load_lds_dwordx4 v194, s[6:7]
	s_add_i32 s20, 0, 0x1c000
	v_add_u32_e32 v202, s20, v1
	ds_read_b128 v[180:183], v202
	ds_read_b128 v[184:187], v202 offset:1024
	ds_read_b128 v[188:191], v202 offset:2048
	ds_read_b128 v[202:205], v202 offset:3072
	s_waitcnt lgkmcnt(0)
	s_setprio 1
	s_barrier
	v_mfma_f32_16x16x32_bf16 v[128:131], v[132:135], v[148:151], v[128:131]
	v_mfma_f32_16x16x32_bf16 v[124:127], v[140:143], v[148:151], v[124:127]
	v_mfma_f32_16x16x32_bf16 v[112:115], v[132:135], v[156:159], v[112:115]
	v_mfma_f32_16x16x32_bf16 v[108:111], v[140:143], v[156:159], v[108:111]
	v_mfma_f32_16x16x32_bf16 v[100:103], v[132:135], v[164:167], v[100:103]
	v_mfma_f32_16x16x32_bf16 v[92:95], v[140:143], v[164:167], v[92:95]
	v_mfma_f32_16x16x32_bf16 v[84:87], v[132:135], v[172:175], v[84:87]
	v_mfma_f32_16x16x32_bf16 v[76:79], v[140:143], v[172:175], v[76:79]
	v_mfma_f32_16x16x32_bf16 v[128:131], v[136:139], v[152:155], v[128:131]
	v_mfma_f32_16x16x32_bf16 v[124:127], v[144:147], v[152:155], v[124:127]
	v_mfma_f32_16x16x32_bf16 v[112:115], v[136:139], v[160:163], v[112:115]
	v_mfma_f32_16x16x32_bf16 v[108:111], v[144:147], v[160:163], v[108:111]
	v_mfma_f32_16x16x32_bf16 v[100:103], v[136:139], v[168:171], v[100:103]
	v_mfma_f32_16x16x32_bf16 v[92:95], v[144:147], v[168:171], v[92:95]
	v_mfma_f32_16x16x32_bf16 v[84:87], v[136:139], v[176:179], v[84:87]
	v_mfma_f32_16x16x32_bf16 v[76:79], v[144:147], v[176:179], v[76:79]
	v_mfma_f32_16x16x32_bf16 v[120:123], v[180:183], v[148:151], v[120:123]
	v_mfma_f32_16x16x32_bf16 v[116:119], v[188:191], v[148:151], v[116:119]
	v_mfma_f32_16x16x32_bf16 v[104:107], v[180:183], v[156:159], v[104:107]
	v_mfma_f32_16x16x32_bf16 v[96:99], v[188:191], v[156:159], v[96:99]
	v_mfma_f32_16x16x32_bf16 v[88:91], v[180:183], v[164:167], v[88:91]
	v_mfma_f32_16x16x32_bf16 v[80:83], v[188:191], v[164:167], v[80:83]
	v_mfma_f32_16x16x32_bf16 v[72:75], v[180:183], v[172:175], v[72:75]
	v_mfma_f32_16x16x32_bf16 v[68:71], v[188:191], v[172:175], v[68:71]
	v_mfma_f32_16x16x32_bf16 v[120:123], v[184:187], v[152:155], v[120:123]
	v_mfma_f32_16x16x32_bf16 v[116:119], v[202:205], v[152:155], v[116:119]
	v_mfma_f32_16x16x32_bf16 v[104:107], v[184:187], v[160:163], v[104:107]
	v_mfma_f32_16x16x32_bf16 v[96:99], v[202:205], v[160:163], v[96:99]
	v_mfma_f32_16x16x32_bf16 v[88:91], v[184:187], v[168:171], v[88:91]
	v_mfma_f32_16x16x32_bf16 v[80:83], v[202:205], v[168:171], v[80:83]
	v_mfma_f32_16x16x32_bf16 v[72:75], v[184:187], v[176:179], v[72:75]
	v_mfma_f32_16x16x32_bf16 v[68:71], v[202:205], v[176:179], v[68:71]
	s_barrier
; __device__ __forceinline__ int opaque_tid() { int t = threadIdx.x; asm volatile("" : "+v"(t)); return t; }
; #define PG8_STAGE(bufoff, gbase, voff) do { _Pragma("unroll") for (int _i = 0; _i < 2; ++_i) \
;         __builtin_amdgcn_global_load_lds((const unsigned*)((const char*)(gbase) + (voff)[_i]), (LAS unsigned*)(lds + (bufoff) + ldsw + _i * 8192), 16, 0, 0); } while (0)
; #define PG8_LDA(dst, b, h) do { _Pragma("unroll") for (int m = 0; m < 4; ++m) _Pragma("unroll") for (int k = 0; k < 2; ++k) dst[m][k] = *(const LAS bf16x8*)(lds + PG8_SA(b, h) + aoff + m * 2048 + k * 1024); } while (0)
; #define PG8_MMA(ai, bj, At, Bt) do { __builtin_amdgcn_s_setprio(1); _Pragma("unroll") for (int m = 0; m < 4; ++m) _Pragma("unroll") for (int n = 0; n < 2; ++n) _Pragma("unroll") for (int k = 0; k < 2; ++k) \
;         acc[ai][bj][m][n] = __builtin_amdgcn_mfma_f32_16x16x32_bf16(Bt[n][k], At[m][k], acc[ai][bj][m][n], 0, 0, 0); __builtin_amdgcn_s_setprio(0); } while (0)
; #define PG8_WAIT_V(n) asm volatile("s_waitcnt vmcnt(" #n ")" ::: "memory")
; #define PG8_WAIT_L(n) asm volatile("s_waitcnt lgkmcnt(" #n ")" ::: "memory")
; #define PG8_BAR __builtin_amdgcn_s_barrier()
; #define PG8_SCHED __builtin_amdgcn_sched_barrier(0)
;     __device__ __forceinline__ void operator()(const f32x4 (&acc)[2][2][4][2], const Unit& u, int wr, int wc, int, int) const {
;         const int ol_ = opaque_tid() & 63, fr = ol_ & 15, fq = ol_ >> 4;
;         const int row0 = u.pm * BM + wr * 64 + fr, col0 = u.pn * BM + wc * 32 + 8 * fq;
;         u32x4 cin[2][4][2];
; #pragma unroll
;         for (int ai = 0; ai < 2; ++ai)
; #pragma unroll
;             for (int m = 0; m < 4; ++m)
; #pragma unroll
;                 for (int bj = 0; bj < 2; ++bj) cin[ai][m][bj] = *(const u32x4*)(C + (size_t)(row0 + ai * HALF + m * 16) * ldc + col0 + bj * HALF);
; template <class Epi, class Sched>
; __device__ __forceinline__ void gemm_phase(LAS unsigned char* lds, const Gemm g, const Sched& S, const Epi& E) {
;     ...
;             PG8_LDA(At, 1, 1); PG8_STAGE(PG8_SA(1, 0), a3, voffA);
;             PG8_BAR; PG8_WAIT_L(0); PG8_MMA(1, 0, At, B0); PG8_BAR; PG8_SCHED;
;             PG8_STAGE(PG8_SB(1, 1), b3 + hstepB, voffB);
;             PG8_WAIT_V(6); PG8_BAR; PG8_MMA(1, 1, At, B1); PG8_BAR;
;         }
;         E(acc, cur, wr, wc, ui, fq);
;         S.done(cur);
;         if (!has_next) break;
	s_setprio 0
	ds_read_b128 v[148:151], v224 offset:49152
	ds_read_b128 v[152:155], v224 offset:50176
	ds_read_b128 v[156:159], v224 offset:51200
	ds_read_b128 v[160:163], v224 offset:52224
	ds_read_b128 v[164:167], v224 offset:53248
	ds_read_b128 v[168:171], v224 offset:54272
	ds_read_b128 v[172:175], v224 offset:55296
	ds_read_b128 v[176:179], v224 offset:56320
	s_add_i32 s6, s45, s28
	v_lshl_add_u64 v[206:207], v[206:207], 0, s[8:9]
	s_mov_b32 m0, s6
	s_nop 0
	global_load_lds_dwordx4 v[206:207], off
	v_lshl_add_u64 v[206:207], v[208:209], 0, s[8:9]
	s_add_i32 m0, s6, 0x2000
	s_nop 0
	global_load_lds_dwordx4 v[206:207], off
	s_mov_b32 m0, s38
	v_lshl_add_u64 v[206:207], v[210:211], 0, s[8:9]
	global_load_lds_dwordx4 v[206:207], off
	v_lshl_add_u64 v[206:207], v[212:213], 0, s[8:9]
	s_mov_b32 m0, s39
	s_nop 0
	global_load_lds_dwordx4 v[206:207], off
	s_add_u32 s6, s18, 0x160080
	s_addc_u32 s7, s19, 0
	s_add_i32 s18, s20, s28
	s_mov_b32 m0, s18
	s_nop 0
	global_load_lds_dwordx4 v2, s[6:7]
	s_add_i32 m0, s18, 0x2000
	s_nop 0
	global_load_lds_dwordx4 v192, s[6:7]
	s_add_i32 s44, s44, 2
	s_add_u32 s42, s42, 0x100
	s_addc_u32 s43, s43, 0
	s_cmpk_gt_u32 s44, 0x55
	s_mov_b64 s[6:7], s[14:15]
	s_waitcnt lgkmcnt(0)
	s_waitcnt vmcnt(6)
	s_setprio 1
	s_barrier
	v_mfma_f32_16x16x32_bf16 v[64:67], v[132:135], v[148:151], v[64:67]
	v_mfma_f32_16x16x32_bf16 v[60:63], v[140:143], v[148:151], v[60:63]
	v_mfma_f32_16x16x32_bf16 v[52:55], v[132:135], v[156:159], v[52:55]
	v_mfma_f32_16x16x32_bf16 v[44:47], v[140:143], v[156:159], v[44:47]
	v_mfma_f32_16x16x32_bf16 v[36:39], v[132:135], v[164:167], v[36:39]
	v_mfma_f32_16x16x32_bf16 v[28:31], v[140:143], v[164:167], v[28:31]
	v_mfma_f32_16x16x32_bf16 v[20:23], v[132:135], v[172:175], v[20:23]
	v_mfma_f32_16x16x32_bf16 v[12:15], v[140:143], v[172:175], v[12:15]
	v_mfma_f32_16x16x32_bf16 v[64:67], v[136:139], v[152:155], v[64:67]
	v_mfma_f32_16x16x32_bf16 v[60:63], v[144:147], v[152:155], v[60:63]
	v_mfma_f32_16x16x32_bf16 v[52:55], v[136:139], v[160:163], v[52:55]
	v_mfma_f32_16x16x32_bf16 v[44:47], v[144:147], v[160:163], v[44:47]
	v_mfma_f32_16x16x32_bf16 v[36:39], v[136:139], v[168:171], v[36:39]
	v_mfma_f32_16x16x32_bf16 v[28:31], v[144:147], v[168:171], v[28:31]
	v_mfma_f32_16x16x32_bf16 v[20:23], v[136:139], v[176:179], v[20:23]
	v_mfma_f32_16x16x32_bf16 v[12:15], v[144:147], v[176:179], v[12:15]
	v_mfma_f32_16x16x32_bf16 v[56:59], v[180:183], v[148:151], v[56:59]
	v_mfma_f32_16x16x32_bf16 v[48:51], v[188:191], v[148:151], v[48:51]
	v_mfma_f32_16x16x32_bf16 v[40:43], v[180:183], v[156:159], v[40:43]
	v_mfma_f32_16x16x32_bf16 v[32:35], v[188:191], v[156:159], v[32:35]
	v_mfma_f32_16x16x32_bf16 v[24:27], v[180:183], v[164:167], v[24:27]
	v_mfma_f32_16x16x32_bf16 v[16:19], v[188:191], v[164:167], v[16:19]
	v_mfma_f32_16x16x32_bf16 v[8:11], v[180:183], v[172:175], v[8:11]
	v_mfma_f32_16x16x32_bf16 v[4:7], v[188:191], v[172:175], v[4:7]
	v_mfma_f32_16x16x32_bf16 v[56:59], v[184:187], v[152:155], v[56:59]
	v_mfma_f32_16x16x32_bf16 v[48:51], v[202:205], v[152:155], v[48:51]
	v_mfma_f32_16x16x32_bf16 v[40:43], v[184:187], v[160:163], v[40:43]
	v_mfma_f32_16x16x32_bf16 v[32:35], v[202:205], v[160:163], v[32:35]
	v_mfma_f32_16x16x32_bf16 v[24:27], v[184:187], v[168:171], v[24:27]
	v_mfma_f32_16x16x32_bf16 v[16:19], v[202:205], v[168:171], v[16:19]
	v_mfma_f32_16x16x32_bf16 v[8:11], v[184:187], v[176:179], v[8:11]
	v_mfma_f32_16x16x32_bf16 v[4:7], v[202:205], v[176:179], v[4:7]
	s_barrier
	s_cbranch_scc0 .LBB0_1666
	s_setprio 0
	v_mov_b32_e32 v133, v0
	s_lshl_b32 s6, s50, 8
	s_add_i32 s6, s6, s36
	v_and_or_b32 v132, v133, 15, s6
	s_lshl_b32 s6, s49, 8
	v_lshrrev_b32_e32 v133, 1, v133
	v_and_or_b32 v133, v133, 24, s6
	v_or_b32_e32 v134, s37, v133
	v_ashrrev_i32_e32 v135, 31, v134
	v_lshlrev_b64 v[202:203], 1, v[134:135]
	v_ashrrev_i32_e32 v133, 31, v132
	v_lshl_add_u64 v[134:135], s[88:89], 0, v[202:203]
	v_lshlrev_b64 v[226:227], 12, v[132:133]
	v_lshl_add_u64 v[136:137], v[134:135], 0, v[226:227]
	global_load_dwordx4 v[216:219], v[136:137], off
	global_load_dwordx4 v[188:191], v[136:137], off offset:256
	v_or_b32_e32 v136, 16, v132
	v_ashrrev_i32_e32 v137, 31, v136
	v_lshlrev_b64 v[222:223], 12, v[136:137]
	v_lshl_add_u64 v[136:137], v[134:135], 0, v[222:223]
	global_load_dwordx4 v[184:187], v[136:137], off
	global_load_dwordx4 v[180:183], v[136:137], off offset:256
	v_or_b32_e32 v136, 32, v132
	v_ashrrev_i32_e32 v137, 31, v136
	v_lshlrev_b64 v[220:221], 12, v[136:137]
	v_lshl_add_u64 v[136:137], v[134:135], 0, v[220:221]
	global_load_dwordx4 v[176:179], v[136:137], off
	global_load_dwordx4 v[168:171], v[136:137], off offset:256
	v_or_b32_e32 v132, 48, v132
	v_ashrrev_i32_e32 v133, 31, v132
	v_lshlrev_b64 v[212:213], 12, v[132:133]
	v_lshl_add_u64 v[132:133], v[134:135], 0, v[212:213]
	global_load_dwordx4 v[172:175], v[132:133], off
	global_load_dwordx4 v[164:167], v[132:133], off offset:256
	s_mov_b64 s[6:7], 0x80000
	v_lshl_add_u64 v[210:211], v[226:227], 0, s[6:7]
	v_lshl_add_u64 v[132:133], v[134:135], 0, v[210:211]
	global_load_dwordx4 v[160:163], v[132:133], off
	global_load_dwordx4 v[156:159], v[132:133], off offset:256
	s_mov_b64 s[6:7], 0x90000
	v_lshl_add_u64 v[208:209], v[226:227], 0, s[6:7]
	v_lshl_add_u64 v[132:133], v[134:135], 0, v[208:209]
	global_load_dwordx4 v[152:155], v[132:133], off
	global_load_dwordx4 v[148:151], v[132:133], off offset:256
	s_mov_b64 s[6:7], 0xa0000
	v_lshl_add_u64 v[206:207], v[226:227], 0, s[6:7]
	v_lshl_add_u64 v[132:133], v[134:135], 0, v[206:207]
	global_load_dwordx4 v[144:147], v[132:133], off
	global_load_dwordx4 v[140:143], v[132:133], off offset:256
	s_mov_b64 s[6:7], 0xb0000
	v_lshl_add_u64 v[204:205], v[226:227], 0, s[6:7]
	v_lshl_add_u64 v[132:133], v[134:135], 0, v[204:205]
	global_load_dwordx4 v[136:139], v[132:133], off
	s_nop 0
	global_load_dwordx4 v[132:135], v[132:133], off offset:256
	s_and_b64 vcc, exec, s[40:41]
	s_mov_b32 s49, s47
	s_mov_b32 s50, s48
	s_mov_b64 s[14:15], s[4:5]
	s_mov_b64 s[6:7], s[0:1]
	s_waitcnt vmcnt(15)
; __device__ __forceinline__ unsigned cvt_pk_bf16(float lo, float hi) { const f32x2 v = {lo, hi}; const bf16v2_ r = __builtin_convertvector(v, bf16v2_); return __builtin_bit_cast(unsigned, r); }
; __device__ __forceinline__ float bflo(unsigned w) { return __uint_as_float(w << 16); }
; __device__ __forceinline__ float bfhi(unsigned w) { return __uint_as_float(w & 0xffff0000u); }
;     __device__ __forceinline__ void operator()(const f32x4 (&acc)[2][2][4][2], const Unit& u, int wr, int wc, int, int) const {
;     ...
;         for (int ai = 0; ai < 2; ++ai)
; #pragma unroll
;             for (int m = 0; m < 4; ++m)
; #pragma unroll
;                 for (int bj = 0; bj < 2; ++bj) { const u32x4 c = cin[ai][m][bj]; const f32x4 v0 = acc[ai][bj][m][0], v1 = acc[ai][bj][m][1];
;                     u32x4 w; w.x = cvt_pk_bf16(bflo(c.x) + v0[0], bfhi(c.x) + v0[1]); w.y = cvt_pk_bf16(bflo(c.y) + v0[2], bfhi(c.y) + v0[3]);
;                     w.z = cvt_pk_bf16(bflo(c.z) + v1[0], bfhi(c.z) + v1[1]); w.w = cvt_pk_bf16(bflo(c.w) + v1[2], bfhi(c.w) + v1[3]);
;                     *(u32x4*)(C + (size_t)(row0 + ai * HALF + m * 16) * ldc + col0 + bj * HALF) = w; }
	v_lshlrev_b32_e32 v228, 16, v216
	v_and_b32_e32 v229, 0xffff0000, v216
	v_lshlrev_b32_e32 v216, 16, v217
	v_and_b32_e32 v217, 0xffff0000, v217
	v_pk_add_f32 v[128:129], v[128:129], v[228:229]
	v_pk_add_f32 v[130:131], v[130:131], v[216:217]
	v_cvt_pk_bf16_f32 v128, v128, v129
	v_cvt_pk_bf16_f32 v129, v130, v131
	v_lshlrev_b32_e32 v130, 16, v218
	v_and_b32_e32 v131, 0xffff0000, v218
	v_pk_add_f32 v[124:125], v[124:125], v[130:131]
	s_nop 0
	v_cvt_pk_bf16_f32 v130, v124, v125
	v_lshlrev_b32_e32 v124, 16, v219
	v_and_b32_e32 v125, 0xffff0000, v219
	v_pk_add_f32 v[124:125], v[126:127], v[124:125]
	s_waitcnt vmcnt(14)
	v_lshlrev_b32_e32 v126, 16, v188
	v_and_b32_e32 v127, 0xffff0000, v188
	v_pk_add_f32 v[120:121], v[120:121], v[126:127]
	v_lshlrev_b32_e32 v126, 16, v189
	v_and_b32_e32 v127, 0xffff0000, v189
	v_pk_add_f32 v[122:123], v[122:123], v[126:127]
	v_cvt_pk_bf16_f32 v120, v120, v121
	v_cvt_pk_bf16_f32 v121, v122, v123
	v_lshlrev_b32_e32 v122, 16, v190
	v_and_b32_e32 v123, 0xffff0000, v190
	v_pk_add_f32 v[116:117], v[116:117], v[122:123]
	v_cvt_pk_bf16_f32 v131, v124, v125
	v_cvt_pk_bf16_f32 v122, v116, v117
	v_lshlrev_b32_e32 v116, 16, v191
	v_and_b32_e32 v117, 0xffff0000, v191
	v_pk_add_f32 v[116:117], v[118:119], v[116:117]
	v_lshl_add_u64 v[124:125], s[88:89], 0, v[226:227]
	v_cvt_pk_bf16_f32 v123, v116, v117
	s_waitcnt vmcnt(13)
	v_lshlrev_b32_e32 v116, 16, v184
	v_and_b32_e32 v117, 0xffff0000, v184
	v_pk_add_f32 v[112:113], v[112:113], v[116:117]
	v_lshlrev_b32_e32 v116, 16, v185
	v_and_b32_e32 v117, 0xffff0000, v185
	v_pk_add_f32 v[114:115], v[114:115], v[116:117]
	v_cvt_pk_bf16_f32 v112, v112, v113
	v_cvt_pk_bf16_f32 v113, v114, v115
	v_lshlrev_b32_e32 v114, 16, v186
	v_and_b32_e32 v115, 0xffff0000, v186
	v_pk_add_f32 v[108:109], v[108:109], v[114:115]
	v_lshl_add_u64 v[124:125], v[124:125], 0, v[202:203]
	v_cvt_pk_bf16_f32 v114, v108, v109
	v_lshlrev_b32_e32 v108, 16, v187
	v_and_b32_e32 v109, 0xffff0000, v187
	v_pk_add_f32 v[108:109], v[110:111], v[108:109]
	s_waitcnt vmcnt(12)
	v_lshlrev_b32_e32 v110, 16, v180
	v_and_b32_e32 v111, 0xffff0000, v180
	v_pk_add_f32 v[104:105], v[104:105], v[110:111]
	v_lshlrev_b32_e32 v110, 16, v181
	v_and_b32_e32 v111, 0xffff0000, v181
	v_pk_add_f32 v[106:107], v[106:107], v[110:111]
	v_cvt_pk_bf16_f32 v104, v104, v105
	v_cvt_pk_bf16_f32 v105, v106, v107
	v_lshlrev_b32_e32 v106, 16, v182
	v_and_b32_e32 v107, 0xffff0000, v182
	v_pk_add_f32 v[96:97], v[96:97], v[106:107]
	v_cvt_pk_bf16_f32 v115, v108, v109
	v_cvt_pk_bf16_f32 v106, v96, v97
	v_lshlrev_b32_e32 v96, 16, v183
	v_and_b32_e32 v97, 0xffff0000, v183
	v_pk_add_f32 v[96:97], v[98:99], v[96:97]
	s_waitcnt vmcnt(11)
	v_lshlrev_b32_e32 v98, 16, v177
	v_cvt_pk_bf16_f32 v107, v96, v97
	v_lshlrev_b32_e32 v96, 16, v176
	v_and_b32_e32 v97, 0xffff0000, v176
	v_and_b32_e32 v99, 0xffff0000, v177
	v_pk_add_f32 v[96:97], v[100:101], v[96:97]
	v_pk_add_f32 v[98:99], v[102:103], v[98:99]
	v_cvt_pk_bf16_f32 v96, v96, v97
	v_cvt_pk_bf16_f32 v97, v98, v99
	v_lshlrev_b32_e32 v98, 16, v178
	v_and_b32_e32 v99, 0xffff0000, v178
	v_pk_add_f32 v[92:93], v[92:93], v[98:99]
	v_lshl_add_u64 v[108:109], s[88:89], 0, v[222:223]
	v_cvt_pk_bf16_f32 v98, v92, v93
	v_lshlrev_b32_e32 v92, 16, v179
	v_and_b32_e32 v93, 0xffff0000, v179
	v_pk_add_f32 v[92:93], v[94:95], v[92:93]
	s_waitcnt vmcnt(10)
	v_lshlrev_b32_e32 v94, 16, v168
	v_and_b32_e32 v95, 0xffff0000, v168
	v_pk_add_f32 v[88:89], v[88:89], v[94:95]
	v_lshlrev_b32_e32 v94, 16, v169
	v_and_b32_e32 v95, 0xffff0000, v169
	v_pk_add_f32 v[90:91], v[90:91], v[94:95]
	v_cvt_pk_bf16_f32 v88, v88, v89
	v_cvt_pk_bf16_f32 v89, v90, v91
	v_lshlrev_b32_e32 v90, 16, v170
	v_and_b32_e32 v91, 0xffff0000, v170
	v_pk_add_f32 v[80:81], v[80:81], v[90:91]
	v_cvt_pk_bf16_f32 v99, v92, v93
	v_cvt_pk_bf16_f32 v90, v80, v81
	v_lshlrev_b32_e32 v80, 16, v171
	v_and_b32_e32 v81, 0xffff0000, v171
	v_pk_add_f32 v[80:81], v[82:83], v[80:81]
	s_waitcnt vmcnt(9)
	v_lshlrev_b32_e32 v82, 16, v173
	v_cvt_pk_bf16_f32 v91, v80, v81
	v_lshlrev_b32_e32 v80, 16, v172
	v_and_b32_e32 v81, 0xffff0000, v172
	v_and_b32_e32 v83, 0xffff0000, v173
	v_pk_add_f32 v[80:81], v[84:85], v[80:81]
	v_pk_add_f32 v[82:83], v[86:87], v[82:83]
	v_cvt_pk_bf16_f32 v80, v80, v81
	v_cvt_pk_bf16_f32 v81, v82, v83
	v_lshlrev_b32_e32 v82, 16, v174
	v_and_b32_e32 v83, 0xffff0000, v174
	v_pk_add_f32 v[76:77], v[76:77], v[82:83]
	v_lshl_add_u64 v[92:93], s[88:89], 0, v[220:221]
	v_cvt_pk_bf16_f32 v82, v76, v77
	v_lshlrev_b32_e32 v76, 16, v175
	v_and_b32_e32 v77, 0xffff0000, v175
	v_pk_add_f32 v[76:77], v[78:79], v[76:77]
	s_waitcnt vmcnt(8)
	v_lshlrev_b32_e32 v78, 16, v164
	v_and_b32_e32 v79, 0xffff0000, v164
	v_pk_add_f32 v[72:73], v[72:73], v[78:79]
	v_lshlrev_b32_e32 v78, 16, v165
	v_and_b32_e32 v79, 0xffff0000, v165
	v_pk_add_f32 v[74:75], v[74:75], v[78:79]
	v_cvt_pk_bf16_f32 v72, v72, v73
	v_cvt_pk_bf16_f32 v73, v74, v75
	v_lshlrev_b32_e32 v74, 16, v166
	v_and_b32_e32 v75, 0xffff0000, v166
	v_pk_add_f32 v[68:69], v[68:69], v[74:75]
	v_cvt_pk_bf16_f32 v83, v76, v77
	v_cvt_pk_bf16_f32 v74, v68, v69
	v_lshlrev_b32_e32 v68, 16, v167
	v_and_b32_e32 v69, 0xffff0000, v167
	v_pk_add_f32 v[68:69], v[70:71], v[68:69]
	v_lshl_add_u64 v[76:77], s[88:89], 0, v[212:213]
	v_cvt_pk_bf16_f32 v75, v68, v69
	s_waitcnt vmcnt(7)
	v_lshlrev_b32_e32 v68, 16, v160
	v_and_b32_e32 v69, 0xffff0000, v160
	v_pk_add_f32 v[64:65], v[64:65], v[68:69]
	v_lshlrev_b32_e32 v68, 16, v161
	v_and_b32_e32 v69, 0xffff0000, v161
	v_pk_add_f32 v[66:67], v[66:67], v[68:69]
	v_cvt_pk_bf16_f32 v64, v64, v65
	v_cvt_pk_bf16_f32 v65, v66, v67
	v_lshlrev_b32_e32 v66, 16, v162
	v_and_b32_e32 v67, 0xffff0000, v162
	v_pk_add_f32 v[60:61], v[60:61], v[66:67]
	v_lshl_add_u64 v[108:109], v[108:109], 0, v[202:203]
	v_cvt_pk_bf16_f32 v66, v60, v61
	v_lshlrev_b32_e32 v60, 16, v163
	v_and_b32_e32 v61, 0xffff0000, v163
	v_pk_add_f32 v[60:61], v[62:63], v[60:61]
	s_waitcnt vmcnt(6)
; __device__ __forceinline__ unsigned cvt_pk_bf16(float lo, float hi) { const f32x2 v = {lo, hi}; const bf16v2_ r = __builtin_convertvector(v, bf16v2_); return __builtin_bit_cast(unsigned, r); }
; __device__ __forceinline__ float bflo(unsigned w) { return __uint_as_float(w << 16); }
; __device__ __forceinline__ float bfhi(unsigned w) { return __uint_as_float(w & 0xffff0000u); }
;     __device__ __forceinline__ void operator()(const f32x4 (&acc)[2][2][4][2], const Unit& u, int wr, int wc, int, int) const {
;     ...
;         for (int ai = 0; ai < 2; ++ai)
; #pragma unroll
;             for (int m = 0; m < 4; ++m)
; #pragma unroll
;                 for (int bj = 0; bj < 2; ++bj) { const u32x4 c = cin[ai][m][bj]; const f32x4 v0 = acc[ai][bj][m][0], v1 = acc[ai][bj][m][1];
;                     u32x4 w; w.x = cvt_pk_bf16(bflo(c.x) + v0[0], bfhi(c.x) + v0[1]); w.y = cvt_pk_bf16(bflo(c.y) + v0[2], bfhi(c.y) + v0[3]);
;                     w.z = cvt_pk_bf16(bflo(c.z) + v1[0], bfhi(c.z) + v1[1]); w.w = cvt_pk_bf16(bflo(c.w) + v1[2], bfhi(c.w) + v1[3]);
;                     *(u32x4*)(C + (size_t)(row0 + ai * HALF + m * 16) * ldc + col0 + bj * HALF) = w; }
	v_lshlrev_b32_e32 v62, 16, v156
	v_and_b32_e32 v63, 0xffff0000, v156
	v_pk_add_f32 v[56:57], v[56:57], v[62:63]
	v_lshlrev_b32_e32 v62, 16, v157
	v_and_b32_e32 v63, 0xffff0000, v157
	v_pk_add_f32 v[58:59], v[58:59], v[62:63]
	v_cvt_pk_bf16_f32 v56, v56, v57
	v_cvt_pk_bf16_f32 v57, v58, v59
	v_lshlrev_b32_e32 v58, 16, v158
	v_and_b32_e32 v59, 0xffff0000, v158
	v_pk_add_f32 v[48:49], v[48:49], v[58:59]
	v_cvt_pk_bf16_f32 v67, v60, v61
	v_cvt_pk_bf16_f32 v58, v48, v49
	v_lshlrev_b32_e32 v48, 16, v159
	v_and_b32_e32 v49, 0xffff0000, v159
	v_pk_add_f32 v[48:49], v[50:51], v[48:49]
	s_waitcnt vmcnt(5)
	v_lshlrev_b32_e32 v50, 16, v153
	v_cvt_pk_bf16_f32 v59, v48, v49
	v_lshlrev_b32_e32 v48, 16, v152
	v_and_b32_e32 v49, 0xffff0000, v152
	v_and_b32_e32 v51, 0xffff0000, v153
	v_pk_add_f32 v[48:49], v[52:53], v[48:49]
	v_pk_add_f32 v[50:51], v[54:55], v[50:51]
	v_cvt_pk_bf16_f32 v48, v48, v49
	v_cvt_pk_bf16_f32 v49, v50, v51
	v_lshlrev_b32_e32 v50, 16, v154
	v_and_b32_e32 v51, 0xffff0000, v154
	v_pk_add_f32 v[44:45], v[44:45], v[50:51]
	v_lshl_add_u64 v[60:61], s[88:89], 0, v[210:211]
	v_cvt_pk_bf16_f32 v50, v44, v45
	v_lshlrev_b32_e32 v44, 16, v155
	v_and_b32_e32 v45, 0xffff0000, v155
	v_pk_add_f32 v[44:45], v[46:47], v[44:45]
	s_waitcnt vmcnt(4)
	v_lshlrev_b32_e32 v46, 16, v148
	v_and_b32_e32 v47, 0xffff0000, v148
	v_pk_add_f32 v[40:41], v[40:41], v[46:47]
	v_lshlrev_b32_e32 v46, 16, v149
	v_and_b32_e32 v47, 0xffff0000, v149
	v_pk_add_f32 v[42:43], v[42:43], v[46:47]
	v_cvt_pk_bf16_f32 v40, v40, v41
	v_cvt_pk_bf16_f32 v41, v42, v43
	v_lshlrev_b32_e32 v42, 16, v150
	v_and_b32_e32 v43, 0xffff0000, v150
	v_pk_add_f32 v[32:33], v[32:33], v[42:43]
	v_cvt_pk_bf16_f32 v51, v44, v45
	v_cvt_pk_bf16_f32 v42, v32, v33
	v_lshlrev_b32_e32 v32, 16, v151
	v_and_b32_e32 v33, 0xffff0000, v151
	v_pk_add_f32 v[32:33], v[34:35], v[32:33]
	s_waitcnt vmcnt(3)
	v_lshlrev_b32_e32 v34, 16, v145
	v_cvt_pk_bf16_f32 v43, v32, v33
	v_lshlrev_b32_e32 v32, 16, v144
	v_and_b32_e32 v33, 0xffff0000, v144
	v_and_b32_e32 v35, 0xffff0000, v145
	v_pk_add_f32 v[32:33], v[36:37], v[32:33]
	v_pk_add_f32 v[34:35], v[38:39], v[34:35]
	v_cvt_pk_bf16_f32 v32, v32, v33
	v_cvt_pk_bf16_f32 v33, v34, v35
	v_lshlrev_b32_e32 v34, 16, v146
	v_and_b32_e32 v35, 0xffff0000, v146
	v_pk_add_f32 v[28:29], v[28:29], v[34:35]
	v_lshl_add_u64 v[44:45], s[88:89], 0, v[208:209]
	v_cvt_pk_bf16_f32 v34, v28, v29
	v_lshlrev_b32_e32 v28, 16, v147
	v_and_b32_e32 v29, 0xffff0000, v147
	v_pk_add_f32 v[28:29], v[30:31], v[28:29]
	s_waitcnt vmcnt(2)
	v_lshlrev_b32_e32 v30, 16, v140
	v_and_b32_e32 v31, 0xffff0000, v140
	v_pk_add_f32 v[24:25], v[24:25], v[30:31]
	v_lshlrev_b32_e32 v30, 16, v141
	v_and_b32_e32 v31, 0xffff0000, v141
	v_pk_add_f32 v[26:27], v[26:27], v[30:31]
	v_cvt_pk_bf16_f32 v24, v24, v25
	v_cvt_pk_bf16_f32 v25, v26, v27
	v_lshlrev_b32_e32 v26, 16, v142
	v_and_b32_e32 v27, 0xffff0000, v142
	v_pk_add_f32 v[16:17], v[16:17], v[26:27]
	v_cvt_pk_bf16_f32 v35, v28, v29
	v_cvt_pk_bf16_f32 v26, v16, v17
	v_lshlrev_b32_e32 v16, 16, v143
	v_and_b32_e32 v17, 0xffff0000, v143
	v_pk_add_f32 v[16:17], v[18:19], v[16:17]
	s_waitcnt vmcnt(1)
	v_lshlrev_b32_e32 v18, 16, v137
	v_cvt_pk_bf16_f32 v27, v16, v17
	v_lshlrev_b32_e32 v16, 16, v136
	v_and_b32_e32 v17, 0xffff0000, v136
	v_and_b32_e32 v19, 0xffff0000, v137
	v_pk_add_f32 v[16:17], v[20:21], v[16:17]
	v_pk_add_f32 v[18:19], v[22:23], v[18:19]
	v_cvt_pk_bf16_f32 v16, v16, v17
	v_cvt_pk_bf16_f32 v17, v18, v19
	v_lshlrev_b32_e32 v18, 16, v138
	v_and_b32_e32 v19, 0xffff0000, v138
	v_pk_add_f32 v[12:13], v[12:13], v[18:19]
	v_lshl_add_u64 v[28:29], s[88:89], 0, v[206:207]
	v_cvt_pk_bf16_f32 v18, v12, v13
	v_lshlrev_b32_e32 v12, 16, v139
	v_and_b32_e32 v13, 0xffff0000, v139
	v_pk_add_f32 v[12:13], v[14:15], v[12:13]
	s_waitcnt vmcnt(0)
; __device__ __forceinline__ unsigned cvt_pk_bf16(float lo, float hi) { const f32x2 v = {lo, hi}; const bf16v2_ r = __builtin_convertvector(v, bf16v2_); return __builtin_bit_cast(unsigned, r); }
; __device__ __forceinline__ float bflo(unsigned w) { return __uint_as_float(w << 16); }
; __device__ __forceinline__ float bfhi(unsigned w) { return __uint_as_float(w & 0xffff0000u); }
; __device__ __forceinline__ float wave_sum(float v) { v = row16_sum(v); v += shx(v, 16); v += shx(v, 32); return v; }
;     __device__ __forceinline__ void operator()(const f32x4 (&acc)[2][2][4][2], const Unit& u, int wr, int wc, int, int) const {
;     ...
;                 for (int bj = 0; bj < 2; ++bj) { const u32x4 c = cin[ai][m][bj]; const f32x4 v0 = acc[ai][bj][m][0], v1 = acc[ai][bj][m][1];
;                     u32x4 w; w.x = cvt_pk_bf16(bflo(c.x) + v0[0], bfhi(c.x) + v0[1]); w.y = cvt_pk_bf16(bflo(c.y) + v0[2], bfhi(c.y) + v0[3]);
;                     w.z = cvt_pk_bf16(bflo(c.z) + v1[0], bfhi(c.z) + v1[1]); w.w = cvt_pk_bf16(bflo(c.w) + v1[2], bfhi(c.w) + v1[3]);
;                     *(u32x4*)(C + (size_t)(row0 + ai * HALF + m * 16) * ldc + col0 + bj * HALF) = w; }
; __device__ __forceinline__ void rowstat_phase(const Frame& F, const bf16_t* __restrict__ res, float* __restrict__ rstd_out) {
;     ...
;         for (int r = 0; r < 4; ++r) { ss[r] = 0.f;
; #pragma unroll
;             for (int i = 0; i < 4; ++i) { const u32x4 x = v[r][i];
;                 ss[r] += bflo(x.x) * bflo(x.x) + bfhi(x.x) * bfhi(x.x) + bflo(x.y) * bflo(x.y) + bfhi(x.y) * bfhi(x.y) + bflo(x.z) * bflo(x.z) + bfhi(x.z) * bfhi(x.z) + bflo(x.w) * bflo(x.w) + bfhi(x.w) * bfhi(x.w); }
;             ss[r] = wave_sum(ss[r]); }
	v_lshlrev_b32_e32 v14, 16, v132
	v_and_b32_e32 v15, 0xffff0000, v132
	v_pk_add_f32 v[8:9], v[8:9], v[14:15]
	v_lshlrev_b32_e32 v14, 16, v133
	v_and_b32_e32 v15, 0xffff0000, v133
	v_pk_add_f32 v[10:11], v[10:11], v[14:15]
	v_cvt_pk_bf16_f32 v8, v8, v9
	v_cvt_pk_bf16_f32 v9, v10, v11
	v_lshlrev_b32_e32 v10, 16, v134
	v_and_b32_e32 v11, 0xffff0000, v134
	v_pk_add_f32 v[4:5], v[4:5], v[10:11]
	v_cvt_pk_bf16_f32 v19, v12, v13
	v_cvt_pk_bf16_f32 v10, v4, v5
	v_lshlrev_b32_e32 v4, 16, v135
	v_and_b32_e32 v5, 0xffff0000, v135
	v_lshl_add_u64 v[12:13], s[88:89], 0, v[204:205]
	v_pk_add_f32 v[4:5], v[6:7], v[4:5]
	v_lshl_add_u64 v[92:93], v[92:93], 0, v[202:203]
	v_lshl_add_u64 v[76:77], v[76:77], 0, v[202:203]
	v_lshl_add_u64 v[60:61], v[60:61], 0, v[202:203]
	v_lshl_add_u64 v[44:45], v[44:45], 0, v[202:203]
	v_lshl_add_u64 v[28:29], v[28:29], 0, v[202:203]
	v_lshl_add_u64 v[12:13], v[12:13], 0, v[202:203]
	v_cvt_pk_bf16_f32 v11, v4, v5
	global_store_dwordx4 v[124:125], v[128:131], off
	global_store_dwordx4 v[124:125], v[120:123], off offset:256
	global_store_dwordx4 v[108:109], v[112:115], off
	global_store_dwordx4 v[108:109], v[104:107], off offset:256
	global_store_dwordx4 v[92:93], v[96:99], off
	global_store_dwordx4 v[92:93], v[88:91], off offset:256
	global_store_dwordx4 v[76:77], v[80:83], off
	global_store_dwordx4 v[76:77], v[72:75], off offset:256
	global_store_dwordx4 v[60:61], v[64:67], off
	global_store_dwordx4 v[60:61], v[56:59], off offset:256
	global_store_dwordx4 v[44:45], v[48:51], off
	global_store_dwordx4 v[44:45], v[40:43], off offset:256
	global_store_dwordx4 v[28:29], v[32:35], off
	global_store_dwordx4 v[28:29], v[24:27], off offset:256
	global_store_dwordx4 v[12:13], v[16:19], off
	global_store_dwordx4 v[12:13], v[8:11], off offset:256
	v_subrev_u32_e32 v216, s88, v124
	v_bfe_u32 v217, v216, 4, 8
	v_lshrrev_b32_e32 v216, 12, v216
	v_and_b32_e32 v218, 15, v217
	v_lshrrev_b32_e32 v217, 5, v217
	v_lshl_or_b32 v217, v217, 4, v218
	v_lshlrev_b32_e32 v217, 17, v217
	v_and_b32_e32 v218, 15, v216
	v_and_b32_e32 v216, 0xffffffc0, v216
	v_lshl_or_b32 v216, v218, 2, v216
	v_lshl_add_u32 v216, v216, 2, v217
	v_add_u32_e32 v216, 0x1e000000, v216
	v_mov_b32_e32 v188, 0
	v_dot2c_f32_bf16_e32 v188, v128, v128
	v_dot2c_f32_bf16_e32 v188, v129, v129
	v_dot2c_f32_bf16_e32 v188, v130, v130
	v_dot2c_f32_bf16_e32 v188, v131, v131
	v_dot2c_f32_bf16_e32 v188, v120, v120
	v_dot2c_f32_bf16_e32 v188, v121, v121
	v_dot2c_f32_bf16_e32 v188, v122, v122
	v_dot2c_f32_bf16_e32 v188, v123, v123
	v_mov_b32_e32 v189, 0
	v_dot2c_f32_bf16_e32 v189, v112, v112
	v_dot2c_f32_bf16_e32 v189, v113, v113
	v_dot2c_f32_bf16_e32 v189, v114, v114
	v_dot2c_f32_bf16_e32 v189, v115, v115
	v_dot2c_f32_bf16_e32 v189, v104, v104
	v_dot2c_f32_bf16_e32 v189, v105, v105
	v_dot2c_f32_bf16_e32 v189, v106, v106
	v_dot2c_f32_bf16_e32 v189, v107, v107
	v_mov_b32_e32 v190, 0
	v_dot2c_f32_bf16_e32 v190, v96, v96
	v_dot2c_f32_bf16_e32 v190, v97, v97
	v_dot2c_f32_bf16_e32 v190, v98, v98
	v_dot2c_f32_bf16_e32 v190, v99, v99
	v_dot2c_f32_bf16_e32 v190, v88, v88
	v_dot2c_f32_bf16_e32 v190, v89, v89
	v_dot2c_f32_bf16_e32 v190, v90, v90
	v_dot2c_f32_bf16_e32 v190, v91, v91
	v_mov_b32_e32 v191, 0
	v_dot2c_f32_bf16_e32 v191, v80, v80
	v_dot2c_f32_bf16_e32 v191, v81, v81
	v_dot2c_f32_bf16_e32 v191, v82, v82
	v_dot2c_f32_bf16_e32 v191, v83, v83
	v_dot2c_f32_bf16_e32 v191, v72, v72
	v_dot2c_f32_bf16_e32 v191, v73, v73
	v_dot2c_f32_bf16_e32 v191, v74, v74
	v_dot2c_f32_bf16_e32 v191, v75, v75
	s_nop 2
	global_store_dwordx4 v216, v[188:191], s[88:89]
	s_nop 1
	v_mov_b32_e32 v188, 0
	v_dot2c_f32_bf16_e32 v188, v64, v64
	v_dot2c_f32_bf16_e32 v188, v65, v65
	v_dot2c_f32_bf16_e32 v188, v66, v66
	v_dot2c_f32_bf16_e32 v188, v67, v67
	v_dot2c_f32_bf16_e32 v188, v56, v56
	v_dot2c_f32_bf16_e32 v188, v57, v57
	v_dot2c_f32_bf16_e32 v188, v58, v58
	v_dot2c_f32_bf16_e32 v188, v59, v59
	v_mov_b32_e32 v189, 0
	v_dot2c_f32_bf16_e32 v189, v48, v48
	v_dot2c_f32_bf16_e32 v189, v49, v49
	v_dot2c_f32_bf16_e32 v189, v50, v50
	v_dot2c_f32_bf16_e32 v189, v51, v51
	v_dot2c_f32_bf16_e32 v189, v40, v40
	v_dot2c_f32_bf16_e32 v189, v41, v41
	v_dot2c_f32_bf16_e32 v189, v42, v42
	v_dot2c_f32_bf16_e32 v189, v43, v43
	v_mov_b32_e32 v190, 0
	v_dot2c_f32_bf16_e32 v190, v32, v32
	v_dot2c_f32_bf16_e32 v190, v33, v33
	v_dot2c_f32_bf16_e32 v190, v34, v34
	v_dot2c_f32_bf16_e32 v190, v35, v35
	v_dot2c_f32_bf16_e32 v190, v24, v24
	v_dot2c_f32_bf16_e32 v190, v25, v25
	v_dot2c_f32_bf16_e32 v190, v26, v26
	v_dot2c_f32_bf16_e32 v190, v27, v27
	v_mov_b32_e32 v191, 0
	v_dot2c_f32_bf16_e32 v191, v16, v16
	v_dot2c_f32_bf16_e32 v191, v17, v17
	v_dot2c_f32_bf16_e32 v191, v18, v18
	v_dot2c_f32_bf16_e32 v191, v19, v19
	v_dot2c_f32_bf16_e32 v191, v8, v8
	v_dot2c_f32_bf16_e32 v191, v9, v9
	v_dot2c_f32_bf16_e32 v191, v10, v10
	v_dot2c_f32_bf16_e32 v191, v11, v11
	s_nop 2
	global_store_dwordx4 v216, v[188:191], s[88:89] offset:512
	s_nop 1
	s_cbranch_vccz .LBB0_1655
	s_waitcnt vmcnt(0)
	s_cmpk_gt_u32 s2, 0xff
	s_cbranch_scc1 .LBB0_1670
	s_barrier
